# GEMM K-loops: duplicate post-barrier s_waitcnt lgkmcnt(0) removed (plus s_setprio flips removed)
# speedup vs baseline: 1.0132x; 1.0132x over previous
.LBB0_344:
	s_add_i32 s30, s8, 2
	s_add_u32 s9, s12, 0xfff80080
	s_addc_u32 s16, s13, -1
	s_add_i32 s31, 0, 0x10000
	s_cmp_eq_u32 s60, s8
	s_cselect_b32 s17, s53, s16
	s_cselect_b32 s16, s52, s9
	s_cselect_b32 s9, s2, s10
	s_cselect_b32 s8, s3, s7
	s_add_i32 s33, 0, 0x14000
	v_add_u32_e32 v140, s31, v162
	v_add_u32_e32 v168, s33, v162
	ds_read_b128 v[128:131], v140
	ds_read_b128 v[132:135], v140 offset:1024
	ds_read_b128 v[136:139], v140 offset:2048
	ds_read_b128 v[140:143], v140 offset:3072
	ds_read_b128 v[154:157], v168
	ds_read_b128 v[158:161], v168 offset:1024
	ds_read_b128 v[164:167], v168 offset:2048
	ds_read_b128 v[168:171], v168 offset:3072
	v_lshl_add_u64 v[204:205], s[12:13], 0, v[150:151]
	s_add_i32 m0, s28, 0xc000
	ds_read_b128 v[172:175], v163
	ds_read_b128 v[176:179], v163 offset:1024
	ds_read_b128 v[180:183], v163 offset:2048
	ds_read_b128 v[184:187], v163 offset:3072
	ds_read_b128 v[188:191], v163 offset:4096
	ds_read_b128 v[192:195], v163 offset:5120
	ds_read_b128 v[196:199], v163 offset:6144
	ds_read_b128 v[200:203], v163 offset:7168
	global_load_lds_dwordx4 v[204:205], off
	v_lshl_add_u64 v[204:205], s[12:13], 0, v[152:153]
	s_add_i32 m0, s28, 0xe000
	s_nop 0
	global_load_lds_dwordx4 v[204:205], off
	s_waitcnt vmcnt(8)
	s_waitcnt lgkmcnt(0)
	s_barrier
	v_mfma_f32_16x16x32_bf16 v[112:115], v[128:131], v[172:175], v[112:115]
	v_mfma_f32_16x16x32_bf16 v[116:119], v[136:139], v[172:175], v[116:119]
	v_mfma_f32_16x16x32_bf16 v[96:99], v[128:131], v[180:183], v[96:99]
	v_mfma_f32_16x16x32_bf16 v[100:103], v[136:139], v[180:183], v[100:103]
	v_mfma_f32_16x16x32_bf16 v[80:83], v[128:131], v[188:191], v[80:83]
	v_mfma_f32_16x16x32_bf16 v[84:87], v[136:139], v[188:191], v[84:87]
	v_mfma_f32_16x16x32_bf16 v[48:51], v[128:131], v[196:199], v[48:51]
	v_mfma_f32_16x16x32_bf16 v[52:55], v[136:139], v[196:199], v[52:55]
	v_mfma_f32_16x16x32_bf16 v[112:115], v[132:135], v[176:179], v[112:115]
	v_mfma_f32_16x16x32_bf16 v[116:119], v[140:143], v[176:179], v[116:119]
	v_mfma_f32_16x16x32_bf16 v[96:99], v[132:135], v[184:187], v[96:99]
	v_mfma_f32_16x16x32_bf16 v[100:103], v[140:143], v[184:187], v[100:103]
	v_mfma_f32_16x16x32_bf16 v[80:83], v[132:135], v[192:195], v[80:83]
	v_mfma_f32_16x16x32_bf16 v[84:87], v[140:143], v[192:195], v[84:87]
	v_mfma_f32_16x16x32_bf16 v[48:51], v[132:135], v[200:203], v[48:51]
	v_mfma_f32_16x16x32_bf16 v[52:55], v[140:143], v[200:203], v[52:55]
	v_mfma_f32_16x16x32_bf16 v[120:123], v[154:157], v[172:175], v[120:123]
	v_mfma_f32_16x16x32_bf16 v[124:127], v[164:167], v[172:175], v[124:127]
	v_mfma_f32_16x16x32_bf16 v[104:107], v[154:157], v[180:183], v[104:107]
	v_mfma_f32_16x16x32_bf16 v[108:111], v[164:167], v[180:183], v[108:111]
	v_mfma_f32_16x16x32_bf16 v[88:91], v[154:157], v[188:191], v[88:91]
	v_mfma_f32_16x16x32_bf16 v[92:95], v[164:167], v[188:191], v[92:95]
	v_mfma_f32_16x16x32_bf16 v[64:67], v[154:157], v[196:199], v[64:67]
	v_mfma_f32_16x16x32_bf16 v[68:71], v[164:167], v[196:199], v[68:71]
	v_mfma_f32_16x16x32_bf16 v[120:123], v[158:161], v[176:179], v[120:123]
	v_mfma_f32_16x16x32_bf16 v[124:127], v[168:171], v[176:179], v[124:127]
	v_mfma_f32_16x16x32_bf16 v[104:107], v[158:161], v[184:187], v[104:107]
	v_mfma_f32_16x16x32_bf16 v[108:111], v[168:171], v[184:187], v[108:111]
	v_mfma_f32_16x16x32_bf16 v[88:91], v[158:161], v[192:195], v[88:91]
	v_mfma_f32_16x16x32_bf16 v[92:95], v[168:171], v[192:195], v[92:95]
	v_mfma_f32_16x16x32_bf16 v[64:67], v[158:161], v[200:203], v[64:67]
	v_mfma_f32_16x16x32_bf16 v[68:71], v[168:171], v[200:203], v[68:71]
	s_barrier
	s_add_i32 s31, s31, s26
	v_lshl_add_u64 v[204:205], s[8:9], 0, v[224:225]
	s_mov_b32 m0, s31
	ds_read_b128 v[172:175], v163 offset:16384
	ds_read_b128 v[176:179], v163 offset:17408
	ds_read_b128 v[180:183], v163 offset:18432
	ds_read_b128 v[184:187], v163 offset:19456
	ds_read_b128 v[188:191], v163 offset:20480
	ds_read_b128 v[192:195], v163 offset:21504
	ds_read_b128 v[196:199], v163 offset:22528
	ds_read_b128 v[200:203], v163 offset:23552
	global_load_lds_dwordx4 v[204:205], off
	s_add_i32 m0, s31, 0x2000
	s_add_u32 s40, s8, 0x80000
	v_lshl_add_u64 v[206:207], s[8:9], 0, v[144:145]
	s_addc_u32 s41, s9, 0
	s_add_i32 s31, s33, s26
	global_load_lds_dwordx4 v[206:207], off
	v_lshl_add_u64 v[208:209], s[40:41], 0, v[224:225]
	s_mov_b32 m0, s31
	v_lshl_add_u64 v[210:211], s[16:17], 0, v[146:147]
	global_load_lds_dwordx4 v[208:209], off
	v_lshl_add_u64 v[208:209], s[40:41], 0, v[144:145]
	s_add_i32 m0, s31, 0x2000
	s_nop 0
	global_load_lds_dwordx4 v[208:209], off
	v_lshl_add_u64 v[208:209], s[16:17], 0, v[148:149]
	s_mov_b32 m0, s28
	s_nop 0
	global_load_lds_dwordx4 v[208:209], off
	s_mov_b32 m0, s29
	s_nop 0
	global_load_lds_dwordx4 v[210:211], off
	s_waitcnt vmcnt(8)
	s_waitcnt lgkmcnt(0)
	s_barrier
	v_mfma_f32_16x16x32_bf16 v[56:59], v[128:131], v[172:175], v[56:59]
	v_mfma_f32_16x16x32_bf16 v[60:63], v[136:139], v[172:175], v[60:63]
	v_mfma_f32_16x16x32_bf16 v[32:35], v[128:131], v[180:183], v[32:35]
	v_mfma_f32_16x16x32_bf16 v[36:39], v[136:139], v[180:183], v[36:39]
	v_mfma_f32_16x16x32_bf16 v[16:19], v[128:131], v[188:191], v[16:19]
	v_mfma_f32_16x16x32_bf16 v[20:23], v[136:139], v[188:191], v[20:23]
	v_mfma_f32_16x16x32_bf16 v[0:3], v[128:131], v[196:199], v[0:3]
	v_mfma_f32_16x16x32_bf16 v[4:7], v[136:139], v[196:199], v[4:7]
	v_mfma_f32_16x16x32_bf16 v[56:59], v[132:135], v[176:179], v[56:59]
	v_mfma_f32_16x16x32_bf16 v[60:63], v[140:143], v[176:179], v[60:63]
	v_mfma_f32_16x16x32_bf16 v[32:35], v[132:135], v[184:187], v[32:35]
	v_mfma_f32_16x16x32_bf16 v[36:39], v[140:143], v[184:187], v[36:39]
	v_mfma_f32_16x16x32_bf16 v[16:19], v[132:135], v[192:195], v[16:19]
	v_mfma_f32_16x16x32_bf16 v[20:23], v[140:143], v[192:195], v[20:23]
	v_mfma_f32_16x16x32_bf16 v[0:3], v[132:135], v[200:203], v[0:3]
	v_mfma_f32_16x16x32_bf16 v[4:7], v[140:143], v[200:203], v[4:7]
	v_mfma_f32_16x16x32_bf16 v[72:75], v[154:157], v[172:175], v[72:75]
	v_mfma_f32_16x16x32_bf16 v[76:79], v[164:167], v[172:175], v[76:79]
	v_mfma_f32_16x16x32_bf16 v[40:43], v[154:157], v[180:183], v[40:43]
	v_mfma_f32_16x16x32_bf16 v[44:47], v[164:167], v[180:183], v[44:47]
	v_mfma_f32_16x16x32_bf16 v[24:27], v[154:157], v[188:191], v[24:27]
	v_mfma_f32_16x16x32_bf16 v[28:31], v[164:167], v[188:191], v[28:31]
	v_mfma_f32_16x16x32_bf16 v[8:11], v[154:157], v[196:199], v[8:11]
	v_mfma_f32_16x16x32_bf16 v[12:15], v[164:167], v[196:199], v[12:15]
	v_mfma_f32_16x16x32_bf16 v[72:75], v[158:161], v[176:179], v[72:75]
	v_mfma_f32_16x16x32_bf16 v[76:79], v[168:171], v[176:179], v[76:79]
	v_mfma_f32_16x16x32_bf16 v[40:43], v[158:161], v[184:187], v[40:43]
	v_mfma_f32_16x16x32_bf16 v[44:47], v[168:171], v[184:187], v[44:47]
	v_mfma_f32_16x16x32_bf16 v[24:27], v[158:161], v[192:195], v[24:27]
	v_mfma_f32_16x16x32_bf16 v[28:31], v[168:171], v[192:195], v[28:31]
	v_mfma_f32_16x16x32_bf16 v[8:11], v[158:161], v[200:203], v[8:11]
	v_mfma_f32_16x16x32_bf16 v[12:15], v[168:171], v[200:203], v[12:15]
	s_barrier
	s_add_i32 s31, 0, 0x18000
	s_add_i32 s33, 0, 0x1c000
	v_add_u32_e32 v140, s31, v162
	v_add_u32_e32 v168, s33, v162
	ds_read_b128 v[128:131], v140
	ds_read_b128 v[132:135], v140 offset:1024
	ds_read_b128 v[136:139], v140 offset:2048
	ds_read_b128 v[140:143], v140 offset:3072
	ds_read_b128 v[154:157], v168
	ds_read_b128 v[158:161], v168 offset:1024
	ds_read_b128 v[164:167], v168 offset:2048
	ds_read_b128 v[168:171], v168 offset:3072
	s_add_u32 s16, s16, 0x80000
	s_addc_u32 s17, s17, 0
	s_mov_b32 m0, s34
	v_lshl_add_u64 v[212:213], s[16:17], 0, v[148:149]
	ds_read_b128 v[172:175], v163 offset:32768
	ds_read_b128 v[176:179], v163 offset:33792
	ds_read_b128 v[180:183], v163 offset:34816
	ds_read_b128 v[184:187], v163 offset:35840
	ds_read_b128 v[188:191], v163 offset:36864
	ds_read_b128 v[192:195], v163 offset:37888
	ds_read_b128 v[196:199], v163 offset:38912
	ds_read_b128 v[200:203], v163 offset:39936
	global_load_lds_dwordx4 v[212:213], off
	v_lshl_add_u64 v[212:213], s[16:17], 0, v[146:147]
	s_mov_b32 m0, s35
	s_nop 0
	global_load_lds_dwordx4 v[212:213], off
	s_waitcnt vmcnt(8)
	s_waitcnt lgkmcnt(0)
	s_barrier
	v_mfma_f32_16x16x32_bf16 v[112:115], v[128:131], v[172:175], v[112:115]
	v_mfma_f32_16x16x32_bf16 v[116:119], v[136:139], v[172:175], v[116:119]
	v_mfma_f32_16x16x32_bf16 v[96:99], v[128:131], v[180:183], v[96:99]
	v_mfma_f32_16x16x32_bf16 v[100:103], v[136:139], v[180:183], v[100:103]
	v_mfma_f32_16x16x32_bf16 v[80:83], v[128:131], v[188:191], v[80:83]
	v_mfma_f32_16x16x32_bf16 v[84:87], v[136:139], v[188:191], v[84:87]
	v_mfma_f32_16x16x32_bf16 v[48:51], v[128:131], v[196:199], v[48:51]
	v_mfma_f32_16x16x32_bf16 v[52:55], v[136:139], v[196:199], v[52:55]
	v_mfma_f32_16x16x32_bf16 v[112:115], v[132:135], v[176:179], v[112:115]
	v_mfma_f32_16x16x32_bf16 v[116:119], v[140:143], v[176:179], v[116:119]
	v_mfma_f32_16x16x32_bf16 v[96:99], v[132:135], v[184:187], v[96:99]
	v_mfma_f32_16x16x32_bf16 v[100:103], v[140:143], v[184:187], v[100:103]
	v_mfma_f32_16x16x32_bf16 v[80:83], v[132:135], v[192:195], v[80:83]
	v_mfma_f32_16x16x32_bf16 v[84:87], v[140:143], v[192:195], v[84:87]
	v_mfma_f32_16x16x32_bf16 v[48:51], v[132:135], v[200:203], v[48:51]
	v_mfma_f32_16x16x32_bf16 v[52:55], v[140:143], v[200:203], v[52:55]
	v_mfma_f32_16x16x32_bf16 v[120:123], v[154:157], v[172:175], v[120:123]
	v_mfma_f32_16x16x32_bf16 v[124:127], v[164:167], v[172:175], v[124:127]
	v_mfma_f32_16x16x32_bf16 v[104:107], v[154:157], v[180:183], v[104:107]
	v_mfma_f32_16x16x32_bf16 v[108:111], v[164:167], v[180:183], v[108:111]
	v_mfma_f32_16x16x32_bf16 v[88:91], v[154:157], v[188:191], v[88:91]
	v_mfma_f32_16x16x32_bf16 v[92:95], v[164:167], v[188:191], v[92:95]
	v_mfma_f32_16x16x32_bf16 v[64:67], v[154:157], v[196:199], v[64:67]
	v_mfma_f32_16x16x32_bf16 v[68:71], v[164:167], v[196:199], v[68:71]
	v_mfma_f32_16x16x32_bf16 v[120:123], v[158:161], v[176:179], v[120:123]
	v_mfma_f32_16x16x32_bf16 v[124:127], v[168:171], v[176:179], v[124:127]
	v_mfma_f32_16x16x32_bf16 v[104:107], v[158:161], v[184:187], v[104:107]
	v_mfma_f32_16x16x32_bf16 v[108:111], v[168:171], v[184:187], v[108:111]
	v_mfma_f32_16x16x32_bf16 v[88:91], v[158:161], v[192:195], v[88:91]
	v_mfma_f32_16x16x32_bf16 v[92:95], v[168:171], v[192:195], v[92:95]
	v_mfma_f32_16x16x32_bf16 v[64:67], v[158:161], v[200:203], v[64:67]
	v_mfma_f32_16x16x32_bf16 v[68:71], v[168:171], v[200:203], v[68:71]
	s_barrier
	s_add_i32 s16, s31, s26
	v_lshl_add_u64 v[204:205], v[204:205], 0, s[24:25]
	s_mov_b32 m0, s16
	ds_read_b128 v[172:175], v163 offset:49152
	ds_read_b128 v[176:179], v163 offset:50176
	ds_read_b128 v[180:183], v163 offset:51200
	ds_read_b128 v[184:187], v163 offset:52224
	ds_read_b128 v[188:191], v163 offset:53248
	ds_read_b128 v[192:195], v163 offset:54272
	ds_read_b128 v[196:199], v163 offset:55296
	ds_read_b128 v[200:203], v163 offset:56320
	global_load_lds_dwordx4 v[204:205], off
	s_add_i32 m0, s16, 0x2000
	s_add_u32 s8, s8, 0x80080
	v_lshl_add_u64 v[204:205], v[206:207], 0, s[24:25]
	s_addc_u32 s9, s9, 0
	s_add_i32 s16, s33, s26
	global_load_lds_dwordx4 v[204:205], off
	v_lshl_add_u64 v[204:205], s[8:9], 0, v[224:225]
	s_mov_b32 m0, s16
	s_nop 0
	global_load_lds_dwordx4 v[204:205], off
	v_lshl_add_u64 v[204:205], s[8:9], 0, v[144:145]
	s_add_i32 m0, s16, 0x2000
	s_nop 0
	global_load_lds_dwordx4 v[204:205], off
	v_lshl_add_u64 v[204:205], v[208:209], 0, s[24:25]
	s_mov_b32 m0, s58
	s_nop 0
	global_load_lds_dwordx4 v[204:205], off
	v_lshl_add_u64 v[204:205], v[210:211], 0, s[24:25]
	s_mov_b32 m0, s59
	s_nop 0
	global_load_lds_dwordx4 v[204:205], off
	s_waitcnt vmcnt(8)
	s_waitcnt lgkmcnt(0)
	s_barrier
	v_mfma_f32_16x16x32_bf16 v[56:59], v[128:131], v[172:175], v[56:59]
	v_mfma_f32_16x16x32_bf16 v[60:63], v[136:139], v[172:175], v[60:63]
	v_mfma_f32_16x16x32_bf16 v[32:35], v[128:131], v[180:183], v[32:35]
	v_mfma_f32_16x16x32_bf16 v[36:39], v[136:139], v[180:183], v[36:39]
	v_mfma_f32_16x16x32_bf16 v[16:19], v[128:131], v[188:191], v[16:19]
	v_mfma_f32_16x16x32_bf16 v[20:23], v[136:139], v[188:191], v[20:23]
	v_mfma_f32_16x16x32_bf16 v[0:3], v[128:131], v[196:199], v[0:3]
	v_mfma_f32_16x16x32_bf16 v[4:7], v[136:139], v[196:199], v[4:7]
	v_mfma_f32_16x16x32_bf16 v[56:59], v[132:135], v[176:179], v[56:59]
	v_mfma_f32_16x16x32_bf16 v[60:63], v[140:143], v[176:179], v[60:63]
	v_mfma_f32_16x16x32_bf16 v[32:35], v[132:135], v[184:187], v[32:35]
	v_mfma_f32_16x16x32_bf16 v[36:39], v[140:143], v[184:187], v[36:39]
	v_mfma_f32_16x16x32_bf16 v[16:19], v[132:135], v[192:195], v[16:19]
	v_mfma_f32_16x16x32_bf16 v[20:23], v[140:143], v[192:195], v[20:23]
	v_mfma_f32_16x16x32_bf16 v[0:3], v[132:135], v[200:203], v[0:3]
	v_mfma_f32_16x16x32_bf16 v[4:7], v[140:143], v[200:203], v[4:7]
	v_mfma_f32_16x16x32_bf16 v[72:75], v[154:157], v[172:175], v[72:75]
	v_mfma_f32_16x16x32_bf16 v[76:79], v[164:167], v[172:175], v[76:79]
	v_mfma_f32_16x16x32_bf16 v[40:43], v[154:157], v[180:183], v[40:43]
	v_mfma_f32_16x16x32_bf16 v[44:47], v[164:167], v[180:183], v[44:47]
	v_mfma_f32_16x16x32_bf16 v[24:27], v[154:157], v[188:191], v[24:27]
	v_mfma_f32_16x16x32_bf16 v[28:31], v[164:167], v[188:191], v[28:31]
	v_mfma_f32_16x16x32_bf16 v[8:11], v[154:157], v[196:199], v[8:11]
	v_mfma_f32_16x16x32_bf16 v[12:15], v[164:167], v[196:199], v[12:15]
	v_mfma_f32_16x16x32_bf16 v[72:75], v[158:161], v[176:179], v[72:75]
	v_mfma_f32_16x16x32_bf16 v[76:79], v[168:171], v[176:179], v[76:79]
	v_mfma_f32_16x16x32_bf16 v[40:43], v[158:161], v[184:187], v[40:43]
	v_mfma_f32_16x16x32_bf16 v[44:47], v[168:171], v[184:187], v[44:47]
	v_mfma_f32_16x16x32_bf16 v[24:27], v[158:161], v[192:195], v[24:27]
	v_mfma_f32_16x16x32_bf16 v[28:31], v[168:171], v[192:195], v[28:31]
	v_mfma_f32_16x16x32_bf16 v[8:11], v[158:161], v[200:203], v[8:11]
	v_mfma_f32_16x16x32_bf16 v[12:15], v[168:171], v[200:203], v[12:15]
	s_barrier
	s_add_u32 s12, s12, 0x100
	s_addc_u32 s13, s13, 0
	s_add_u32 s7, s7, 0x100
	s_addc_u32 s10, s10, 0
	s_cmp_ge_i32 s30, s57
	s_mov_b32 s8, s30
	s_cbranch_scc0 .LBB0_344

.LBB0_920:
	s_add_i32 s33, s8, 2
	s_add_u32 s9, s12, 0xffff0080
	s_addc_u32 s20, s13, -1
	s_add_i32 s61, 0, 0x10000
	s_cmp_eq_u32 s59, s8
	s_cselect_b32 s21, s3, s20
	s_cselect_b32 s20, s7, s9
	s_cselect_b32 s9, s23, s31
	s_cselect_b32 s8, s27, s30
	s_add_i32 s64, 0, 0x14000
	v_add_u32_e32 v150, s61, v170
	v_add_u32_e32 v166, s64, v170
	ds_read_b128 v[128:131], v150
	ds_read_b128 v[132:135], v150 offset:1024
	ds_read_b128 v[146:149], v150 offset:2048
	ds_read_b128 v[150:153], v150 offset:3072
	ds_read_b128 v[154:157], v166
	ds_read_b128 v[158:161], v166 offset:1024
	ds_read_b128 v[162:165], v166 offset:2048
	ds_read_b128 v[166:169], v166 offset:3072
	v_lshl_add_u64 v[204:205], s[12:13], 0, v[142:143]
	s_add_i32 m0, s49, 0xc000
	ds_read_b128 v[172:175], v171
	ds_read_b128 v[176:179], v171 offset:1024
	ds_read_b128 v[180:183], v171 offset:2048
	ds_read_b128 v[184:187], v171 offset:3072
	ds_read_b128 v[188:191], v171 offset:4096
	ds_read_b128 v[192:195], v171 offset:5120
	ds_read_b128 v[196:199], v171 offset:6144
	ds_read_b128 v[200:203], v171 offset:7168
	global_load_lds_dwordx4 v[204:205], off
	v_lshl_add_u64 v[204:205], s[12:13], 0, v[144:145]
	s_add_i32 m0, s49, 0xe000
	s_nop 0
	global_load_lds_dwordx4 v[204:205], off
	s_waitcnt vmcnt(8)
	s_waitcnt lgkmcnt(0)
	s_barrier
	v_mfma_f32_16x16x32_bf16 v[120:123], v[128:131], v[172:175], v[120:123]
	v_mfma_f32_16x16x32_bf16 v[124:127], v[146:149], v[172:175], v[124:127]
	v_mfma_f32_16x16x32_bf16 v[116:119], v[128:131], v[180:183], v[116:119]
	v_mfma_f32_16x16x32_bf16 v[112:115], v[146:149], v[180:183], v[112:115]
	v_mfma_f32_16x16x32_bf16 v[108:111], v[128:131], v[188:191], v[108:111]
	v_mfma_f32_16x16x32_bf16 v[104:107], v[146:149], v[188:191], v[104:107]
	v_mfma_f32_16x16x32_bf16 v[100:103], v[128:131], v[196:199], v[100:103]
	v_mfma_f32_16x16x32_bf16 v[96:99], v[146:149], v[196:199], v[96:99]
	v_mfma_f32_16x16x32_bf16 v[120:123], v[132:135], v[176:179], v[120:123]
	v_mfma_f32_16x16x32_bf16 v[124:127], v[150:153], v[176:179], v[124:127]
	v_mfma_f32_16x16x32_bf16 v[116:119], v[132:135], v[184:187], v[116:119]
	v_mfma_f32_16x16x32_bf16 v[112:115], v[150:153], v[184:187], v[112:115]
	v_mfma_f32_16x16x32_bf16 v[108:111], v[132:135], v[192:195], v[108:111]
	v_mfma_f32_16x16x32_bf16 v[104:107], v[150:153], v[192:195], v[104:107]
	v_mfma_f32_16x16x32_bf16 v[100:103], v[132:135], v[200:203], v[100:103]
	v_mfma_f32_16x16x32_bf16 v[96:99], v[150:153], v[200:203], v[96:99]
	v_mfma_f32_16x16x32_bf16 v[60:63], v[154:157], v[172:175], v[60:63]
	v_mfma_f32_16x16x32_bf16 v[56:59], v[162:165], v[172:175], v[56:59]
	v_mfma_f32_16x16x32_bf16 v[52:55], v[154:157], v[180:183], v[52:55]
	v_mfma_f32_16x16x32_bf16 v[48:51], v[162:165], v[180:183], v[48:51]
	v_mfma_f32_16x16x32_bf16 v[44:47], v[154:157], v[188:191], v[44:47]
	v_mfma_f32_16x16x32_bf16 v[40:43], v[162:165], v[188:191], v[40:43]
	v_mfma_f32_16x16x32_bf16 v[36:39], v[154:157], v[196:199], v[36:39]
	v_mfma_f32_16x16x32_bf16 v[32:35], v[162:165], v[196:199], v[32:35]
	v_mfma_f32_16x16x32_bf16 v[60:63], v[158:161], v[176:179], v[60:63]
	v_mfma_f32_16x16x32_bf16 v[56:59], v[166:169], v[176:179], v[56:59]
	v_mfma_f32_16x16x32_bf16 v[52:55], v[158:161], v[184:187], v[52:55]
	v_mfma_f32_16x16x32_bf16 v[48:51], v[166:169], v[184:187], v[48:51]
	v_mfma_f32_16x16x32_bf16 v[44:47], v[158:161], v[192:195], v[44:47]
	v_mfma_f32_16x16x32_bf16 v[40:43], v[166:169], v[192:195], v[40:43]
	v_mfma_f32_16x16x32_bf16 v[36:39], v[158:161], v[200:203], v[36:39]
	v_mfma_f32_16x16x32_bf16 v[32:35], v[166:169], v[200:203], v[32:35]
	s_barrier
	s_add_i32 s61, s61, s35
	v_lshl_add_u64 v[204:205], s[8:9], 0, v[224:225]
	s_mov_b32 m0, s61
	ds_read_b128 v[172:175], v171 offset:16384
	ds_read_b128 v[176:179], v171 offset:17408
	ds_read_b128 v[180:183], v171 offset:18432
	ds_read_b128 v[184:187], v171 offset:19456
	ds_read_b128 v[188:191], v171 offset:20480
	ds_read_b128 v[192:195], v171 offset:21504
	ds_read_b128 v[196:199], v171 offset:22528
	ds_read_b128 v[200:203], v171 offset:23552
	global_load_lds_dwordx4 v[204:205], off
	s_add_i32 m0, s61, 0x2000
	s_add_u32 s62, s8, 0x10000
	v_lshl_add_u64 v[206:207], s[8:9], 0, v[136:137]
	s_addc_u32 s63, s9, 0
	s_add_i32 s61, s64, s35
	global_load_lds_dwordx4 v[206:207], off
	v_lshl_add_u64 v[208:209], s[62:63], 0, v[224:225]
	s_mov_b32 m0, s61
	v_lshl_add_u64 v[210:211], s[20:21], 0, v[138:139]
	global_load_lds_dwordx4 v[208:209], off
	v_lshl_add_u64 v[208:209], s[62:63], 0, v[136:137]
	s_add_i32 m0, s61, 0x2000
	s_nop 0
	global_load_lds_dwordx4 v[208:209], off
	v_lshl_add_u64 v[208:209], s[20:21], 0, v[140:141]
	s_mov_b32 m0, s49
	s_nop 0
	global_load_lds_dwordx4 v[208:209], off
	s_mov_b32 m0, s50
	s_nop 0
	global_load_lds_dwordx4 v[210:211], off
	s_waitcnt vmcnt(8)
	s_waitcnt lgkmcnt(0)
	s_barrier
	v_mfma_f32_16x16x32_bf16 v[92:95], v[128:131], v[172:175], v[92:95]
	v_mfma_f32_16x16x32_bf16 v[88:91], v[146:149], v[172:175], v[88:91]
	v_mfma_f32_16x16x32_bf16 v[84:87], v[128:131], v[180:183], v[84:87]
	v_mfma_f32_16x16x32_bf16 v[80:83], v[146:149], v[180:183], v[80:83]
	v_mfma_f32_16x16x32_bf16 v[76:79], v[128:131], v[188:191], v[76:79]
	v_mfma_f32_16x16x32_bf16 v[72:75], v[146:149], v[188:191], v[72:75]
	v_mfma_f32_16x16x32_bf16 v[68:71], v[128:131], v[196:199], v[68:71]
	v_mfma_f32_16x16x32_bf16 v[64:67], v[146:149], v[196:199], v[64:67]
	v_mfma_f32_16x16x32_bf16 v[92:95], v[132:135], v[176:179], v[92:95]
	v_mfma_f32_16x16x32_bf16 v[88:91], v[150:153], v[176:179], v[88:91]
	v_mfma_f32_16x16x32_bf16 v[84:87], v[132:135], v[184:187], v[84:87]
	v_mfma_f32_16x16x32_bf16 v[80:83], v[150:153], v[184:187], v[80:83]
	v_mfma_f32_16x16x32_bf16 v[76:79], v[132:135], v[192:195], v[76:79]
	v_mfma_f32_16x16x32_bf16 v[72:75], v[150:153], v[192:195], v[72:75]
	v_mfma_f32_16x16x32_bf16 v[68:71], v[132:135], v[200:203], v[68:71]
	v_mfma_f32_16x16x32_bf16 v[64:67], v[150:153], v[200:203], v[64:67]
	v_mfma_f32_16x16x32_bf16 v[28:31], v[154:157], v[172:175], v[28:31]
	v_mfma_f32_16x16x32_bf16 v[24:27], v[162:165], v[172:175], v[24:27]
	v_mfma_f32_16x16x32_bf16 v[20:23], v[154:157], v[180:183], v[20:23]
	v_mfma_f32_16x16x32_bf16 v[16:19], v[162:165], v[180:183], v[16:19]
	v_mfma_f32_16x16x32_bf16 v[12:15], v[154:157], v[188:191], v[12:15]
	v_mfma_f32_16x16x32_bf16 v[8:11], v[162:165], v[188:191], v[8:11]
	v_mfma_f32_16x16x32_bf16 v[4:7], v[154:157], v[196:199], v[4:7]
	v_mfma_f32_16x16x32_bf16 v[0:3], v[162:165], v[196:199], v[0:3]
	v_mfma_f32_16x16x32_bf16 v[28:31], v[158:161], v[176:179], v[28:31]
	v_mfma_f32_16x16x32_bf16 v[24:27], v[166:169], v[176:179], v[24:27]
	v_mfma_f32_16x16x32_bf16 v[20:23], v[158:161], v[184:187], v[20:23]
	v_mfma_f32_16x16x32_bf16 v[16:19], v[166:169], v[184:187], v[16:19]
	v_mfma_f32_16x16x32_bf16 v[12:15], v[158:161], v[192:195], v[12:15]
	v_mfma_f32_16x16x32_bf16 v[8:11], v[166:169], v[192:195], v[8:11]
	v_mfma_f32_16x16x32_bf16 v[4:7], v[158:161], v[200:203], v[4:7]
	v_mfma_f32_16x16x32_bf16 v[0:3], v[166:169], v[200:203], v[0:3]
	s_barrier
	s_add_i32 s61, 0, 0x18000
	s_add_i32 s62, 0, 0x1c000
	v_add_u32_e32 v150, s61, v170
	v_add_u32_e32 v166, s62, v170
	ds_read_b128 v[128:131], v150
	ds_read_b128 v[132:135], v150 offset:1024
	ds_read_b128 v[146:149], v150 offset:2048
	ds_read_b128 v[150:153], v150 offset:3072
	ds_read_b128 v[154:157], v166
	ds_read_b128 v[158:161], v166 offset:1024
	ds_read_b128 v[162:165], v166 offset:2048
	ds_read_b128 v[166:169], v166 offset:3072
	s_add_u32 s20, s20, 0x10000
	s_addc_u32 s21, s21, 0
	s_mov_b32 m0, s51
	v_lshl_add_u64 v[212:213], s[20:21], 0, v[140:141]
	ds_read_b128 v[172:175], v171 offset:32768
	ds_read_b128 v[176:179], v171 offset:33792
	ds_read_b128 v[180:183], v171 offset:34816
	ds_read_b128 v[184:187], v171 offset:35840
	ds_read_b128 v[188:191], v171 offset:36864
	ds_read_b128 v[192:195], v171 offset:37888
	ds_read_b128 v[196:199], v171 offset:38912
	ds_read_b128 v[200:203], v171 offset:39936
	global_load_lds_dwordx4 v[212:213], off
	v_lshl_add_u64 v[212:213], s[20:21], 0, v[138:139]
	s_mov_b32 m0, s52
	s_nop 0
	global_load_lds_dwordx4 v[212:213], off
	s_waitcnt vmcnt(8)
	s_waitcnt lgkmcnt(0)
	s_barrier
	v_mfma_f32_16x16x32_bf16 v[120:123], v[128:131], v[172:175], v[120:123]
	v_mfma_f32_16x16x32_bf16 v[124:127], v[146:149], v[172:175], v[124:127]
	v_mfma_f32_16x16x32_bf16 v[116:119], v[128:131], v[180:183], v[116:119]
	v_mfma_f32_16x16x32_bf16 v[112:115], v[146:149], v[180:183], v[112:115]
	v_mfma_f32_16x16x32_bf16 v[108:111], v[128:131], v[188:191], v[108:111]
	v_mfma_f32_16x16x32_bf16 v[104:107], v[146:149], v[188:191], v[104:107]
	v_mfma_f32_16x16x32_bf16 v[100:103], v[128:131], v[196:199], v[100:103]
	v_mfma_f32_16x16x32_bf16 v[96:99], v[146:149], v[196:199], v[96:99]
	v_mfma_f32_16x16x32_bf16 v[120:123], v[132:135], v[176:179], v[120:123]
	v_mfma_f32_16x16x32_bf16 v[124:127], v[150:153], v[176:179], v[124:127]
	v_mfma_f32_16x16x32_bf16 v[116:119], v[132:135], v[184:187], v[116:119]
	v_mfma_f32_16x16x32_bf16 v[112:115], v[150:153], v[184:187], v[112:115]
	v_mfma_f32_16x16x32_bf16 v[108:111], v[132:135], v[192:195], v[108:111]
	v_mfma_f32_16x16x32_bf16 v[104:107], v[150:153], v[192:195], v[104:107]
	v_mfma_f32_16x16x32_bf16 v[100:103], v[132:135], v[200:203], v[100:103]
	v_mfma_f32_16x16x32_bf16 v[96:99], v[150:153], v[200:203], v[96:99]
	v_mfma_f32_16x16x32_bf16 v[60:63], v[154:157], v[172:175], v[60:63]
	v_mfma_f32_16x16x32_bf16 v[56:59], v[162:165], v[172:175], v[56:59]
	v_mfma_f32_16x16x32_bf16 v[52:55], v[154:157], v[180:183], v[52:55]
	v_mfma_f32_16x16x32_bf16 v[48:51], v[162:165], v[180:183], v[48:51]
	v_mfma_f32_16x16x32_bf16 v[44:47], v[154:157], v[188:191], v[44:47]
	v_mfma_f32_16x16x32_bf16 v[40:43], v[162:165], v[188:191], v[40:43]
	v_mfma_f32_16x16x32_bf16 v[36:39], v[154:157], v[196:199], v[36:39]
	v_mfma_f32_16x16x32_bf16 v[32:35], v[162:165], v[196:199], v[32:35]
	v_mfma_f32_16x16x32_bf16 v[60:63], v[158:161], v[176:179], v[60:63]
	v_mfma_f32_16x16x32_bf16 v[56:59], v[166:169], v[176:179], v[56:59]
	v_mfma_f32_16x16x32_bf16 v[52:55], v[158:161], v[184:187], v[52:55]
	v_mfma_f32_16x16x32_bf16 v[48:51], v[166:169], v[184:187], v[48:51]
	v_mfma_f32_16x16x32_bf16 v[44:47], v[158:161], v[192:195], v[44:47]
	v_mfma_f32_16x16x32_bf16 v[40:43], v[166:169], v[192:195], v[40:43]
	v_mfma_f32_16x16x32_bf16 v[36:39], v[158:161], v[200:203], v[36:39]
	v_mfma_f32_16x16x32_bf16 v[32:35], v[166:169], v[200:203], v[32:35]
	s_barrier
	s_add_i32 s20, s61, s35
	v_lshl_add_u64 v[204:205], v[204:205], 0, s[24:25]
	s_mov_b32 m0, s20
	ds_read_b128 v[172:175], v171 offset:49152
	ds_read_b128 v[176:179], v171 offset:50176
	ds_read_b128 v[180:183], v171 offset:51200
	ds_read_b128 v[184:187], v171 offset:52224
	ds_read_b128 v[188:191], v171 offset:53248
	ds_read_b128 v[192:195], v171 offset:54272
	ds_read_b128 v[196:199], v171 offset:55296
	ds_read_b128 v[200:203], v171 offset:56320
	global_load_lds_dwordx4 v[204:205], off
	s_add_i32 m0, s20, 0x2000
	s_add_u32 s8, s8, 0x10080
	v_lshl_add_u64 v[204:205], v[206:207], 0, s[24:25]
	s_addc_u32 s9, s9, 0
	s_add_i32 s20, s62, s35
	global_load_lds_dwordx4 v[204:205], off
	v_lshl_add_u64 v[204:205], s[8:9], 0, v[224:225]
	s_mov_b32 m0, s20
	s_nop 0
	global_load_lds_dwordx4 v[204:205], off
	v_lshl_add_u64 v[204:205], s[8:9], 0, v[136:137]
	s_add_i32 m0, s20, 0x2000
	s_nop 0
	global_load_lds_dwordx4 v[204:205], off
	v_lshl_add_u64 v[204:205], v[208:209], 0, s[24:25]
	s_mov_b32 m0, s57
	s_nop 0
	global_load_lds_dwordx4 v[204:205], off
	v_lshl_add_u64 v[204:205], v[210:211], 0, s[24:25]
	s_mov_b32 m0, s58
	s_nop 0
	global_load_lds_dwordx4 v[204:205], off
	s_waitcnt vmcnt(8)
	s_waitcnt lgkmcnt(0)
	s_barrier
	v_mfma_f32_16x16x32_bf16 v[92:95], v[128:131], v[172:175], v[92:95]
	v_mfma_f32_16x16x32_bf16 v[88:91], v[146:149], v[172:175], v[88:91]
	v_mfma_f32_16x16x32_bf16 v[84:87], v[128:131], v[180:183], v[84:87]
	v_mfma_f32_16x16x32_bf16 v[80:83], v[146:149], v[180:183], v[80:83]
	v_mfma_f32_16x16x32_bf16 v[76:79], v[128:131], v[188:191], v[76:79]
	v_mfma_f32_16x16x32_bf16 v[72:75], v[146:149], v[188:191], v[72:75]
	v_mfma_f32_16x16x32_bf16 v[68:71], v[128:131], v[196:199], v[68:71]
	v_mfma_f32_16x16x32_bf16 v[64:67], v[146:149], v[196:199], v[64:67]
	v_mfma_f32_16x16x32_bf16 v[92:95], v[132:135], v[176:179], v[92:95]
	v_mfma_f32_16x16x32_bf16 v[88:91], v[150:153], v[176:179], v[88:91]
	v_mfma_f32_16x16x32_bf16 v[84:87], v[132:135], v[184:187], v[84:87]
	v_mfma_f32_16x16x32_bf16 v[80:83], v[150:153], v[184:187], v[80:83]
	v_mfma_f32_16x16x32_bf16 v[76:79], v[132:135], v[192:195], v[76:79]
	v_mfma_f32_16x16x32_bf16 v[72:75], v[150:153], v[192:195], v[72:75]
	v_mfma_f32_16x16x32_bf16 v[68:71], v[132:135], v[200:203], v[68:71]
	v_mfma_f32_16x16x32_bf16 v[64:67], v[150:153], v[200:203], v[64:67]
	v_mfma_f32_16x16x32_bf16 v[28:31], v[154:157], v[172:175], v[28:31]
	v_mfma_f32_16x16x32_bf16 v[24:27], v[162:165], v[172:175], v[24:27]
	v_mfma_f32_16x16x32_bf16 v[20:23], v[154:157], v[180:183], v[20:23]
	v_mfma_f32_16x16x32_bf16 v[16:19], v[162:165], v[180:183], v[16:19]
	v_mfma_f32_16x16x32_bf16 v[12:15], v[154:157], v[188:191], v[12:15]
	v_mfma_f32_16x16x32_bf16 v[8:11], v[162:165], v[188:191], v[8:11]
	v_mfma_f32_16x16x32_bf16 v[4:7], v[154:157], v[196:199], v[4:7]
	v_mfma_f32_16x16x32_bf16 v[0:3], v[162:165], v[196:199], v[0:3]
	v_mfma_f32_16x16x32_bf16 v[28:31], v[158:161], v[176:179], v[28:31]
	v_mfma_f32_16x16x32_bf16 v[24:27], v[166:169], v[176:179], v[24:27]
	v_mfma_f32_16x16x32_bf16 v[20:23], v[158:161], v[184:187], v[20:23]
	v_mfma_f32_16x16x32_bf16 v[16:19], v[166:169], v[184:187], v[16:19]
	v_mfma_f32_16x16x32_bf16 v[12:15], v[158:161], v[192:195], v[12:15]
	v_mfma_f32_16x16x32_bf16 v[8:11], v[166:169], v[192:195], v[8:11]
	v_mfma_f32_16x16x32_bf16 v[4:7], v[158:161], v[200:203], v[4:7]
	v_mfma_f32_16x16x32_bf16 v[0:3], v[166:169], v[200:203], v[0:3]
	s_barrier
	s_add_u32 s12, s12, 0x100
	s_addc_u32 s13, s13, 0
	s_add_u32 s30, s30, 0x100
	s_addc_u32 s31, s31, 0
	s_cmp_ge_i32 s33, s56
	s_mov_b32 s8, s33
	s_cbranch_scc0 .LBB0_920
	v_readlane_b32 s64, v253, 21
	v_readlane_b32 s63, v253, 24
	v_readlane_b32 s65, v253, 22

.LBB0_1313:
	s_add_i32 s56, s8, 2
	s_add_u32 s9, s12, 0xfff80080
	s_addc_u32 s28, s13, -1
	s_add_i32 s57, 0, 0x10000
	s_cmp_eq_u32 s48, s8
	s_cselect_b32 s29, s27, s28
	s_cselect_b32 s28, s35, s9
	v_add_u32_e32 v138, s57, v139
	s_cselect_b32 s9, s52, s55
	s_cselect_b32 s8, s53, s54
	s_add_i32 s60, 0, 0x14000
	ds_read_b128 v[140:143], v138
	ds_read_b128 v[146:149], v138 offset:1024
	ds_read_b128 v[150:153], v138 offset:2048
	ds_read_b128 v[154:157], v138 offset:3072
	v_add_u32_e32 v138, s60, v139
	ds_read_b128 v[158:161], v138
	ds_read_b128 v[162:165], v138 offset:1024
	ds_read_b128 v[166:169], v138 offset:2048
	ds_read_b128 v[170:173], v138 offset:3072
	v_lshl_add_u64 v[206:207], s[12:13], 0, v[134:135]
	s_add_i32 m0, s31, 0xc000
	ds_read_b128 v[174:177], v144
	ds_read_b128 v[178:181], v144 offset:1024
	ds_read_b128 v[182:185], v144 offset:2048
	ds_read_b128 v[186:189], v144 offset:3072
	ds_read_b128 v[190:193], v144 offset:4096
	ds_read_b128 v[194:197], v144 offset:5120
	ds_read_b128 v[198:201], v144 offset:6144
	ds_read_b128 v[202:205], v144 offset:7168
	global_load_lds_dwordx4 v[206:207], off
	v_lshl_add_u64 v[206:207], s[12:13], 0, v[136:137]
	s_add_i32 m0, s31, 0xe000
	s_nop 0
	global_load_lds_dwordx4 v[206:207], off
	s_waitcnt vmcnt(8)
	s_waitcnt lgkmcnt(0)
	s_barrier
	v_mfma_f32_16x16x32_bf16 v[116:119], v[140:143], v[174:177], v[116:119]
	v_mfma_f32_16x16x32_bf16 v[112:115], v[150:153], v[174:177], v[112:115]
	v_mfma_f32_16x16x32_bf16 v[100:103], v[140:143], v[182:185], v[100:103]
	v_mfma_f32_16x16x32_bf16 v[96:99], v[150:153], v[182:185], v[96:99]
	v_mfma_f32_16x16x32_bf16 v[84:87], v[140:143], v[190:193], v[84:87]
	v_mfma_f32_16x16x32_bf16 v[80:83], v[150:153], v[190:193], v[80:83]
	v_mfma_f32_16x16x32_bf16 v[68:71], v[140:143], v[198:201], v[68:71]
	v_mfma_f32_16x16x32_bf16 v[60:63], v[150:153], v[198:201], v[60:63]
	v_mfma_f32_16x16x32_bf16 v[116:119], v[146:149], v[178:181], v[116:119]
	v_mfma_f32_16x16x32_bf16 v[112:115], v[154:157], v[178:181], v[112:115]
	v_mfma_f32_16x16x32_bf16 v[100:103], v[146:149], v[186:189], v[100:103]
	v_mfma_f32_16x16x32_bf16 v[96:99], v[154:157], v[186:189], v[96:99]
	v_mfma_f32_16x16x32_bf16 v[84:87], v[146:149], v[194:197], v[84:87]
	v_mfma_f32_16x16x32_bf16 v[80:83], v[154:157], v[194:197], v[80:83]
	v_mfma_f32_16x16x32_bf16 v[68:71], v[146:149], v[202:205], v[68:71]
	v_mfma_f32_16x16x32_bf16 v[60:63], v[154:157], v[202:205], v[60:63]
	v_mfma_f32_16x16x32_bf16 v[124:127], v[158:161], v[174:177], v[124:127]
	v_mfma_f32_16x16x32_bf16 v[120:123], v[166:169], v[174:177], v[120:123]
	v_mfma_f32_16x16x32_bf16 v[108:111], v[158:161], v[182:185], v[108:111]
	v_mfma_f32_16x16x32_bf16 v[104:107], v[166:169], v[182:185], v[104:107]
	v_mfma_f32_16x16x32_bf16 v[92:95], v[158:161], v[190:193], v[92:95]
	v_mfma_f32_16x16x32_bf16 v[88:91], v[166:169], v[190:193], v[88:91]
	v_mfma_f32_16x16x32_bf16 v[76:79], v[158:161], v[198:201], v[76:79]
	v_mfma_f32_16x16x32_bf16 v[72:75], v[166:169], v[198:201], v[72:75]
	v_mfma_f32_16x16x32_bf16 v[124:127], v[162:165], v[178:181], v[124:127]
	v_mfma_f32_16x16x32_bf16 v[120:123], v[170:173], v[178:181], v[120:123]
	v_mfma_f32_16x16x32_bf16 v[108:111], v[162:165], v[186:189], v[108:111]
	v_mfma_f32_16x16x32_bf16 v[104:107], v[170:173], v[186:189], v[104:107]
	v_mfma_f32_16x16x32_bf16 v[92:95], v[162:165], v[194:197], v[92:95]
	v_mfma_f32_16x16x32_bf16 v[88:91], v[170:173], v[194:197], v[88:91]
	v_mfma_f32_16x16x32_bf16 v[76:79], v[162:165], v[202:205], v[76:79]
	v_mfma_f32_16x16x32_bf16 v[72:75], v[170:173], v[202:205], v[72:75]
	s_barrier
	s_add_i32 s57, s57, s10
	v_lshl_add_u64 v[206:207], s[8:9], 0, v[224:225]
	s_mov_b32 m0, s57
	ds_read_b128 v[174:177], v144 offset:16384
	ds_read_b128 v[178:181], v144 offset:17408
	ds_read_b128 v[182:185], v144 offset:18432
	ds_read_b128 v[186:189], v144 offset:19456
	ds_read_b128 v[190:193], v144 offset:20480
	ds_read_b128 v[194:197], v144 offset:21504
	ds_read_b128 v[198:201], v144 offset:22528
	ds_read_b128 v[202:205], v144 offset:23552
	global_load_lds_dwordx4 v[206:207], off
	s_add_i32 m0, s57, 0x2000
	s_add_u32 s58, s8, 0x80000
	v_lshl_add_u64 v[208:209], s[8:9], 0, v[128:129]
	s_addc_u32 s59, s9, 0
	s_add_i32 s57, s60, s10
	global_load_lds_dwordx4 v[208:209], off
	v_lshl_add_u64 v[210:211], s[58:59], 0, v[224:225]
	s_mov_b32 m0, s57
	v_lshl_add_u64 v[212:213], s[28:29], 0, v[130:131]
	global_load_lds_dwordx4 v[210:211], off
	v_lshl_add_u64 v[210:211], s[58:59], 0, v[128:129]
	s_add_i32 m0, s57, 0x2000
	s_nop 0
	global_load_lds_dwordx4 v[210:211], off
	v_lshl_add_u64 v[210:211], s[28:29], 0, v[132:133]
	s_mov_b32 m0, s31
	s_nop 0
	global_load_lds_dwordx4 v[210:211], off
	s_mov_b32 m0, s33
	s_nop 0
	global_load_lds_dwordx4 v[212:213], off
	s_waitcnt vmcnt(8)
	s_waitcnt lgkmcnt(0)
	s_barrier
	v_mfma_f32_16x16x32_bf16 v[52:55], v[140:143], v[174:177], v[52:55]
	v_mfma_f32_16x16x32_bf16 v[48:51], v[150:153], v[174:177], v[48:51]
	v_mfma_f32_16x16x32_bf16 v[36:39], v[140:143], v[182:185], v[36:39]
	v_mfma_f32_16x16x32_bf16 v[32:35], v[150:153], v[182:185], v[32:35]
	v_mfma_f32_16x16x32_bf16 v[20:23], v[140:143], v[190:193], v[20:23]
	v_mfma_f32_16x16x32_bf16 v[16:19], v[150:153], v[190:193], v[16:19]
	v_mfma_f32_16x16x32_bf16 v[4:7], v[140:143], v[198:201], v[4:7]
	v_mfma_f32_16x16x32_bf16 v[0:3], v[150:153], v[198:201], v[0:3]
	v_mfma_f32_16x16x32_bf16 v[52:55], v[146:149], v[178:181], v[52:55]
	v_mfma_f32_16x16x32_bf16 v[48:51], v[154:157], v[178:181], v[48:51]
	v_mfma_f32_16x16x32_bf16 v[36:39], v[146:149], v[186:189], v[36:39]
	v_mfma_f32_16x16x32_bf16 v[32:35], v[154:157], v[186:189], v[32:35]
	v_mfma_f32_16x16x32_bf16 v[20:23], v[146:149], v[194:197], v[20:23]
	v_mfma_f32_16x16x32_bf16 v[16:19], v[154:157], v[194:197], v[16:19]
	v_mfma_f32_16x16x32_bf16 v[4:7], v[146:149], v[202:205], v[4:7]
	v_mfma_f32_16x16x32_bf16 v[0:3], v[154:157], v[202:205], v[0:3]
	v_mfma_f32_16x16x32_bf16 v[64:67], v[158:161], v[174:177], v[64:67]
	v_mfma_f32_16x16x32_bf16 v[56:59], v[166:169], v[174:177], v[56:59]
	v_mfma_f32_16x16x32_bf16 v[44:47], v[158:161], v[182:185], v[44:47]
	v_mfma_f32_16x16x32_bf16 v[40:43], v[166:169], v[182:185], v[40:43]
	v_mfma_f32_16x16x32_bf16 v[28:31], v[158:161], v[190:193], v[28:31]
	v_mfma_f32_16x16x32_bf16 v[24:27], v[166:169], v[190:193], v[24:27]
	v_mfma_f32_16x16x32_bf16 v[8:11], v[158:161], v[198:201], v[8:11]
	v_mfma_f32_16x16x32_bf16 v[12:15], v[166:169], v[198:201], v[12:15]
	v_mfma_f32_16x16x32_bf16 v[64:67], v[162:165], v[178:181], v[64:67]
	v_mfma_f32_16x16x32_bf16 v[56:59], v[170:173], v[178:181], v[56:59]
	v_mfma_f32_16x16x32_bf16 v[44:47], v[162:165], v[186:189], v[44:47]
	v_mfma_f32_16x16x32_bf16 v[40:43], v[170:173], v[186:189], v[40:43]
	v_mfma_f32_16x16x32_bf16 v[28:31], v[162:165], v[194:197], v[28:31]
	v_mfma_f32_16x16x32_bf16 v[24:27], v[170:173], v[194:197], v[24:27]
	v_mfma_f32_16x16x32_bf16 v[8:11], v[162:165], v[202:205], v[8:11]
	v_mfma_f32_16x16x32_bf16 v[12:15], v[170:173], v[202:205], v[12:15]
	s_barrier
	s_add_i32 s57, 0, 0x18000
	v_add_u32_e32 v138, s57, v139
	s_add_i32 s58, 0, 0x1c000
	ds_read_b128 v[140:143], v138
	ds_read_b128 v[146:149], v138 offset:1024
	ds_read_b128 v[150:153], v138 offset:2048
	ds_read_b128 v[154:157], v138 offset:3072
	v_add_u32_e32 v138, s58, v139
	ds_read_b128 v[158:161], v138
	ds_read_b128 v[162:165], v138 offset:1024
	ds_read_b128 v[166:169], v138 offset:2048
	ds_read_b128 v[170:173], v138 offset:3072
	s_add_u32 s28, s28, 0x80000
	s_addc_u32 s29, s29, 0
	s_mov_b32 m0, s42
	v_lshl_add_u64 v[214:215], s[28:29], 0, v[132:133]
	ds_read_b128 v[174:177], v144 offset:32768
	ds_read_b128 v[178:181], v144 offset:33792
	ds_read_b128 v[182:185], v144 offset:34816
	ds_read_b128 v[186:189], v144 offset:35840
	ds_read_b128 v[190:193], v144 offset:36864
	ds_read_b128 v[194:197], v144 offset:37888
	ds_read_b128 v[198:201], v144 offset:38912
	ds_read_b128 v[202:205], v144 offset:39936
	global_load_lds_dwordx4 v[214:215], off
	v_lshl_add_u64 v[214:215], s[28:29], 0, v[130:131]
	s_mov_b32 m0, s43
	s_nop 0
	global_load_lds_dwordx4 v[214:215], off
	s_waitcnt vmcnt(8)
	s_waitcnt lgkmcnt(0)
	s_barrier
	v_mfma_f32_16x16x32_bf16 v[116:119], v[140:143], v[174:177], v[116:119]
	v_mfma_f32_16x16x32_bf16 v[112:115], v[150:153], v[174:177], v[112:115]
	v_mfma_f32_16x16x32_bf16 v[100:103], v[140:143], v[182:185], v[100:103]
	v_mfma_f32_16x16x32_bf16 v[96:99], v[150:153], v[182:185], v[96:99]
	v_mfma_f32_16x16x32_bf16 v[84:87], v[140:143], v[190:193], v[84:87]
	v_mfma_f32_16x16x32_bf16 v[80:83], v[150:153], v[190:193], v[80:83]
	v_mfma_f32_16x16x32_bf16 v[68:71], v[140:143], v[198:201], v[68:71]
	v_mfma_f32_16x16x32_bf16 v[60:63], v[150:153], v[198:201], v[60:63]
	v_mfma_f32_16x16x32_bf16 v[116:119], v[146:149], v[178:181], v[116:119]
	v_mfma_f32_16x16x32_bf16 v[112:115], v[154:157], v[178:181], v[112:115]
	v_mfma_f32_16x16x32_bf16 v[100:103], v[146:149], v[186:189], v[100:103]
	v_mfma_f32_16x16x32_bf16 v[96:99], v[154:157], v[186:189], v[96:99]
	v_mfma_f32_16x16x32_bf16 v[84:87], v[146:149], v[194:197], v[84:87]
	v_mfma_f32_16x16x32_bf16 v[80:83], v[154:157], v[194:197], v[80:83]
	v_mfma_f32_16x16x32_bf16 v[68:71], v[146:149], v[202:205], v[68:71]
	v_mfma_f32_16x16x32_bf16 v[60:63], v[154:157], v[202:205], v[60:63]
	v_mfma_f32_16x16x32_bf16 v[124:127], v[158:161], v[174:177], v[124:127]
	v_mfma_f32_16x16x32_bf16 v[120:123], v[166:169], v[174:177], v[120:123]
	v_mfma_f32_16x16x32_bf16 v[108:111], v[158:161], v[182:185], v[108:111]
	v_mfma_f32_16x16x32_bf16 v[104:107], v[166:169], v[182:185], v[104:107]
	v_mfma_f32_16x16x32_bf16 v[92:95], v[158:161], v[190:193], v[92:95]
	v_mfma_f32_16x16x32_bf16 v[88:91], v[166:169], v[190:193], v[88:91]
	v_mfma_f32_16x16x32_bf16 v[76:79], v[158:161], v[198:201], v[76:79]
	v_mfma_f32_16x16x32_bf16 v[72:75], v[166:169], v[198:201], v[72:75]
	v_mfma_f32_16x16x32_bf16 v[124:127], v[162:165], v[178:181], v[124:127]
	v_mfma_f32_16x16x32_bf16 v[120:123], v[170:173], v[178:181], v[120:123]
	v_mfma_f32_16x16x32_bf16 v[108:111], v[162:165], v[186:189], v[108:111]
	v_mfma_f32_16x16x32_bf16 v[104:107], v[170:173], v[186:189], v[104:107]
	v_mfma_f32_16x16x32_bf16 v[92:95], v[162:165], v[194:197], v[92:95]
	v_mfma_f32_16x16x32_bf16 v[88:91], v[170:173], v[194:197], v[88:91]
	v_mfma_f32_16x16x32_bf16 v[76:79], v[162:165], v[202:205], v[76:79]
	v_mfma_f32_16x16x32_bf16 v[72:75], v[170:173], v[202:205], v[72:75]
	s_barrier
	s_add_i32 s28, s57, s10
	v_lshl_add_u64 v[206:207], v[206:207], 0, s[24:25]
	s_mov_b32 m0, s28
	ds_read_b128 v[174:177], v144 offset:49152
	ds_read_b128 v[178:181], v144 offset:50176
	ds_read_b128 v[182:185], v144 offset:51200
	ds_read_b128 v[186:189], v144 offset:52224
	ds_read_b128 v[190:193], v144 offset:53248
	ds_read_b128 v[194:197], v144 offset:54272
	ds_read_b128 v[198:201], v144 offset:55296
	ds_read_b128 v[202:205], v144 offset:56320
	global_load_lds_dwordx4 v[206:207], off
	s_add_i32 m0, s28, 0x2000
	s_add_u32 s8, s8, 0x80080
	v_lshl_add_u64 v[206:207], v[208:209], 0, s[24:25]
	s_addc_u32 s9, s9, 0
	s_add_i32 s28, s58, s10
	global_load_lds_dwordx4 v[206:207], off
	v_lshl_add_u64 v[206:207], s[8:9], 0, v[224:225]
	s_mov_b32 m0, s28
	s_nop 0
	global_load_lds_dwordx4 v[206:207], off
	v_lshl_add_u64 v[206:207], s[8:9], 0, v[128:129]
	s_add_i32 m0, s28, 0x2000
	s_nop 0
	global_load_lds_dwordx4 v[206:207], off
	v_lshl_add_u64 v[206:207], v[210:211], 0, s[24:25]
	s_mov_b32 m0, s46
	s_nop 0
	global_load_lds_dwordx4 v[206:207], off
	v_lshl_add_u64 v[206:207], v[212:213], 0, s[24:25]
	s_mov_b32 m0, s47
	s_nop 0
	global_load_lds_dwordx4 v[206:207], off
	s_waitcnt vmcnt(8)
	s_waitcnt lgkmcnt(0)
	s_barrier
	v_mfma_f32_16x16x32_bf16 v[52:55], v[140:143], v[174:177], v[52:55]
	v_mfma_f32_16x16x32_bf16 v[48:51], v[150:153], v[174:177], v[48:51]
	v_mfma_f32_16x16x32_bf16 v[36:39], v[140:143], v[182:185], v[36:39]
	v_mfma_f32_16x16x32_bf16 v[32:35], v[150:153], v[182:185], v[32:35]
	v_mfma_f32_16x16x32_bf16 v[20:23], v[140:143], v[190:193], v[20:23]
	v_mfma_f32_16x16x32_bf16 v[16:19], v[150:153], v[190:193], v[16:19]
	v_mfma_f32_16x16x32_bf16 v[4:7], v[140:143], v[198:201], v[4:7]
	v_mfma_f32_16x16x32_bf16 v[0:3], v[150:153], v[198:201], v[0:3]
	v_mfma_f32_16x16x32_bf16 v[52:55], v[146:149], v[178:181], v[52:55]
	v_mfma_f32_16x16x32_bf16 v[48:51], v[154:157], v[178:181], v[48:51]
	v_mfma_f32_16x16x32_bf16 v[36:39], v[146:149], v[186:189], v[36:39]
	v_mfma_f32_16x16x32_bf16 v[32:35], v[154:157], v[186:189], v[32:35]
	v_mfma_f32_16x16x32_bf16 v[20:23], v[146:149], v[194:197], v[20:23]
	v_mfma_f32_16x16x32_bf16 v[16:19], v[154:157], v[194:197], v[16:19]
	v_mfma_f32_16x16x32_bf16 v[4:7], v[146:149], v[202:205], v[4:7]
	v_mfma_f32_16x16x32_bf16 v[0:3], v[154:157], v[202:205], v[0:3]
	v_mfma_f32_16x16x32_bf16 v[64:67], v[158:161], v[174:177], v[64:67]
	v_mfma_f32_16x16x32_bf16 v[56:59], v[166:169], v[174:177], v[56:59]
	v_mfma_f32_16x16x32_bf16 v[44:47], v[158:161], v[182:185], v[44:47]
	v_mfma_f32_16x16x32_bf16 v[40:43], v[166:169], v[182:185], v[40:43]
	v_mfma_f32_16x16x32_bf16 v[28:31], v[158:161], v[190:193], v[28:31]
	v_mfma_f32_16x16x32_bf16 v[24:27], v[166:169], v[190:193], v[24:27]
	v_mfma_f32_16x16x32_bf16 v[8:11], v[158:161], v[198:201], v[8:11]
	v_mfma_f32_16x16x32_bf16 v[12:15], v[166:169], v[198:201], v[12:15]
	v_mfma_f32_16x16x32_bf16 v[64:67], v[162:165], v[178:181], v[64:67]
	v_mfma_f32_16x16x32_bf16 v[56:59], v[170:173], v[178:181], v[56:59]
	v_mfma_f32_16x16x32_bf16 v[44:47], v[162:165], v[186:189], v[44:47]
	v_mfma_f32_16x16x32_bf16 v[40:43], v[170:173], v[186:189], v[40:43]
	v_mfma_f32_16x16x32_bf16 v[28:31], v[162:165], v[194:197], v[28:31]
	v_mfma_f32_16x16x32_bf16 v[24:27], v[170:173], v[194:197], v[24:27]
	v_mfma_f32_16x16x32_bf16 v[8:11], v[162:165], v[202:205], v[8:11]
	v_mfma_f32_16x16x32_bf16 v[12:15], v[170:173], v[202:205], v[12:15]
	s_barrier
	s_add_u32 s12, s12, 0x100
	s_addc_u32 s13, s13, 0
	s_add_u32 s54, s54, 0x100
	s_addc_u32 s55, s55, 0
	s_cmp_ge_i32 s56, s45
	s_mov_b32 s8, s56
	s_cbranch_scc0 .LBB0_1313
	s_mov_b32 s53, 0x5040100
	s_mov_b64 s[56:57], 0x400000
	s_mov_b64 s[58:59], 0x3fffff
	s_mov_b64 s[60:61], 0x20000

.LBB0_1626:
	s_add_i32 s33, s8, 2
	s_add_u32 s9, s12, 0xfff80080
	s_addc_u32 s28, s13, -1
	s_add_i32 s40, 0, 0x10000
	s_cmp_eq_u32 s68, s8
	s_cselect_b32 s29, s3, s28
	s_cselect_b32 s28, s7, s9
	s_cselect_b32 s9, s10, s31
	s_cselect_b32 s8, s21, s30
	s_add_i32 s43, 0, 0x14000
	v_add_u32_e32 v140, s40, v200
	v_add_u32_e32 v156, s43, v200
	ds_read_b128 v[128:131], v140
	ds_read_b128 v[132:135], v140 offset:1024
	ds_read_b128 v[136:139], v140 offset:2048
	ds_read_b128 v[140:143], v140 offset:3072
	ds_read_b128 v[144:147], v156
	ds_read_b128 v[148:151], v156 offset:1024
	ds_read_b128 v[152:155], v156 offset:2048
	ds_read_b128 v[156:159], v156 offset:3072
	v_lshl_add_u64 v[206:207], s[12:13], 0, v[184:185]
	s_add_i32 m0, s56, 0xc000
	ds_read_b128 v[160:163], v201
	ds_read_b128 v[164:167], v201 offset:1024
	ds_read_b128 v[168:171], v201 offset:2048
	ds_read_b128 v[172:175], v201 offset:3072
	ds_read_b128 v[188:191], v201 offset:4096
	ds_read_b128 v[192:195], v201 offset:5120
	ds_read_b128 v[196:199], v201 offset:6144
	ds_read_b128 v[202:205], v201 offset:7168
	global_load_lds_dwordx4 v[206:207], off
	v_lshl_add_u64 v[206:207], s[12:13], 0, v[186:187]
	s_add_i32 m0, s56, 0xe000
	s_nop 0
	global_load_lds_dwordx4 v[206:207], off
	s_waitcnt vmcnt(8)
	s_waitcnt lgkmcnt(0)
	s_barrier
	v_mfma_f32_16x16x32_bf16 v[112:115], v[128:131], v[160:163], v[112:115]
	v_mfma_f32_16x16x32_bf16 v[116:119], v[136:139], v[160:163], v[116:119]
	v_mfma_f32_16x16x32_bf16 v[100:103], v[128:131], v[168:171], v[100:103]
	v_mfma_f32_16x16x32_bf16 v[96:99], v[136:139], v[168:171], v[96:99]
	v_mfma_f32_16x16x32_bf16 v[84:87], v[128:131], v[188:191], v[84:87]
	v_mfma_f32_16x16x32_bf16 v[80:83], v[136:139], v[188:191], v[80:83]
	v_mfma_f32_16x16x32_bf16 v[68:71], v[128:131], v[196:199], v[68:71]
	v_mfma_f32_16x16x32_bf16 v[64:67], v[136:139], v[196:199], v[64:67]
	v_mfma_f32_16x16x32_bf16 v[112:115], v[132:135], v[164:167], v[112:115]
	v_mfma_f32_16x16x32_bf16 v[116:119], v[140:143], v[164:167], v[116:119]
	v_mfma_f32_16x16x32_bf16 v[100:103], v[132:135], v[172:175], v[100:103]
	v_mfma_f32_16x16x32_bf16 v[96:99], v[140:143], v[172:175], v[96:99]
	v_mfma_f32_16x16x32_bf16 v[84:87], v[132:135], v[192:195], v[84:87]
	v_mfma_f32_16x16x32_bf16 v[80:83], v[140:143], v[192:195], v[80:83]
	v_mfma_f32_16x16x32_bf16 v[68:71], v[132:135], v[202:205], v[68:71]
	v_mfma_f32_16x16x32_bf16 v[64:67], v[140:143], v[202:205], v[64:67]
	v_mfma_f32_16x16x32_bf16 v[120:123], v[144:147], v[160:163], v[120:123]
	v_mfma_f32_16x16x32_bf16 v[124:127], v[152:155], v[160:163], v[124:127]
	v_mfma_f32_16x16x32_bf16 v[108:111], v[144:147], v[168:171], v[108:111]
	v_mfma_f32_16x16x32_bf16 v[104:107], v[152:155], v[168:171], v[104:107]
	v_mfma_f32_16x16x32_bf16 v[92:95], v[144:147], v[188:191], v[92:95]
	v_mfma_f32_16x16x32_bf16 v[88:91], v[152:155], v[188:191], v[88:91]
	v_mfma_f32_16x16x32_bf16 v[76:79], v[144:147], v[196:199], v[76:79]
	v_mfma_f32_16x16x32_bf16 v[72:75], v[152:155], v[196:199], v[72:75]
	v_mfma_f32_16x16x32_bf16 v[120:123], v[148:151], v[164:167], v[120:123]
	v_mfma_f32_16x16x32_bf16 v[124:127], v[156:159], v[164:167], v[124:127]
	v_mfma_f32_16x16x32_bf16 v[108:111], v[148:151], v[172:175], v[108:111]
	v_mfma_f32_16x16x32_bf16 v[104:107], v[156:159], v[172:175], v[104:107]
	v_mfma_f32_16x16x32_bf16 v[92:95], v[148:151], v[192:195], v[92:95]
	v_mfma_f32_16x16x32_bf16 v[88:91], v[156:159], v[192:195], v[88:91]
	v_mfma_f32_16x16x32_bf16 v[76:79], v[148:151], v[202:205], v[76:79]
	v_mfma_f32_16x16x32_bf16 v[72:75], v[156:159], v[202:205], v[72:75]
	s_barrier
	s_add_i32 s40, s40, s54
	v_lshl_add_u64 v[206:207], s[8:9], 0, v[180:181]
	s_mov_b32 m0, s40
	ds_read_b128 v[160:163], v201 offset:16384
	ds_read_b128 v[164:167], v201 offset:17408
	ds_read_b128 v[168:171], v201 offset:18432
	ds_read_b128 v[172:175], v201 offset:19456
	ds_read_b128 v[188:191], v201 offset:20480
	ds_read_b128 v[192:195], v201 offset:21504
	ds_read_b128 v[196:199], v201 offset:22528
	ds_read_b128 v[202:205], v201 offset:23552
	global_load_lds_dwordx4 v[206:207], off
	s_add_i32 m0, s40, 0x2000
	s_add_u32 s40, s8, 0x80000
	v_lshl_add_u64 v[208:209], s[8:9], 0, v[176:177]
	s_addc_u32 s41, s9, 0
	s_add_i32 s43, s43, s54
	global_load_lds_dwordx4 v[208:209], off
	v_lshl_add_u64 v[210:211], s[40:41], 0, v[180:181]
	s_mov_b32 m0, s43
	v_lshl_add_u64 v[212:213], s[28:29], 0, v[178:179]
	global_load_lds_dwordx4 v[210:211], off
	v_lshl_add_u64 v[210:211], s[40:41], 0, v[176:177]
	s_add_i32 m0, s43, 0x2000
	s_nop 0
	global_load_lds_dwordx4 v[210:211], off
	v_lshl_add_u64 v[210:211], s[28:29], 0, v[182:183]
	s_mov_b32 m0, s56
	s_nop 0
	global_load_lds_dwordx4 v[210:211], off
	s_mov_b32 m0, s57
	s_nop 0
	global_load_lds_dwordx4 v[212:213], off
	s_waitcnt vmcnt(8)
	s_waitcnt lgkmcnt(0)
	s_barrier
	v_mfma_f32_16x16x32_bf16 v[52:55], v[128:131], v[160:163], v[52:55]
	v_mfma_f32_16x16x32_bf16 v[48:51], v[136:139], v[160:163], v[48:51]
	v_mfma_f32_16x16x32_bf16 v[36:39], v[128:131], v[168:171], v[36:39]
	v_mfma_f32_16x16x32_bf16 v[32:35], v[136:139], v[168:171], v[32:35]
	v_mfma_f32_16x16x32_bf16 v[20:23], v[128:131], v[188:191], v[20:23]
	v_mfma_f32_16x16x32_bf16 v[16:19], v[136:139], v[188:191], v[16:19]
	v_mfma_f32_16x16x32_bf16 v[4:7], v[128:131], v[196:199], v[4:7]
	v_mfma_f32_16x16x32_bf16 v[0:3], v[136:139], v[196:199], v[0:3]
	v_mfma_f32_16x16x32_bf16 v[52:55], v[132:135], v[164:167], v[52:55]
	v_mfma_f32_16x16x32_bf16 v[48:51], v[140:143], v[164:167], v[48:51]
	v_mfma_f32_16x16x32_bf16 v[36:39], v[132:135], v[172:175], v[36:39]
	v_mfma_f32_16x16x32_bf16 v[32:35], v[140:143], v[172:175], v[32:35]
	v_mfma_f32_16x16x32_bf16 v[20:23], v[132:135], v[192:195], v[20:23]
	v_mfma_f32_16x16x32_bf16 v[16:19], v[140:143], v[192:195], v[16:19]
	v_mfma_f32_16x16x32_bf16 v[4:7], v[132:135], v[202:205], v[4:7]
	v_mfma_f32_16x16x32_bf16 v[0:3], v[140:143], v[202:205], v[0:3]
	v_mfma_f32_16x16x32_bf16 v[60:63], v[144:147], v[160:163], v[60:63]
	v_mfma_f32_16x16x32_bf16 v[56:59], v[152:155], v[160:163], v[56:59]
	v_mfma_f32_16x16x32_bf16 v[44:47], v[144:147], v[168:171], v[44:47]
	v_mfma_f32_16x16x32_bf16 v[40:43], v[152:155], v[168:171], v[40:43]
	v_mfma_f32_16x16x32_bf16 v[28:31], v[144:147], v[188:191], v[28:31]
	v_mfma_f32_16x16x32_bf16 v[24:27], v[152:155], v[188:191], v[24:27]
	v_mfma_f32_16x16x32_bf16 v[8:11], v[144:147], v[196:199], v[8:11]
	v_mfma_f32_16x16x32_bf16 v[12:15], v[152:155], v[196:199], v[12:15]
	v_mfma_f32_16x16x32_bf16 v[60:63], v[148:151], v[164:167], v[60:63]
	v_mfma_f32_16x16x32_bf16 v[56:59], v[156:159], v[164:167], v[56:59]
	v_mfma_f32_16x16x32_bf16 v[44:47], v[148:151], v[172:175], v[44:47]
	v_mfma_f32_16x16x32_bf16 v[40:43], v[156:159], v[172:175], v[40:43]
	v_mfma_f32_16x16x32_bf16 v[28:31], v[148:151], v[192:195], v[28:31]
	v_mfma_f32_16x16x32_bf16 v[24:27], v[156:159], v[192:195], v[24:27]
	v_mfma_f32_16x16x32_bf16 v[8:11], v[148:151], v[202:205], v[8:11]
	v_mfma_f32_16x16x32_bf16 v[12:15], v[156:159], v[202:205], v[12:15]
	s_barrier
	s_add_i32 s40, 0, 0x18000
	s_add_i32 s41, 0, 0x1c000
	v_add_u32_e32 v140, s40, v200
	v_add_u32_e32 v156, s41, v200
	ds_read_b128 v[128:131], v140
	ds_read_b128 v[132:135], v140 offset:1024
	ds_read_b128 v[136:139], v140 offset:2048
	ds_read_b128 v[140:143], v140 offset:3072
	ds_read_b128 v[144:147], v156
	ds_read_b128 v[148:151], v156 offset:1024
	ds_read_b128 v[152:155], v156 offset:2048
	ds_read_b128 v[156:159], v156 offset:3072
	s_add_u32 s28, s28, 0x80000
	s_addc_u32 s29, s29, 0
	s_mov_b32 m0, s58
	v_lshl_add_u64 v[214:215], s[28:29], 0, v[182:183]
	ds_read_b128 v[160:163], v201 offset:32768
	ds_read_b128 v[164:167], v201 offset:33792
	ds_read_b128 v[168:171], v201 offset:34816
	ds_read_b128 v[172:175], v201 offset:35840
	ds_read_b128 v[188:191], v201 offset:36864
	ds_read_b128 v[192:195], v201 offset:37888
	ds_read_b128 v[196:199], v201 offset:38912
	ds_read_b128 v[202:205], v201 offset:39936
	global_load_lds_dwordx4 v[214:215], off
	v_lshl_add_u64 v[214:215], s[28:29], 0, v[178:179]
	s_mov_b32 m0, s59
	s_nop 0
	global_load_lds_dwordx4 v[214:215], off
	s_waitcnt vmcnt(8)
	s_waitcnt lgkmcnt(0)
	s_barrier
	v_mfma_f32_16x16x32_bf16 v[112:115], v[128:131], v[160:163], v[112:115]
	v_mfma_f32_16x16x32_bf16 v[116:119], v[136:139], v[160:163], v[116:119]
	v_mfma_f32_16x16x32_bf16 v[100:103], v[128:131], v[168:171], v[100:103]
	v_mfma_f32_16x16x32_bf16 v[96:99], v[136:139], v[168:171], v[96:99]
	v_mfma_f32_16x16x32_bf16 v[84:87], v[128:131], v[188:191], v[84:87]
	v_mfma_f32_16x16x32_bf16 v[80:83], v[136:139], v[188:191], v[80:83]
	v_mfma_f32_16x16x32_bf16 v[68:71], v[128:131], v[196:199], v[68:71]
	v_mfma_f32_16x16x32_bf16 v[64:67], v[136:139], v[196:199], v[64:67]
	v_mfma_f32_16x16x32_bf16 v[112:115], v[132:135], v[164:167], v[112:115]
	v_mfma_f32_16x16x32_bf16 v[116:119], v[140:143], v[164:167], v[116:119]
	v_mfma_f32_16x16x32_bf16 v[100:103], v[132:135], v[172:175], v[100:103]
	v_mfma_f32_16x16x32_bf16 v[96:99], v[140:143], v[172:175], v[96:99]
	v_mfma_f32_16x16x32_bf16 v[84:87], v[132:135], v[192:195], v[84:87]
	v_mfma_f32_16x16x32_bf16 v[80:83], v[140:143], v[192:195], v[80:83]
	v_mfma_f32_16x16x32_bf16 v[68:71], v[132:135], v[202:205], v[68:71]
	v_mfma_f32_16x16x32_bf16 v[64:67], v[140:143], v[202:205], v[64:67]
	v_mfma_f32_16x16x32_bf16 v[120:123], v[144:147], v[160:163], v[120:123]
	v_mfma_f32_16x16x32_bf16 v[124:127], v[152:155], v[160:163], v[124:127]
	v_mfma_f32_16x16x32_bf16 v[108:111], v[144:147], v[168:171], v[108:111]
	v_mfma_f32_16x16x32_bf16 v[104:107], v[152:155], v[168:171], v[104:107]
	v_mfma_f32_16x16x32_bf16 v[92:95], v[144:147], v[188:191], v[92:95]
	v_mfma_f32_16x16x32_bf16 v[88:91], v[152:155], v[188:191], v[88:91]
	v_mfma_f32_16x16x32_bf16 v[76:79], v[144:147], v[196:199], v[76:79]
	v_mfma_f32_16x16x32_bf16 v[72:75], v[152:155], v[196:199], v[72:75]
	v_mfma_f32_16x16x32_bf16 v[120:123], v[148:151], v[164:167], v[120:123]
	v_mfma_f32_16x16x32_bf16 v[124:127], v[156:159], v[164:167], v[124:127]
	v_mfma_f32_16x16x32_bf16 v[108:111], v[148:151], v[172:175], v[108:111]
	v_mfma_f32_16x16x32_bf16 v[104:107], v[156:159], v[172:175], v[104:107]
	v_mfma_f32_16x16x32_bf16 v[92:95], v[148:151], v[192:195], v[92:95]
	v_mfma_f32_16x16x32_bf16 v[88:91], v[156:159], v[192:195], v[88:91]
	v_mfma_f32_16x16x32_bf16 v[76:79], v[148:151], v[202:205], v[76:79]
	v_mfma_f32_16x16x32_bf16 v[72:75], v[156:159], v[202:205], v[72:75]
	s_barrier
	s_add_i32 s28, s40, s54
	v_lshl_add_u64 v[206:207], v[206:207], 0, s[24:25]
	s_mov_b32 m0, s28
	ds_read_b128 v[160:163], v201 offset:49152
	ds_read_b128 v[164:167], v201 offset:50176
	ds_read_b128 v[168:171], v201 offset:51200
	ds_read_b128 v[172:175], v201 offset:52224
	ds_read_b128 v[188:191], v201 offset:53248
	ds_read_b128 v[192:195], v201 offset:54272
	ds_read_b128 v[196:199], v201 offset:55296
	ds_read_b128 v[202:205], v201 offset:56320
	global_load_lds_dwordx4 v[206:207], off
	s_add_i32 m0, s28, 0x2000
	s_add_u32 s8, s8, 0x80080
	v_lshl_add_u64 v[206:207], v[208:209], 0, s[24:25]
	s_addc_u32 s9, s9, 0
	s_add_i32 s28, s41, s54
	global_load_lds_dwordx4 v[206:207], off
	v_lshl_add_u64 v[206:207], s[8:9], 0, v[180:181]
	s_mov_b32 m0, s28
	s_nop 0
	global_load_lds_dwordx4 v[206:207], off
	v_lshl_add_u64 v[206:207], s[8:9], 0, v[176:177]
	s_add_i32 m0, s28, 0x2000
	s_nop 0
	global_load_lds_dwordx4 v[206:207], off
	v_lshl_add_u64 v[206:207], v[210:211], 0, s[24:25]
	s_mov_b32 m0, s66
	s_nop 0
	global_load_lds_dwordx4 v[206:207], off
	v_lshl_add_u64 v[206:207], v[212:213], 0, s[24:25]
	s_mov_b32 m0, s67
	s_nop 0
	global_load_lds_dwordx4 v[206:207], off
	s_waitcnt vmcnt(8)
	s_waitcnt lgkmcnt(0)
	s_barrier
	v_mfma_f32_16x16x32_bf16 v[52:55], v[128:131], v[160:163], v[52:55]
	v_mfma_f32_16x16x32_bf16 v[48:51], v[136:139], v[160:163], v[48:51]
	v_mfma_f32_16x16x32_bf16 v[36:39], v[128:131], v[168:171], v[36:39]
	v_mfma_f32_16x16x32_bf16 v[32:35], v[136:139], v[168:171], v[32:35]
	v_mfma_f32_16x16x32_bf16 v[20:23], v[128:131], v[188:191], v[20:23]
	v_mfma_f32_16x16x32_bf16 v[16:19], v[136:139], v[188:191], v[16:19]
	v_mfma_f32_16x16x32_bf16 v[4:7], v[128:131], v[196:199], v[4:7]
	v_mfma_f32_16x16x32_bf16 v[0:3], v[136:139], v[196:199], v[0:3]
	v_mfma_f32_16x16x32_bf16 v[52:55], v[132:135], v[164:167], v[52:55]
	v_mfma_f32_16x16x32_bf16 v[48:51], v[140:143], v[164:167], v[48:51]
	v_mfma_f32_16x16x32_bf16 v[36:39], v[132:135], v[172:175], v[36:39]
	v_mfma_f32_16x16x32_bf16 v[32:35], v[140:143], v[172:175], v[32:35]
	v_mfma_f32_16x16x32_bf16 v[20:23], v[132:135], v[192:195], v[20:23]
	v_mfma_f32_16x16x32_bf16 v[16:19], v[140:143], v[192:195], v[16:19]
	v_mfma_f32_16x16x32_bf16 v[4:7], v[132:135], v[202:205], v[4:7]
	v_mfma_f32_16x16x32_bf16 v[0:3], v[140:143], v[202:205], v[0:3]
	v_mfma_f32_16x16x32_bf16 v[60:63], v[144:147], v[160:163], v[60:63]
	v_mfma_f32_16x16x32_bf16 v[56:59], v[152:155], v[160:163], v[56:59]
	v_mfma_f32_16x16x32_bf16 v[44:47], v[144:147], v[168:171], v[44:47]
	v_mfma_f32_16x16x32_bf16 v[40:43], v[152:155], v[168:171], v[40:43]
	v_mfma_f32_16x16x32_bf16 v[28:31], v[144:147], v[188:191], v[28:31]
	v_mfma_f32_16x16x32_bf16 v[24:27], v[152:155], v[188:191], v[24:27]
	v_mfma_f32_16x16x32_bf16 v[8:11], v[144:147], v[196:199], v[8:11]
	v_mfma_f32_16x16x32_bf16 v[12:15], v[152:155], v[196:199], v[12:15]
	v_mfma_f32_16x16x32_bf16 v[60:63], v[148:151], v[164:167], v[60:63]
	v_mfma_f32_16x16x32_bf16 v[56:59], v[156:159], v[164:167], v[56:59]
	v_mfma_f32_16x16x32_bf16 v[44:47], v[148:151], v[172:175], v[44:47]
	v_mfma_f32_16x16x32_bf16 v[40:43], v[156:159], v[172:175], v[40:43]
	v_mfma_f32_16x16x32_bf16 v[28:31], v[148:151], v[192:195], v[28:31]
	v_mfma_f32_16x16x32_bf16 v[24:27], v[156:159], v[192:195], v[24:27]
	v_mfma_f32_16x16x32_bf16 v[8:11], v[148:151], v[202:205], v[8:11]
	v_mfma_f32_16x16x32_bf16 v[12:15], v[156:159], v[202:205], v[12:15]
	s_barrier
	s_add_u32 s12, s12, 0x100
	s_addc_u32 s13, s13, 0
	s_add_u32 s30, s30, 0x100
	s_addc_u32 s31, s31, 0
	s_cmp_ge_i32 s33, s65
	s_mov_b32 s8, s33
	s_cbranch_scc0 .LBB0_1626

.LBB0_1667:
	s_add_i32 s56, s8, 2
	s_add_u32 s9, s12, 0xfff80080
	s_addc_u32 s28, s13, -1
	s_add_i32 s57, 0, 0x10000
	s_cmp_eq_u32 s48, s8
	s_cselect_b32 s29, s27, s28
	s_cselect_b32 s28, s35, s9
	s_cselect_b32 s9, s52, s55
	s_cselect_b32 s8, s53, s54
	s_add_i32 s60, 0, 0x14000
	v_add_u32_e32 v152, s57, v138
	v_add_u32_e32 v168, s60, v138
	ds_read_b128 v[140:143], v152
	ds_read_b128 v[144:147], v152 offset:1024
	ds_read_b128 v[148:151], v152 offset:2048
	ds_read_b128 v[152:155], v152 offset:3072
	ds_read_b128 v[156:159], v168
	ds_read_b128 v[160:163], v168 offset:1024
	ds_read_b128 v[164:167], v168 offset:2048
	ds_read_b128 v[168:171], v168 offset:3072
	v_lshl_add_u64 v[204:205], s[12:13], 0, v[134:135]
	s_add_i32 m0, s31, 0xc000
	ds_read_b128 v[172:175], v139
	ds_read_b128 v[176:179], v139 offset:1024
	ds_read_b128 v[180:183], v139 offset:2048
	ds_read_b128 v[184:187], v139 offset:3072
	ds_read_b128 v[188:191], v139 offset:4096
	ds_read_b128 v[192:195], v139 offset:5120
	ds_read_b128 v[196:199], v139 offset:6144
	ds_read_b128 v[200:203], v139 offset:7168
	global_load_lds_dwordx4 v[204:205], off
	v_lshl_add_u64 v[204:205], s[12:13], 0, v[136:137]
	s_add_i32 m0, s31, 0xe000
	s_nop 0
	global_load_lds_dwordx4 v[204:205], off
	s_waitcnt vmcnt(8)
	s_waitcnt lgkmcnt(0)
	s_barrier
	v_mfma_f32_16x16x32_bf16 v[112:115], v[140:143], v[172:175], v[112:115]
	v_mfma_f32_16x16x32_bf16 v[116:119], v[148:151], v[172:175], v[116:119]
	v_mfma_f32_16x16x32_bf16 v[96:99], v[140:143], v[180:183], v[96:99]
	v_mfma_f32_16x16x32_bf16 v[100:103], v[148:151], v[180:183], v[100:103]
	v_mfma_f32_16x16x32_bf16 v[80:83], v[140:143], v[188:191], v[80:83]
	v_mfma_f32_16x16x32_bf16 v[84:87], v[148:151], v[188:191], v[84:87]
	v_mfma_f32_16x16x32_bf16 v[48:51], v[140:143], v[196:199], v[48:51]
	v_mfma_f32_16x16x32_bf16 v[52:55], v[148:151], v[196:199], v[52:55]
	v_mfma_f32_16x16x32_bf16 v[112:115], v[144:147], v[176:179], v[112:115]
	v_mfma_f32_16x16x32_bf16 v[116:119], v[152:155], v[176:179], v[116:119]
	v_mfma_f32_16x16x32_bf16 v[96:99], v[144:147], v[184:187], v[96:99]
	v_mfma_f32_16x16x32_bf16 v[100:103], v[152:155], v[184:187], v[100:103]
	v_mfma_f32_16x16x32_bf16 v[80:83], v[144:147], v[192:195], v[80:83]
	v_mfma_f32_16x16x32_bf16 v[84:87], v[152:155], v[192:195], v[84:87]
	v_mfma_f32_16x16x32_bf16 v[48:51], v[144:147], v[200:203], v[48:51]
	v_mfma_f32_16x16x32_bf16 v[52:55], v[152:155], v[200:203], v[52:55]
	v_mfma_f32_16x16x32_bf16 v[120:123], v[156:159], v[172:175], v[120:123]
	v_mfma_f32_16x16x32_bf16 v[124:127], v[164:167], v[172:175], v[124:127]
	v_mfma_f32_16x16x32_bf16 v[104:107], v[156:159], v[180:183], v[104:107]
	v_mfma_f32_16x16x32_bf16 v[108:111], v[164:167], v[180:183], v[108:111]
	v_mfma_f32_16x16x32_bf16 v[88:91], v[156:159], v[188:191], v[88:91]
	v_mfma_f32_16x16x32_bf16 v[92:95], v[164:167], v[188:191], v[92:95]
	v_mfma_f32_16x16x32_bf16 v[64:67], v[156:159], v[196:199], v[64:67]
	v_mfma_f32_16x16x32_bf16 v[68:71], v[164:167], v[196:199], v[68:71]
	v_mfma_f32_16x16x32_bf16 v[120:123], v[160:163], v[176:179], v[120:123]
	v_mfma_f32_16x16x32_bf16 v[124:127], v[168:171], v[176:179], v[124:127]
	v_mfma_f32_16x16x32_bf16 v[104:107], v[160:163], v[184:187], v[104:107]
	v_mfma_f32_16x16x32_bf16 v[108:111], v[168:171], v[184:187], v[108:111]
	v_mfma_f32_16x16x32_bf16 v[88:91], v[160:163], v[192:195], v[88:91]
	v_mfma_f32_16x16x32_bf16 v[92:95], v[168:171], v[192:195], v[92:95]
	v_mfma_f32_16x16x32_bf16 v[64:67], v[160:163], v[200:203], v[64:67]
	v_mfma_f32_16x16x32_bf16 v[68:71], v[168:171], v[200:203], v[68:71]
	s_barrier
	s_add_i32 s57, s57, s10
	v_lshl_add_u64 v[204:205], s[8:9], 0, v[224:225]
	s_mov_b32 m0, s57
	ds_read_b128 v[172:175], v139 offset:16384
	ds_read_b128 v[176:179], v139 offset:17408
	ds_read_b128 v[180:183], v139 offset:18432
	ds_read_b128 v[184:187], v139 offset:19456
	ds_read_b128 v[188:191], v139 offset:20480
	ds_read_b128 v[192:195], v139 offset:21504
	ds_read_b128 v[196:199], v139 offset:22528
	ds_read_b128 v[200:203], v139 offset:23552
	global_load_lds_dwordx4 v[204:205], off
	s_add_i32 m0, s57, 0x2000
	s_add_u32 s58, s8, 0x80000
	v_lshl_add_u64 v[206:207], s[8:9], 0, v[128:129]
	s_addc_u32 s59, s9, 0
	s_add_i32 s57, s60, s10
	global_load_lds_dwordx4 v[206:207], off
	v_lshl_add_u64 v[208:209], s[58:59], 0, v[224:225]
	s_mov_b32 m0, s57
	v_lshl_add_u64 v[210:211], s[28:29], 0, v[130:131]
	global_load_lds_dwordx4 v[208:209], off
	v_lshl_add_u64 v[208:209], s[58:59], 0, v[128:129]
	s_add_i32 m0, s57, 0x2000
	s_nop 0
	global_load_lds_dwordx4 v[208:209], off
	v_lshl_add_u64 v[208:209], s[28:29], 0, v[132:133]
	s_mov_b32 m0, s31
	s_nop 0
	global_load_lds_dwordx4 v[208:209], off
	s_mov_b32 m0, s33
	s_nop 0
	global_load_lds_dwordx4 v[210:211], off
	s_waitcnt vmcnt(8)
	s_waitcnt lgkmcnt(0)
	s_barrier
	v_mfma_f32_16x16x32_bf16 v[56:59], v[140:143], v[172:175], v[56:59]
	v_mfma_f32_16x16x32_bf16 v[60:63], v[148:151], v[172:175], v[60:63]
	v_mfma_f32_16x16x32_bf16 v[32:35], v[140:143], v[180:183], v[32:35]
	v_mfma_f32_16x16x32_bf16 v[36:39], v[148:151], v[180:183], v[36:39]
	v_mfma_f32_16x16x32_bf16 v[16:19], v[140:143], v[188:191], v[16:19]
	v_mfma_f32_16x16x32_bf16 v[20:23], v[148:151], v[188:191], v[20:23]
	v_mfma_f32_16x16x32_bf16 v[0:3], v[140:143], v[196:199], v[0:3]
	v_mfma_f32_16x16x32_bf16 v[4:7], v[148:151], v[196:199], v[4:7]
	v_mfma_f32_16x16x32_bf16 v[56:59], v[144:147], v[176:179], v[56:59]
	v_mfma_f32_16x16x32_bf16 v[60:63], v[152:155], v[176:179], v[60:63]
	v_mfma_f32_16x16x32_bf16 v[32:35], v[144:147], v[184:187], v[32:35]
	v_mfma_f32_16x16x32_bf16 v[36:39], v[152:155], v[184:187], v[36:39]
	v_mfma_f32_16x16x32_bf16 v[16:19], v[144:147], v[192:195], v[16:19]
	v_mfma_f32_16x16x32_bf16 v[20:23], v[152:155], v[192:195], v[20:23]
	v_mfma_f32_16x16x32_bf16 v[0:3], v[144:147], v[200:203], v[0:3]
	v_mfma_f32_16x16x32_bf16 v[4:7], v[152:155], v[200:203], v[4:7]
	v_mfma_f32_16x16x32_bf16 v[72:75], v[156:159], v[172:175], v[72:75]
	v_mfma_f32_16x16x32_bf16 v[76:79], v[164:167], v[172:175], v[76:79]
	v_mfma_f32_16x16x32_bf16 v[40:43], v[156:159], v[180:183], v[40:43]
	v_mfma_f32_16x16x32_bf16 v[44:47], v[164:167], v[180:183], v[44:47]
	v_mfma_f32_16x16x32_bf16 v[24:27], v[156:159], v[188:191], v[24:27]
	v_mfma_f32_16x16x32_bf16 v[28:31], v[164:167], v[188:191], v[28:31]
	v_mfma_f32_16x16x32_bf16 v[8:11], v[156:159], v[196:199], v[8:11]
	v_mfma_f32_16x16x32_bf16 v[12:15], v[164:167], v[196:199], v[12:15]
	v_mfma_f32_16x16x32_bf16 v[72:75], v[160:163], v[176:179], v[72:75]
	v_mfma_f32_16x16x32_bf16 v[76:79], v[168:171], v[176:179], v[76:79]
	v_mfma_f32_16x16x32_bf16 v[40:43], v[160:163], v[184:187], v[40:43]
	v_mfma_f32_16x16x32_bf16 v[44:47], v[168:171], v[184:187], v[44:47]
	v_mfma_f32_16x16x32_bf16 v[24:27], v[160:163], v[192:195], v[24:27]
	v_mfma_f32_16x16x32_bf16 v[28:31], v[168:171], v[192:195], v[28:31]
	v_mfma_f32_16x16x32_bf16 v[8:11], v[160:163], v[200:203], v[8:11]
	v_mfma_f32_16x16x32_bf16 v[12:15], v[168:171], v[200:203], v[12:15]
	s_barrier
	s_add_i32 s57, 0, 0x18000
	s_add_i32 s58, 0, 0x1c000
	v_add_u32_e32 v152, s57, v138
	v_add_u32_e32 v168, s58, v138
	ds_read_b128 v[140:143], v152
	ds_read_b128 v[144:147], v152 offset:1024
	ds_read_b128 v[148:151], v152 offset:2048
	ds_read_b128 v[152:155], v152 offset:3072
	ds_read_b128 v[156:159], v168
	ds_read_b128 v[160:163], v168 offset:1024
	ds_read_b128 v[164:167], v168 offset:2048
	ds_read_b128 v[168:171], v168 offset:3072
	s_add_u32 s28, s28, 0x80000
	s_addc_u32 s29, s29, 0
	s_mov_b32 m0, s42
	v_lshl_add_u64 v[212:213], s[28:29], 0, v[132:133]
	ds_read_b128 v[172:175], v139 offset:32768
	ds_read_b128 v[176:179], v139 offset:33792
	ds_read_b128 v[180:183], v139 offset:34816
	ds_read_b128 v[184:187], v139 offset:35840
	ds_read_b128 v[188:191], v139 offset:36864
	ds_read_b128 v[192:195], v139 offset:37888
	ds_read_b128 v[196:199], v139 offset:38912
	ds_read_b128 v[200:203], v139 offset:39936
	global_load_lds_dwordx4 v[212:213], off
	v_lshl_add_u64 v[212:213], s[28:29], 0, v[130:131]
	s_mov_b32 m0, s43
	s_nop 0
	global_load_lds_dwordx4 v[212:213], off
	s_waitcnt vmcnt(8)
	s_waitcnt lgkmcnt(0)
	s_barrier
	v_mfma_f32_16x16x32_bf16 v[112:115], v[140:143], v[172:175], v[112:115]
	v_mfma_f32_16x16x32_bf16 v[116:119], v[148:151], v[172:175], v[116:119]
	v_mfma_f32_16x16x32_bf16 v[96:99], v[140:143], v[180:183], v[96:99]
	v_mfma_f32_16x16x32_bf16 v[100:103], v[148:151], v[180:183], v[100:103]
	v_mfma_f32_16x16x32_bf16 v[80:83], v[140:143], v[188:191], v[80:83]
	v_mfma_f32_16x16x32_bf16 v[84:87], v[148:151], v[188:191], v[84:87]
	v_mfma_f32_16x16x32_bf16 v[48:51], v[140:143], v[196:199], v[48:51]
	v_mfma_f32_16x16x32_bf16 v[52:55], v[148:151], v[196:199], v[52:55]
	v_mfma_f32_16x16x32_bf16 v[112:115], v[144:147], v[176:179], v[112:115]
	v_mfma_f32_16x16x32_bf16 v[116:119], v[152:155], v[176:179], v[116:119]
	v_mfma_f32_16x16x32_bf16 v[96:99], v[144:147], v[184:187], v[96:99]
	v_mfma_f32_16x16x32_bf16 v[100:103], v[152:155], v[184:187], v[100:103]
	v_mfma_f32_16x16x32_bf16 v[80:83], v[144:147], v[192:195], v[80:83]
	v_mfma_f32_16x16x32_bf16 v[84:87], v[152:155], v[192:195], v[84:87]
	v_mfma_f32_16x16x32_bf16 v[48:51], v[144:147], v[200:203], v[48:51]
	v_mfma_f32_16x16x32_bf16 v[52:55], v[152:155], v[200:203], v[52:55]
	v_mfma_f32_16x16x32_bf16 v[120:123], v[156:159], v[172:175], v[120:123]
	v_mfma_f32_16x16x32_bf16 v[124:127], v[164:167], v[172:175], v[124:127]
	v_mfma_f32_16x16x32_bf16 v[104:107], v[156:159], v[180:183], v[104:107]
	v_mfma_f32_16x16x32_bf16 v[108:111], v[164:167], v[180:183], v[108:111]
	v_mfma_f32_16x16x32_bf16 v[88:91], v[156:159], v[188:191], v[88:91]
	v_mfma_f32_16x16x32_bf16 v[92:95], v[164:167], v[188:191], v[92:95]
	v_mfma_f32_16x16x32_bf16 v[64:67], v[156:159], v[196:199], v[64:67]
	v_mfma_f32_16x16x32_bf16 v[68:71], v[164:167], v[196:199], v[68:71]
	v_mfma_f32_16x16x32_bf16 v[120:123], v[160:163], v[176:179], v[120:123]
	v_mfma_f32_16x16x32_bf16 v[124:127], v[168:171], v[176:179], v[124:127]
	v_mfma_f32_16x16x32_bf16 v[104:107], v[160:163], v[184:187], v[104:107]
	v_mfma_f32_16x16x32_bf16 v[108:111], v[168:171], v[184:187], v[108:111]
	v_mfma_f32_16x16x32_bf16 v[88:91], v[160:163], v[192:195], v[88:91]
	v_mfma_f32_16x16x32_bf16 v[92:95], v[168:171], v[192:195], v[92:95]
	v_mfma_f32_16x16x32_bf16 v[64:67], v[160:163], v[200:203], v[64:67]
	v_mfma_f32_16x16x32_bf16 v[68:71], v[168:171], v[200:203], v[68:71]
	s_barrier
	s_add_i32 s28, s57, s10
	v_lshl_add_u64 v[204:205], v[204:205], 0, s[24:25]
	s_mov_b32 m0, s28
	ds_read_b128 v[172:175], v139 offset:49152
	ds_read_b128 v[176:179], v139 offset:50176
	ds_read_b128 v[180:183], v139 offset:51200
	ds_read_b128 v[184:187], v139 offset:52224
	ds_read_b128 v[188:191], v139 offset:53248
	ds_read_b128 v[192:195], v139 offset:54272
	ds_read_b128 v[196:199], v139 offset:55296
	ds_read_b128 v[200:203], v139 offset:56320
	global_load_lds_dwordx4 v[204:205], off
	s_add_i32 m0, s28, 0x2000
	s_add_u32 s8, s8, 0x80080
	v_lshl_add_u64 v[204:205], v[206:207], 0, s[24:25]
	s_addc_u32 s9, s9, 0
	s_add_i32 s28, s58, s10
	global_load_lds_dwordx4 v[204:205], off
	v_lshl_add_u64 v[204:205], s[8:9], 0, v[224:225]
	s_mov_b32 m0, s28
	s_nop 0
	global_load_lds_dwordx4 v[204:205], off
	v_lshl_add_u64 v[204:205], s[8:9], 0, v[128:129]
	s_add_i32 m0, s28, 0x2000
	s_nop 0
	global_load_lds_dwordx4 v[204:205], off
	v_lshl_add_u64 v[204:205], v[208:209], 0, s[24:25]
	s_mov_b32 m0, s46
	s_nop 0
	global_load_lds_dwordx4 v[204:205], off
	v_lshl_add_u64 v[204:205], v[210:211], 0, s[24:25]
	s_mov_b32 m0, s47
	s_nop 0
	global_load_lds_dwordx4 v[204:205], off
	s_waitcnt vmcnt(8)
	s_waitcnt lgkmcnt(0)
	s_barrier
	v_mfma_f32_16x16x32_bf16 v[56:59], v[140:143], v[172:175], v[56:59]
	v_mfma_f32_16x16x32_bf16 v[60:63], v[148:151], v[172:175], v[60:63]
	v_mfma_f32_16x16x32_bf16 v[32:35], v[140:143], v[180:183], v[32:35]
	v_mfma_f32_16x16x32_bf16 v[36:39], v[148:151], v[180:183], v[36:39]
	v_mfma_f32_16x16x32_bf16 v[16:19], v[140:143], v[188:191], v[16:19]
	v_mfma_f32_16x16x32_bf16 v[20:23], v[148:151], v[188:191], v[20:23]
	v_mfma_f32_16x16x32_bf16 v[0:3], v[140:143], v[196:199], v[0:3]
	v_mfma_f32_16x16x32_bf16 v[4:7], v[148:151], v[196:199], v[4:7]
	v_mfma_f32_16x16x32_bf16 v[56:59], v[144:147], v[176:179], v[56:59]
	v_mfma_f32_16x16x32_bf16 v[60:63], v[152:155], v[176:179], v[60:63]
	v_mfma_f32_16x16x32_bf16 v[32:35], v[144:147], v[184:187], v[32:35]
	v_mfma_f32_16x16x32_bf16 v[36:39], v[152:155], v[184:187], v[36:39]
	v_mfma_f32_16x16x32_bf16 v[16:19], v[144:147], v[192:195], v[16:19]
	v_mfma_f32_16x16x32_bf16 v[20:23], v[152:155], v[192:195], v[20:23]
	v_mfma_f32_16x16x32_bf16 v[0:3], v[144:147], v[200:203], v[0:3]
	v_mfma_f32_16x16x32_bf16 v[4:7], v[152:155], v[200:203], v[4:7]
	v_mfma_f32_16x16x32_bf16 v[72:75], v[156:159], v[172:175], v[72:75]
	v_mfma_f32_16x16x32_bf16 v[76:79], v[164:167], v[172:175], v[76:79]
	v_mfma_f32_16x16x32_bf16 v[40:43], v[156:159], v[180:183], v[40:43]
	v_mfma_f32_16x16x32_bf16 v[44:47], v[164:167], v[180:183], v[44:47]
	v_mfma_f32_16x16x32_bf16 v[24:27], v[156:159], v[188:191], v[24:27]
	v_mfma_f32_16x16x32_bf16 v[28:31], v[164:167], v[188:191], v[28:31]
	v_mfma_f32_16x16x32_bf16 v[8:11], v[156:159], v[196:199], v[8:11]
	v_mfma_f32_16x16x32_bf16 v[12:15], v[164:167], v[196:199], v[12:15]
	v_mfma_f32_16x16x32_bf16 v[72:75], v[160:163], v[176:179], v[72:75]
	v_mfma_f32_16x16x32_bf16 v[76:79], v[168:171], v[176:179], v[76:79]
	v_mfma_f32_16x16x32_bf16 v[40:43], v[160:163], v[184:187], v[40:43]
	v_mfma_f32_16x16x32_bf16 v[44:47], v[168:171], v[184:187], v[44:47]
	v_mfma_f32_16x16x32_bf16 v[24:27], v[160:163], v[192:195], v[24:27]
	v_mfma_f32_16x16x32_bf16 v[28:31], v[168:171], v[192:195], v[28:31]
	v_mfma_f32_16x16x32_bf16 v[8:11], v[160:163], v[200:203], v[8:11]
	v_mfma_f32_16x16x32_bf16 v[12:15], v[168:171], v[200:203], v[12:15]
	s_barrier
	s_add_u32 s12, s12, 0x100
	s_addc_u32 s13, s13, 0
	s_add_u32 s54, s54, 0x100
	s_addc_u32 s55, s55, 0
	s_cmp_ge_i32 s56, s45
	s_mov_b32 s8, s56
	s_cbranch_scc0 .LBB0_1667
	s_mov_b32 s53, 0x5040100
	s_mov_b64 s[56:57], 0x400000
	s_mov_b64 s[58:59], 0x3fffff
	s_mov_b64 s[60:61], 0x20000

.LBB0_1892:
	s_add_i32 s33, s8, 2
	s_add_u32 s35, s12, 0x80
	s_addc_u32 s9, s13, 0
	s_add_i32 s37, 0, 0x10000
	s_cmp_eq_u32 s61, s8
	s_cselect_b32 s9, s3, s9
	s_cselect_b32 s8, s7, s35
	s_cselect_b32 s65, s28, s31
	s_cselect_b32 s64, s29, s30
	s_add_i32 s35, 0, 0x14000
	v_add_u32_e32 v140, s37, v214
	v_add_u32_e32 v156, s35, v214
	ds_read_b128 v[128:131], v140
	ds_read_b128 v[132:135], v140 offset:1024
	ds_read_b128 v[136:139], v140 offset:2048
	ds_read_b128 v[140:143], v140 offset:3072
	ds_read_b128 v[144:147], v156
	ds_read_b128 v[148:151], v156 offset:1024
	ds_read_b128 v[152:155], v156 offset:2048
	ds_read_b128 v[156:159], v156 offset:3072
	v_lshl_add_u64 v[202:203], s[12:13], 0, v[194:195]
	s_add_i32 m0, s53, 0xc000
	ds_read_b128 v[160:163], v215
	ds_read_b128 v[164:167], v215 offset:1024
	ds_read_b128 v[168:171], v215 offset:2048
	ds_read_b128 v[172:175], v215 offset:3072
	ds_read_b128 v[176:179], v215 offset:4096
	ds_read_b128 v[180:183], v215 offset:5120
	ds_read_b128 v[184:187], v215 offset:6144
	ds_read_b128 v[198:201], v215 offset:7168
	global_load_lds_dwordx4 v[202:203], off
	v_lshl_add_u64 v[202:203], s[12:13], 0, v[196:197]
	s_add_i32 m0, s53, 0xe000
	s_nop 0
	global_load_lds_dwordx4 v[202:203], off
	s_waitcnt vmcnt(8)
	s_waitcnt lgkmcnt(0)
	s_barrier
	v_mfma_f32_16x16x32_bf16 v[124:127], v[128:131], v[160:163], v[124:127]
	v_mfma_f32_16x16x32_bf16 v[120:123], v[136:139], v[160:163], v[120:123]
	v_mfma_f32_16x16x32_bf16 v[108:111], v[128:131], v[168:171], v[108:111]
	v_mfma_f32_16x16x32_bf16 v[104:107], v[136:139], v[168:171], v[104:107]
	v_mfma_f32_16x16x32_bf16 v[92:95], v[128:131], v[176:179], v[92:95]
	v_mfma_f32_16x16x32_bf16 v[88:91], v[136:139], v[176:179], v[88:91]
	v_mfma_f32_16x16x32_bf16 v[76:79], v[128:131], v[184:187], v[76:79]
	v_mfma_f32_16x16x32_bf16 v[72:75], v[136:139], v[184:187], v[72:75]
	v_mfma_f32_16x16x32_bf16 v[124:127], v[132:135], v[164:167], v[124:127]
	v_mfma_f32_16x16x32_bf16 v[120:123], v[140:143], v[164:167], v[120:123]
	v_mfma_f32_16x16x32_bf16 v[108:111], v[132:135], v[172:175], v[108:111]
	v_mfma_f32_16x16x32_bf16 v[104:107], v[140:143], v[172:175], v[104:107]
	v_mfma_f32_16x16x32_bf16 v[92:95], v[132:135], v[180:183], v[92:95]
	v_mfma_f32_16x16x32_bf16 v[88:91], v[140:143], v[180:183], v[88:91]
	v_mfma_f32_16x16x32_bf16 v[76:79], v[132:135], v[198:201], v[76:79]
	v_mfma_f32_16x16x32_bf16 v[72:75], v[140:143], v[198:201], v[72:75]
	v_mfma_f32_16x16x32_bf16 v[116:119], v[144:147], v[160:163], v[116:119]
	v_mfma_f32_16x16x32_bf16 v[112:115], v[152:155], v[160:163], v[112:115]
	v_mfma_f32_16x16x32_bf16 v[100:103], v[144:147], v[168:171], v[100:103]
	v_mfma_f32_16x16x32_bf16 v[96:99], v[152:155], v[168:171], v[96:99]
	v_mfma_f32_16x16x32_bf16 v[84:87], v[144:147], v[176:179], v[84:87]
	v_mfma_f32_16x16x32_bf16 v[80:83], v[152:155], v[176:179], v[80:83]
	v_mfma_f32_16x16x32_bf16 v[68:71], v[144:147], v[184:187], v[68:71]
	v_mfma_f32_16x16x32_bf16 v[64:67], v[152:155], v[184:187], v[64:67]
	v_mfma_f32_16x16x32_bf16 v[116:119], v[148:151], v[164:167], v[116:119]
	v_mfma_f32_16x16x32_bf16 v[112:115], v[156:159], v[164:167], v[112:115]
	v_mfma_f32_16x16x32_bf16 v[100:103], v[148:151], v[172:175], v[100:103]
	v_mfma_f32_16x16x32_bf16 v[96:99], v[156:159], v[172:175], v[96:99]
	v_mfma_f32_16x16x32_bf16 v[84:87], v[148:151], v[180:183], v[84:87]
	v_mfma_f32_16x16x32_bf16 v[80:83], v[156:159], v[180:183], v[80:83]
	v_mfma_f32_16x16x32_bf16 v[68:71], v[148:151], v[198:201], v[68:71]
	v_mfma_f32_16x16x32_bf16 v[64:67], v[156:159], v[198:201], v[64:67]
	s_barrier
	s_add_i32 s37, s37, s50
	v_lshl_add_u64 v[202:203], s[64:65], 0, v[224:225]
	s_mov_b32 m0, s37
	ds_read_b128 v[160:163], v215 offset:16384
	ds_read_b128 v[164:167], v215 offset:17408
	ds_read_b128 v[168:171], v215 offset:18432
	ds_read_b128 v[172:175], v215 offset:19456
	ds_read_b128 v[176:179], v215 offset:20480
	ds_read_b128 v[180:183], v215 offset:21504
	ds_read_b128 v[184:187], v215 offset:22528
	ds_read_b128 v[198:201], v215 offset:23552
	global_load_lds_dwordx4 v[202:203], off
	s_add_i32 m0, s37, 0x2000
	v_lshl_add_u64 v[204:205], s[64:65], 0, v[188:189]
	s_add_u32 s64, s64, s10
	s_addc_u32 s65, s65, 0
	s_add_i32 s35, s35, s50
	global_load_lds_dwordx4 v[204:205], off
	v_lshl_add_u64 v[206:207], s[64:65], 0, v[224:225]
	s_mov_b32 m0, s35
	v_lshl_add_u64 v[208:209], s[64:65], 0, v[188:189]
	global_load_lds_dwordx4 v[206:207], off
	s_add_i32 m0, s35, 0x2000
	v_lshl_add_u64 v[210:211], s[8:9], 0, v[192:193]
	global_load_lds_dwordx4 v[208:209], off
	s_mov_b32 m0, s53
	v_lshl_add_u64 v[212:213], s[8:9], 0, v[190:191]
	global_load_lds_dwordx4 v[210:211], off
	s_mov_b32 m0, s54
	s_nop 0
	global_load_lds_dwordx4 v[212:213], off
	s_waitcnt vmcnt(8)
	s_waitcnt lgkmcnt(0)
	s_barrier
	v_mfma_f32_16x16x32_bf16 v[60:63], v[128:131], v[160:163], v[60:63]
	v_mfma_f32_16x16x32_bf16 v[56:59], v[136:139], v[160:163], v[56:59]
	v_mfma_f32_16x16x32_bf16 v[44:47], v[128:131], v[168:171], v[44:47]
	v_mfma_f32_16x16x32_bf16 v[40:43], v[136:139], v[168:171], v[40:43]
	v_mfma_f32_16x16x32_bf16 v[28:31], v[128:131], v[176:179], v[28:31]
	v_mfma_f32_16x16x32_bf16 v[24:27], v[136:139], v[176:179], v[24:27]
	v_mfma_f32_16x16x32_bf16 v[12:15], v[128:131], v[184:187], v[12:15]
	v_mfma_f32_16x16x32_bf16 v[8:11], v[136:139], v[184:187], v[8:11]
	v_mfma_f32_16x16x32_bf16 v[60:63], v[132:135], v[164:167], v[60:63]
	v_mfma_f32_16x16x32_bf16 v[56:59], v[140:143], v[164:167], v[56:59]
	v_mfma_f32_16x16x32_bf16 v[44:47], v[132:135], v[172:175], v[44:47]
	v_mfma_f32_16x16x32_bf16 v[40:43], v[140:143], v[172:175], v[40:43]
	v_mfma_f32_16x16x32_bf16 v[28:31], v[132:135], v[180:183], v[28:31]
	v_mfma_f32_16x16x32_bf16 v[24:27], v[140:143], v[180:183], v[24:27]
	v_mfma_f32_16x16x32_bf16 v[12:15], v[132:135], v[198:201], v[12:15]
	v_mfma_f32_16x16x32_bf16 v[8:11], v[140:143], v[198:201], v[8:11]
	v_mfma_f32_16x16x32_bf16 v[52:55], v[144:147], v[160:163], v[52:55]
	v_mfma_f32_16x16x32_bf16 v[48:51], v[152:155], v[160:163], v[48:51]
	v_mfma_f32_16x16x32_bf16 v[36:39], v[144:147], v[168:171], v[36:39]
	v_mfma_f32_16x16x32_bf16 v[32:35], v[152:155], v[168:171], v[32:35]
	v_mfma_f32_16x16x32_bf16 v[20:23], v[144:147], v[176:179], v[20:23]
	v_mfma_f32_16x16x32_bf16 v[16:19], v[152:155], v[176:179], v[16:19]
	v_mfma_f32_16x16x32_bf16 v[4:7], v[144:147], v[184:187], v[4:7]
	v_mfma_f32_16x16x32_bf16 v[0:3], v[152:155], v[184:187], v[0:3]
	v_mfma_f32_16x16x32_bf16 v[52:55], v[148:151], v[164:167], v[52:55]
	v_mfma_f32_16x16x32_bf16 v[48:51], v[156:159], v[164:167], v[48:51]
	v_mfma_f32_16x16x32_bf16 v[36:39], v[148:151], v[172:175], v[36:39]
	v_mfma_f32_16x16x32_bf16 v[32:35], v[156:159], v[172:175], v[32:35]
	v_mfma_f32_16x16x32_bf16 v[20:23], v[148:151], v[180:183], v[20:23]
	v_mfma_f32_16x16x32_bf16 v[16:19], v[156:159], v[180:183], v[16:19]
	v_mfma_f32_16x16x32_bf16 v[4:7], v[148:151], v[198:201], v[4:7]
	v_mfma_f32_16x16x32_bf16 v[0:3], v[156:159], v[198:201], v[0:3]
	s_barrier
	s_add_i32 s35, 0, 0x18000
	s_add_i32 s37, 0, 0x1c000
	v_add_u32_e32 v140, s35, v214
	v_add_u32_e32 v156, s37, v214
	ds_read_b128 v[128:131], v140
	ds_read_b128 v[132:135], v140 offset:1024
	ds_read_b128 v[136:139], v140 offset:2048
	ds_read_b128 v[140:143], v140 offset:3072
	ds_read_b128 v[144:147], v156
	ds_read_b128 v[148:151], v156 offset:1024
	ds_read_b128 v[152:155], v156 offset:2048
	ds_read_b128 v[156:159], v156 offset:3072
	s_add_u32 s8, s8, s10
	s_addc_u32 s9, s9, 0
	s_mov_b32 m0, s55
	v_lshl_add_u64 v[216:217], s[8:9], 0, v[192:193]
	ds_read_b128 v[160:163], v215 offset:32768
	ds_read_b128 v[164:167], v215 offset:33792
	ds_read_b128 v[168:171], v215 offset:34816
	ds_read_b128 v[172:175], v215 offset:35840
	ds_read_b128 v[176:179], v215 offset:36864
	ds_read_b128 v[180:183], v215 offset:37888
	ds_read_b128 v[184:187], v215 offset:38912
	ds_read_b128 v[198:201], v215 offset:39936
	global_load_lds_dwordx4 v[216:217], off
	v_lshl_add_u64 v[216:217], s[8:9], 0, v[190:191]
	s_mov_b32 m0, s56
	s_nop 0
	global_load_lds_dwordx4 v[216:217], off
	s_waitcnt vmcnt(8)
	s_waitcnt lgkmcnt(0)
	s_barrier
	v_mfma_f32_16x16x32_bf16 v[124:127], v[128:131], v[160:163], v[124:127]
	v_mfma_f32_16x16x32_bf16 v[120:123], v[136:139], v[160:163], v[120:123]
	v_mfma_f32_16x16x32_bf16 v[108:111], v[128:131], v[168:171], v[108:111]
	v_mfma_f32_16x16x32_bf16 v[104:107], v[136:139], v[168:171], v[104:107]
	v_mfma_f32_16x16x32_bf16 v[92:95], v[128:131], v[176:179], v[92:95]
	v_mfma_f32_16x16x32_bf16 v[88:91], v[136:139], v[176:179], v[88:91]
	v_mfma_f32_16x16x32_bf16 v[76:79], v[128:131], v[184:187], v[76:79]
	v_mfma_f32_16x16x32_bf16 v[72:75], v[136:139], v[184:187], v[72:75]
	v_mfma_f32_16x16x32_bf16 v[124:127], v[132:135], v[164:167], v[124:127]
	v_mfma_f32_16x16x32_bf16 v[120:123], v[140:143], v[164:167], v[120:123]
	v_mfma_f32_16x16x32_bf16 v[108:111], v[132:135], v[172:175], v[108:111]
	v_mfma_f32_16x16x32_bf16 v[104:107], v[140:143], v[172:175], v[104:107]
	v_mfma_f32_16x16x32_bf16 v[92:95], v[132:135], v[180:183], v[92:95]
	v_mfma_f32_16x16x32_bf16 v[88:91], v[140:143], v[180:183], v[88:91]
	v_mfma_f32_16x16x32_bf16 v[76:79], v[132:135], v[198:201], v[76:79]
	v_mfma_f32_16x16x32_bf16 v[72:75], v[140:143], v[198:201], v[72:75]
	v_mfma_f32_16x16x32_bf16 v[116:119], v[144:147], v[160:163], v[116:119]
	v_mfma_f32_16x16x32_bf16 v[112:115], v[152:155], v[160:163], v[112:115]
	v_mfma_f32_16x16x32_bf16 v[100:103], v[144:147], v[168:171], v[100:103]
	v_mfma_f32_16x16x32_bf16 v[96:99], v[152:155], v[168:171], v[96:99]
	v_mfma_f32_16x16x32_bf16 v[84:87], v[144:147], v[176:179], v[84:87]
	v_mfma_f32_16x16x32_bf16 v[80:83], v[152:155], v[176:179], v[80:83]
	v_mfma_f32_16x16x32_bf16 v[68:71], v[144:147], v[184:187], v[68:71]
	v_mfma_f32_16x16x32_bf16 v[64:67], v[152:155], v[184:187], v[64:67]
	v_mfma_f32_16x16x32_bf16 v[116:119], v[148:151], v[164:167], v[116:119]
	v_mfma_f32_16x16x32_bf16 v[112:115], v[156:159], v[164:167], v[112:115]
	v_mfma_f32_16x16x32_bf16 v[100:103], v[148:151], v[172:175], v[100:103]
	v_mfma_f32_16x16x32_bf16 v[96:99], v[156:159], v[172:175], v[96:99]
	v_mfma_f32_16x16x32_bf16 v[84:87], v[148:151], v[180:183], v[84:87]
	v_mfma_f32_16x16x32_bf16 v[80:83], v[156:159], v[180:183], v[80:83]
	v_mfma_f32_16x16x32_bf16 v[68:71], v[148:151], v[198:201], v[68:71]
	v_mfma_f32_16x16x32_bf16 v[64:67], v[156:159], v[198:201], v[64:67]
	s_barrier
	s_add_i32 s8, s35, s50
	v_lshl_add_u64 v[202:203], v[202:203], 0, s[24:25]
	s_mov_b32 m0, s8
	ds_read_b128 v[160:163], v215 offset:49152
	ds_read_b128 v[164:167], v215 offset:50176
	ds_read_b128 v[168:171], v215 offset:51200
	ds_read_b128 v[172:175], v215 offset:52224
	ds_read_b128 v[176:179], v215 offset:53248
	ds_read_b128 v[180:183], v215 offset:54272
	ds_read_b128 v[184:187], v215 offset:55296
	ds_read_b128 v[198:201], v215 offset:56320
	global_load_lds_dwordx4 v[202:203], off
	v_lshl_add_u64 v[202:203], v[204:205], 0, s[24:25]
	s_add_i32 m0, s8, 0x2000
	s_add_i32 s8, s37, s50
	global_load_lds_dwordx4 v[202:203], off
	v_lshl_add_u64 v[202:203], v[206:207], 0, s[24:25]
	s_mov_b32 m0, s8
	s_nop 0
	global_load_lds_dwordx4 v[202:203], off
	v_lshl_add_u64 v[202:203], v[208:209], 0, s[24:25]
	s_add_i32 m0, s8, 0x2000
	s_nop 0
	global_load_lds_dwordx4 v[202:203], off
	v_lshl_add_u64 v[202:203], v[210:211], 0, s[24:25]
	s_mov_b32 m0, s57
	s_nop 0
	global_load_lds_dwordx4 v[202:203], off
	v_lshl_add_u64 v[202:203], v[212:213], 0, s[24:25]
	s_mov_b32 m0, s58
	s_nop 0
	global_load_lds_dwordx4 v[202:203], off
	s_waitcnt vmcnt(8)
	s_waitcnt lgkmcnt(0)
	s_barrier
	v_mfma_f32_16x16x32_bf16 v[60:63], v[128:131], v[160:163], v[60:63]
	v_mfma_f32_16x16x32_bf16 v[56:59], v[136:139], v[160:163], v[56:59]
	v_mfma_f32_16x16x32_bf16 v[44:47], v[128:131], v[168:171], v[44:47]
	v_mfma_f32_16x16x32_bf16 v[40:43], v[136:139], v[168:171], v[40:43]
	v_mfma_f32_16x16x32_bf16 v[28:31], v[128:131], v[176:179], v[28:31]
	v_mfma_f32_16x16x32_bf16 v[24:27], v[136:139], v[176:179], v[24:27]
	v_mfma_f32_16x16x32_bf16 v[12:15], v[128:131], v[184:187], v[12:15]
	v_mfma_f32_16x16x32_bf16 v[8:11], v[136:139], v[184:187], v[8:11]
	v_mfma_f32_16x16x32_bf16 v[60:63], v[132:135], v[164:167], v[60:63]
	v_mfma_f32_16x16x32_bf16 v[56:59], v[140:143], v[164:167], v[56:59]
	v_mfma_f32_16x16x32_bf16 v[44:47], v[132:135], v[172:175], v[44:47]
	v_mfma_f32_16x16x32_bf16 v[40:43], v[140:143], v[172:175], v[40:43]
	v_mfma_f32_16x16x32_bf16 v[28:31], v[132:135], v[180:183], v[28:31]
	v_mfma_f32_16x16x32_bf16 v[24:27], v[140:143], v[180:183], v[24:27]
	v_mfma_f32_16x16x32_bf16 v[12:15], v[132:135], v[198:201], v[12:15]
	v_mfma_f32_16x16x32_bf16 v[8:11], v[140:143], v[198:201], v[8:11]
	v_mfma_f32_16x16x32_bf16 v[52:55], v[144:147], v[160:163], v[52:55]
	v_mfma_f32_16x16x32_bf16 v[48:51], v[152:155], v[160:163], v[48:51]
	v_mfma_f32_16x16x32_bf16 v[36:39], v[144:147], v[168:171], v[36:39]
	v_mfma_f32_16x16x32_bf16 v[32:35], v[152:155], v[168:171], v[32:35]
	v_mfma_f32_16x16x32_bf16 v[20:23], v[144:147], v[176:179], v[20:23]
	v_mfma_f32_16x16x32_bf16 v[16:19], v[152:155], v[176:179], v[16:19]
	v_mfma_f32_16x16x32_bf16 v[4:7], v[144:147], v[184:187], v[4:7]
	v_mfma_f32_16x16x32_bf16 v[0:3], v[152:155], v[184:187], v[0:3]
	v_mfma_f32_16x16x32_bf16 v[52:55], v[148:151], v[164:167], v[52:55]
	v_mfma_f32_16x16x32_bf16 v[48:51], v[156:159], v[164:167], v[48:51]
	v_mfma_f32_16x16x32_bf16 v[36:39], v[148:151], v[172:175], v[36:39]
	v_mfma_f32_16x16x32_bf16 v[32:35], v[156:159], v[172:175], v[32:35]
	v_mfma_f32_16x16x32_bf16 v[20:23], v[148:151], v[180:183], v[20:23]
	v_mfma_f32_16x16x32_bf16 v[16:19], v[156:159], v[180:183], v[16:19]
	v_mfma_f32_16x16x32_bf16 v[4:7], v[148:151], v[198:201], v[4:7]
	v_mfma_f32_16x16x32_bf16 v[0:3], v[156:159], v[198:201], v[0:3]
	s_barrier
	s_add_u32 s12, s12, 0x100
	s_addc_u32 s13, s13, 0
	s_add_u32 s30, s30, 0x100
	s_addc_u32 s31, s31, 0
	s_cmp_ge_i32 s33, s60
	s_mov_b32 s8, s33
	s_cbranch_scc0 .LBB0_1892
	v_readlane_b32 s64, v253, 21
	v_readlane_b32 s65, v253, 22

.LBB0_2049:
	s_add_i32 s48, s28, 2
	s_add_u32 s8, s12, 0x100
	s_addc_u32 s9, s13, 0
	s_add_i32 s49, 0, 0x10000
	s_cmp_eq_u32 s66, s28
	s_cselect_b32 s43, s7, s9
	s_cselect_b32 s42, s30, s8
	s_cselect_b32 s29, s31, s37
	s_cselect_b32 s28, s33, s35
	s_add_i32 s70, 0, 0x14000
	v_add_u32_e32 v140, s49, v248
	v_add_u32_e32 v156, s70, v248
	ds_read_b128 v[128:131], v140
	ds_read_b128 v[132:135], v140 offset:1024
	ds_read_b128 v[136:139], v140 offset:2048
	ds_read_b128 v[140:143], v140 offset:3072
	ds_read_b128 v[144:147], v156
	ds_read_b128 v[148:151], v156 offset:1024
	ds_read_b128 v[152:155], v156 offset:2048
	ds_read_b128 v[156:159], v156 offset:3072
	v_lshl_add_u64 v[192:193], s[12:13], 0, v[236:237]
	s_add_i32 m0, s55, 0xc000
	ds_read_b128 v[160:163], v249
	ds_read_b128 v[164:167], v249 offset:1024
	ds_read_b128 v[168:171], v249 offset:2048
	ds_read_b128 v[172:175], v249 offset:3072
	ds_read_b128 v[176:179], v249 offset:4096
	ds_read_b128 v[180:183], v249 offset:5120
	ds_read_b128 v[184:187], v249 offset:6144
	ds_read_b128 v[188:191], v249 offset:7168
	global_load_lds_dwordx4 v[192:193], off
	v_lshl_add_u64 v[192:193], s[12:13], 0, v[238:239]
	s_add_i32 m0, s55, 0xe000
	s_nop 0
	global_load_lds_dwordx4 v[192:193], off
	s_waitcnt vmcnt(8)
	s_waitcnt lgkmcnt(0)
	s_barrier
	v_mfma_f32_16x16x32_bf16 v[100:103], v[128:131], v[160:163], v[100:103]
	v_mfma_f32_16x16x32_bf16 v[116:119], v[136:139], v[160:163], v[116:119]
	v_mfma_f32_16x16x32_bf16 v[96:99], v[128:131], v[168:171], v[96:99]
	v_mfma_f32_16x16x32_bf16 v[112:115], v[136:139], v[168:171], v[112:115]
	v_mfma_f32_16x16x32_bf16 v[104:107], v[128:131], v[176:179], v[104:107]
	v_mfma_f32_16x16x32_bf16 v[120:123], v[136:139], v[176:179], v[120:123]
	v_mfma_f32_16x16x32_bf16 v[108:111], v[128:131], v[184:187], v[108:111]
	v_mfma_f32_16x16x32_bf16 v[124:127], v[136:139], v[184:187], v[124:127]
	v_mfma_f32_16x16x32_bf16 v[100:103], v[132:135], v[164:167], v[100:103]
	v_mfma_f32_16x16x32_bf16 v[116:119], v[140:143], v[164:167], v[116:119]
	v_mfma_f32_16x16x32_bf16 v[96:99], v[132:135], v[172:175], v[96:99]
	v_mfma_f32_16x16x32_bf16 v[112:115], v[140:143], v[172:175], v[112:115]
	v_mfma_f32_16x16x32_bf16 v[104:107], v[132:135], v[180:183], v[104:107]
	v_mfma_f32_16x16x32_bf16 v[120:123], v[140:143], v[180:183], v[120:123]
	v_mfma_f32_16x16x32_bf16 v[108:111], v[132:135], v[188:191], v[108:111]
	v_mfma_f32_16x16x32_bf16 v[124:127], v[140:143], v[188:191], v[124:127]
	v_mfma_f32_16x16x32_bf16 v[84:87], v[144:147], v[160:163], v[84:87]
	v_mfma_f32_16x16x32_bf16 v[68:71], v[152:155], v[160:163], v[68:71]
	v_mfma_f32_16x16x32_bf16 v[80:83], v[144:147], v[168:171], v[80:83]
	v_mfma_f32_16x16x32_bf16 v[64:67], v[152:155], v[168:171], v[64:67]
	v_mfma_f32_16x16x32_bf16 v[88:91], v[144:147], v[176:179], v[88:91]
	v_mfma_f32_16x16x32_bf16 v[72:75], v[152:155], v[176:179], v[72:75]
	v_mfma_f32_16x16x32_bf16 v[92:95], v[144:147], v[184:187], v[92:95]
	v_mfma_f32_16x16x32_bf16 v[76:79], v[152:155], v[184:187], v[76:79]
	v_mfma_f32_16x16x32_bf16 v[84:87], v[148:151], v[164:167], v[84:87]
	v_mfma_f32_16x16x32_bf16 v[68:71], v[156:159], v[164:167], v[68:71]
	v_mfma_f32_16x16x32_bf16 v[80:83], v[148:151], v[172:175], v[80:83]
	v_mfma_f32_16x16x32_bf16 v[64:67], v[156:159], v[172:175], v[64:67]
	v_mfma_f32_16x16x32_bf16 v[88:91], v[148:151], v[180:183], v[88:91]
	v_mfma_f32_16x16x32_bf16 v[72:75], v[156:159], v[180:183], v[72:75]
	v_mfma_f32_16x16x32_bf16 v[92:95], v[148:151], v[188:191], v[92:95]
	v_mfma_f32_16x16x32_bf16 v[76:79], v[156:159], v[188:191], v[76:79]
	s_barrier
	s_add_i32 s12, s49, s53
	v_lshl_add_u64 v[192:193], s[28:29], 0, v[224:225]
	s_mov_b32 m0, s12
	ds_read_b128 v[160:163], v249 offset:16384
	ds_read_b128 v[164:167], v249 offset:17408
	ds_read_b128 v[168:171], v249 offset:18432
	ds_read_b128 v[172:175], v249 offset:19456
	ds_read_b128 v[176:179], v249 offset:20480
	ds_read_b128 v[180:183], v249 offset:21504
	ds_read_b128 v[184:187], v249 offset:22528
	ds_read_b128 v[188:191], v249 offset:23552
	global_load_lds_dwordx4 v[192:193], off
	s_add_i32 m0, s12, 0x2000
	s_add_u32 s12, s28, 0x80000
	v_lshl_add_u64 v[194:195], s[28:29], 0, v[230:231]
	s_addc_u32 s13, s29, 0
	s_add_i32 s49, s70, s53
	global_load_lds_dwordx4 v[194:195], off
	v_lshl_add_u64 v[196:197], s[12:13], 0, v[224:225]
	s_mov_b32 m0, s49
	v_lshl_add_u64 v[198:199], s[42:43], 0, v[232:233]
	global_load_lds_dwordx4 v[196:197], off
	v_lshl_add_u64 v[196:197], s[12:13], 0, v[230:231]
	s_add_i32 m0, s49, 0x2000
	s_nop 0
	global_load_lds_dwordx4 v[196:197], off
	v_lshl_add_u64 v[196:197], s[42:43], 0, v[234:235]
	s_mov_b32 m0, s55
	s_nop 0
	global_load_lds_dwordx4 v[196:197], off
	s_mov_b32 m0, s56
	s_nop 0
	global_load_lds_dwordx4 v[198:199], off
	s_waitcnt vmcnt(8)
	s_waitcnt lgkmcnt(0)
	s_barrier
	v_mfma_f32_16x16x32_bf16 v[16:19], v[128:131], v[160:163], v[16:19]
	v_mfma_f32_16x16x32_bf16 v[44:47], v[136:139], v[160:163], v[44:47]
	v_mfma_f32_16x16x32_bf16 v[24:27], v[128:131], v[168:171], v[24:27]
	v_mfma_f32_16x16x32_bf16 v[52:55], v[136:139], v[168:171], v[52:55]
	v_mfma_f32_16x16x32_bf16 v[32:35], v[128:131], v[176:179], v[32:35]
	v_mfma_f32_16x16x32_bf16 v[56:59], v[136:139], v[176:179], v[56:59]
	v_mfma_f32_16x16x32_bf16 v[40:43], v[128:131], v[184:187], v[40:43]
	v_mfma_f32_16x16x32_bf16 v[60:63], v[136:139], v[184:187], v[60:63]
	v_mfma_f32_16x16x32_bf16 v[16:19], v[132:135], v[164:167], v[16:19]
	v_mfma_f32_16x16x32_bf16 v[44:47], v[140:143], v[164:167], v[44:47]
	v_mfma_f32_16x16x32_bf16 v[24:27], v[132:135], v[172:175], v[24:27]
	v_mfma_f32_16x16x32_bf16 v[52:55], v[140:143], v[172:175], v[52:55]
	v_mfma_f32_16x16x32_bf16 v[32:35], v[132:135], v[180:183], v[32:35]
	v_mfma_f32_16x16x32_bf16 v[56:59], v[140:143], v[180:183], v[56:59]
	v_mfma_f32_16x16x32_bf16 v[40:43], v[132:135], v[188:191], v[40:43]
	v_mfma_f32_16x16x32_bf16 v[60:63], v[140:143], v[188:191], v[60:63]
	v_mfma_f32_16x16x32_bf16 v[20:23], v[144:147], v[160:163], v[20:23]
	v_mfma_f32_16x16x32_bf16 v[4:7], v[152:155], v[160:163], v[4:7]
	v_mfma_f32_16x16x32_bf16 v[28:31], v[144:147], v[168:171], v[28:31]
	v_mfma_f32_16x16x32_bf16 v[0:3], v[152:155], v[168:171], v[0:3]
	v_mfma_f32_16x16x32_bf16 v[36:39], v[144:147], v[176:179], v[36:39]
	v_mfma_f32_16x16x32_bf16 v[8:11], v[152:155], v[176:179], v[8:11]
	v_mfma_f32_16x16x32_bf16 v[48:51], v[144:147], v[184:187], v[48:51]
	v_mfma_f32_16x16x32_bf16 v[12:15], v[152:155], v[184:187], v[12:15]
	v_mfma_f32_16x16x32_bf16 v[20:23], v[148:151], v[164:167], v[20:23]
	v_mfma_f32_16x16x32_bf16 v[4:7], v[156:159], v[164:167], v[4:7]
	v_mfma_f32_16x16x32_bf16 v[28:31], v[148:151], v[172:175], v[28:31]
	v_mfma_f32_16x16x32_bf16 v[0:3], v[156:159], v[172:175], v[0:3]
	v_mfma_f32_16x16x32_bf16 v[36:39], v[148:151], v[180:183], v[36:39]
	v_mfma_f32_16x16x32_bf16 v[8:11], v[156:159], v[180:183], v[8:11]
	v_mfma_f32_16x16x32_bf16 v[48:51], v[148:151], v[188:191], v[48:51]
	v_mfma_f32_16x16x32_bf16 v[12:15], v[156:159], v[188:191], v[12:15]
	s_barrier
	s_add_i32 s49, 0, 0x18000
	s_add_i32 s70, 0, 0x1c000
	v_add_u32_e32 v140, s49, v248
	v_add_u32_e32 v156, s70, v248
	ds_read_b128 v[128:131], v140
	ds_read_b128 v[132:135], v140 offset:1024
	ds_read_b128 v[136:139], v140 offset:2048
	ds_read_b128 v[140:143], v140 offset:3072
	ds_read_b128 v[144:147], v156
	ds_read_b128 v[148:151], v156 offset:1024
	ds_read_b128 v[152:155], v156 offset:2048
	ds_read_b128 v[156:159], v156 offset:3072
	s_add_u32 s12, s42, 0x80000
	s_addc_u32 s13, s43, 0
	s_mov_b32 m0, s57
	v_lshl_add_u64 v[200:201], s[12:13], 0, v[234:235]
	ds_read_b128 v[160:163], v249 offset:32768
	ds_read_b128 v[164:167], v249 offset:33792
	ds_read_b128 v[168:171], v249 offset:34816
	ds_read_b128 v[172:175], v249 offset:35840
	ds_read_b128 v[176:179], v249 offset:36864
	ds_read_b128 v[180:183], v249 offset:37888
	ds_read_b128 v[184:187], v249 offset:38912
	ds_read_b128 v[188:191], v249 offset:39936
	global_load_lds_dwordx4 v[200:201], off
	v_lshl_add_u64 v[200:201], s[12:13], 0, v[232:233]
	s_mov_b32 m0, s58
	s_nop 0
	global_load_lds_dwordx4 v[200:201], off
	s_waitcnt vmcnt(8)
	s_waitcnt lgkmcnt(0)
	s_barrier
	v_mfma_f32_16x16x32_bf16 v[100:103], v[128:131], v[160:163], v[100:103]
	v_mfma_f32_16x16x32_bf16 v[116:119], v[136:139], v[160:163], v[116:119]
	v_mfma_f32_16x16x32_bf16 v[96:99], v[128:131], v[168:171], v[96:99]
	v_mfma_f32_16x16x32_bf16 v[112:115], v[136:139], v[168:171], v[112:115]
	v_mfma_f32_16x16x32_bf16 v[104:107], v[128:131], v[176:179], v[104:107]
	v_mfma_f32_16x16x32_bf16 v[120:123], v[136:139], v[176:179], v[120:123]
	v_mfma_f32_16x16x32_bf16 v[108:111], v[128:131], v[184:187], v[108:111]
	v_mfma_f32_16x16x32_bf16 v[124:127], v[136:139], v[184:187], v[124:127]
	v_mfma_f32_16x16x32_bf16 v[100:103], v[132:135], v[164:167], v[100:103]
	v_mfma_f32_16x16x32_bf16 v[116:119], v[140:143], v[164:167], v[116:119]
	v_mfma_f32_16x16x32_bf16 v[96:99], v[132:135], v[172:175], v[96:99]
	v_mfma_f32_16x16x32_bf16 v[112:115], v[140:143], v[172:175], v[112:115]
	v_mfma_f32_16x16x32_bf16 v[104:107], v[132:135], v[180:183], v[104:107]
	v_mfma_f32_16x16x32_bf16 v[120:123], v[140:143], v[180:183], v[120:123]
	v_mfma_f32_16x16x32_bf16 v[108:111], v[132:135], v[188:191], v[108:111]
	v_mfma_f32_16x16x32_bf16 v[124:127], v[140:143], v[188:191], v[124:127]
	v_mfma_f32_16x16x32_bf16 v[84:87], v[144:147], v[160:163], v[84:87]
	v_mfma_f32_16x16x32_bf16 v[68:71], v[152:155], v[160:163], v[68:71]
	v_mfma_f32_16x16x32_bf16 v[80:83], v[144:147], v[168:171], v[80:83]
	v_mfma_f32_16x16x32_bf16 v[64:67], v[152:155], v[168:171], v[64:67]
	v_mfma_f32_16x16x32_bf16 v[88:91], v[144:147], v[176:179], v[88:91]
	v_mfma_f32_16x16x32_bf16 v[72:75], v[152:155], v[176:179], v[72:75]
	v_mfma_f32_16x16x32_bf16 v[92:95], v[144:147], v[184:187], v[92:95]
	v_mfma_f32_16x16x32_bf16 v[76:79], v[152:155], v[184:187], v[76:79]
	v_mfma_f32_16x16x32_bf16 v[84:87], v[148:151], v[164:167], v[84:87]
	v_mfma_f32_16x16x32_bf16 v[68:71], v[156:159], v[164:167], v[68:71]
	v_mfma_f32_16x16x32_bf16 v[80:83], v[148:151], v[172:175], v[80:83]
	v_mfma_f32_16x16x32_bf16 v[64:67], v[156:159], v[172:175], v[64:67]
	v_mfma_f32_16x16x32_bf16 v[88:91], v[148:151], v[180:183], v[88:91]
	v_mfma_f32_16x16x32_bf16 v[72:75], v[156:159], v[180:183], v[72:75]
	v_mfma_f32_16x16x32_bf16 v[92:95], v[148:151], v[188:191], v[92:95]
	v_mfma_f32_16x16x32_bf16 v[76:79], v[156:159], v[188:191], v[76:79]
	s_barrier
	s_add_i32 s12, s49, s53
	v_lshl_add_u64 v[192:193], v[192:193], 0, s[24:25]
	s_mov_b32 m0, s12
	ds_read_b128 v[160:163], v249 offset:49152
	ds_read_b128 v[164:167], v249 offset:50176
	ds_read_b128 v[168:171], v249 offset:51200
	ds_read_b128 v[172:175], v249 offset:52224
	ds_read_b128 v[176:179], v249 offset:53248
	ds_read_b128 v[180:183], v249 offset:54272
	ds_read_b128 v[184:187], v249 offset:55296
	ds_read_b128 v[188:191], v249 offset:56320
	global_load_lds_dwordx4 v[192:193], off
	s_add_i32 m0, s12, 0x2000
	s_add_u32 s12, s28, 0x80080
	v_lshl_add_u64 v[192:193], v[194:195], 0, s[24:25]
	s_addc_u32 s13, s29, 0
	s_add_i32 s28, s70, s53
	global_load_lds_dwordx4 v[192:193], off
	v_lshl_add_u64 v[192:193], s[12:13], 0, v[224:225]
	s_mov_b32 m0, s28
	s_nop 0
	global_load_lds_dwordx4 v[192:193], off
	v_lshl_add_u64 v[192:193], s[12:13], 0, v[230:231]
	s_add_i32 m0, s28, 0x2000
	s_nop 0
	global_load_lds_dwordx4 v[192:193], off
	v_lshl_add_u64 v[192:193], v[196:197], 0, s[24:25]
	s_mov_b32 m0, s63
	s_nop 0
	global_load_lds_dwordx4 v[192:193], off
	v_lshl_add_u64 v[192:193], v[198:199], 0, s[24:25]
	s_mov_b32 m0, s64
	s_nop 0
	global_load_lds_dwordx4 v[192:193], off
	s_waitcnt vmcnt(8)
	s_waitcnt lgkmcnt(0)
	s_barrier
	v_mfma_f32_16x16x32_bf16 v[16:19], v[128:131], v[160:163], v[16:19]
	v_mfma_f32_16x16x32_bf16 v[44:47], v[136:139], v[160:163], v[44:47]
	v_mfma_f32_16x16x32_bf16 v[24:27], v[128:131], v[168:171], v[24:27]
	v_mfma_f32_16x16x32_bf16 v[52:55], v[136:139], v[168:171], v[52:55]
	v_mfma_f32_16x16x32_bf16 v[32:35], v[128:131], v[176:179], v[32:35]
	v_mfma_f32_16x16x32_bf16 v[56:59], v[136:139], v[176:179], v[56:59]
	v_mfma_f32_16x16x32_bf16 v[40:43], v[128:131], v[184:187], v[40:43]
	v_mfma_f32_16x16x32_bf16 v[60:63], v[136:139], v[184:187], v[60:63]
	v_mfma_f32_16x16x32_bf16 v[16:19], v[132:135], v[164:167], v[16:19]
	v_mfma_f32_16x16x32_bf16 v[44:47], v[140:143], v[164:167], v[44:47]
	v_mfma_f32_16x16x32_bf16 v[24:27], v[132:135], v[172:175], v[24:27]
	v_mfma_f32_16x16x32_bf16 v[52:55], v[140:143], v[172:175], v[52:55]
	v_mfma_f32_16x16x32_bf16 v[32:35], v[132:135], v[180:183], v[32:35]
	v_mfma_f32_16x16x32_bf16 v[56:59], v[140:143], v[180:183], v[56:59]
	v_mfma_f32_16x16x32_bf16 v[40:43], v[132:135], v[188:191], v[40:43]
	v_mfma_f32_16x16x32_bf16 v[60:63], v[140:143], v[188:191], v[60:63]
	v_mfma_f32_16x16x32_bf16 v[20:23], v[144:147], v[160:163], v[20:23]
	v_mfma_f32_16x16x32_bf16 v[4:7], v[152:155], v[160:163], v[4:7]
	v_mfma_f32_16x16x32_bf16 v[28:31], v[144:147], v[168:171], v[28:31]
	v_mfma_f32_16x16x32_bf16 v[0:3], v[152:155], v[168:171], v[0:3]
	v_mfma_f32_16x16x32_bf16 v[36:39], v[144:147], v[176:179], v[36:39]
	v_mfma_f32_16x16x32_bf16 v[8:11], v[152:155], v[176:179], v[8:11]
	v_mfma_f32_16x16x32_bf16 v[48:51], v[144:147], v[184:187], v[48:51]
	v_mfma_f32_16x16x32_bf16 v[12:15], v[152:155], v[184:187], v[12:15]
	v_mfma_f32_16x16x32_bf16 v[20:23], v[148:151], v[164:167], v[20:23]
	v_mfma_f32_16x16x32_bf16 v[4:7], v[156:159], v[164:167], v[4:7]
	v_mfma_f32_16x16x32_bf16 v[28:31], v[148:151], v[172:175], v[28:31]
	v_mfma_f32_16x16x32_bf16 v[0:3], v[156:159], v[172:175], v[0:3]
	v_mfma_f32_16x16x32_bf16 v[36:39], v[148:151], v[180:183], v[36:39]
	v_mfma_f32_16x16x32_bf16 v[8:11], v[156:159], v[180:183], v[8:11]
	v_mfma_f32_16x16x32_bf16 v[48:51], v[148:151], v[188:191], v[48:51]
	v_mfma_f32_16x16x32_bf16 v[12:15], v[156:159], v[188:191], v[12:15]
	s_barrier
	s_add_u32 s35, s35, 0x100
	s_addc_u32 s37, s37, 0
	s_cmp_ge_i32 s48, s62
	s_mov_b64 s[12:13], s[8:9]
	s_mov_b32 s28, s48
	s_cbranch_scc0 .LBB0_2049

.LBB0_2092:
	s_add_i32 s58, s8, 2
	s_add_u32 s9, s12, 0xffff0080
	s_addc_u32 s28, s13, -1
	s_add_i32 s59, 0, 0x10000
	s_cmp_eq_u32 s50, s8
	s_cselect_b32 s29, s27, s28
	s_cselect_b32 s28, s35, s9
	s_cselect_b32 s9, s54, s57
	s_cselect_b32 s8, s55, s56
	s_add_i32 s62, 0, 0x14000
	v_add_u32_e32 v152, s59, v138
	v_add_u32_e32 v168, s62, v138
	ds_read_b128 v[140:143], v152
	ds_read_b128 v[144:147], v152 offset:1024
	ds_read_b128 v[148:151], v152 offset:2048
	ds_read_b128 v[152:155], v152 offset:3072
	ds_read_b128 v[156:159], v168
	ds_read_b128 v[160:163], v168 offset:1024
	ds_read_b128 v[164:167], v168 offset:2048
	ds_read_b128 v[168:171], v168 offset:3072
	v_lshl_add_u64 v[204:205], s[12:13], 0, v[134:135]
	s_add_i32 m0, s31, 0xc000
	ds_read_b128 v[172:175], v139
	ds_read_b128 v[176:179], v139 offset:1024
	ds_read_b128 v[180:183], v139 offset:2048
	ds_read_b128 v[184:187], v139 offset:3072
	ds_read_b128 v[188:191], v139 offset:4096
	ds_read_b128 v[192:195], v139 offset:5120
	ds_read_b128 v[196:199], v139 offset:6144
	ds_read_b128 v[200:203], v139 offset:7168
	global_load_lds_dwordx4 v[204:205], off
	v_lshl_add_u64 v[204:205], s[12:13], 0, v[136:137]
	s_add_i32 m0, s31, 0xe000
	s_nop 0
	global_load_lds_dwordx4 v[204:205], off
	s_waitcnt vmcnt(8)
	s_waitcnt lgkmcnt(0)
	s_barrier
	v_mfma_f32_16x16x32_bf16 v[112:115], v[140:143], v[172:175], v[112:115]
	v_mfma_f32_16x16x32_bf16 v[116:119], v[148:151], v[172:175], v[116:119]
	v_mfma_f32_16x16x32_bf16 v[96:99], v[140:143], v[180:183], v[96:99]
	v_mfma_f32_16x16x32_bf16 v[100:103], v[148:151], v[180:183], v[100:103]
	v_mfma_f32_16x16x32_bf16 v[80:83], v[140:143], v[188:191], v[80:83]
	v_mfma_f32_16x16x32_bf16 v[84:87], v[148:151], v[188:191], v[84:87]
	v_mfma_f32_16x16x32_bf16 v[48:51], v[140:143], v[196:199], v[48:51]
	v_mfma_f32_16x16x32_bf16 v[52:55], v[148:151], v[196:199], v[52:55]
	v_mfma_f32_16x16x32_bf16 v[112:115], v[144:147], v[176:179], v[112:115]
	v_mfma_f32_16x16x32_bf16 v[116:119], v[152:155], v[176:179], v[116:119]
	v_mfma_f32_16x16x32_bf16 v[96:99], v[144:147], v[184:187], v[96:99]
	v_mfma_f32_16x16x32_bf16 v[100:103], v[152:155], v[184:187], v[100:103]
	v_mfma_f32_16x16x32_bf16 v[80:83], v[144:147], v[192:195], v[80:83]
	v_mfma_f32_16x16x32_bf16 v[84:87], v[152:155], v[192:195], v[84:87]
	v_mfma_f32_16x16x32_bf16 v[48:51], v[144:147], v[200:203], v[48:51]
	v_mfma_f32_16x16x32_bf16 v[52:55], v[152:155], v[200:203], v[52:55]
	v_mfma_f32_16x16x32_bf16 v[120:123], v[156:159], v[172:175], v[120:123]
	v_mfma_f32_16x16x32_bf16 v[124:127], v[164:167], v[172:175], v[124:127]
	v_mfma_f32_16x16x32_bf16 v[104:107], v[156:159], v[180:183], v[104:107]
	v_mfma_f32_16x16x32_bf16 v[108:111], v[164:167], v[180:183], v[108:111]
	v_mfma_f32_16x16x32_bf16 v[88:91], v[156:159], v[188:191], v[88:91]
	v_mfma_f32_16x16x32_bf16 v[92:95], v[164:167], v[188:191], v[92:95]
	v_mfma_f32_16x16x32_bf16 v[64:67], v[156:159], v[196:199], v[64:67]
	v_mfma_f32_16x16x32_bf16 v[68:71], v[164:167], v[196:199], v[68:71]
	v_mfma_f32_16x16x32_bf16 v[120:123], v[160:163], v[176:179], v[120:123]
	v_mfma_f32_16x16x32_bf16 v[124:127], v[168:171], v[176:179], v[124:127]
	v_mfma_f32_16x16x32_bf16 v[104:107], v[160:163], v[184:187], v[104:107]
	v_mfma_f32_16x16x32_bf16 v[108:111], v[168:171], v[184:187], v[108:111]
	v_mfma_f32_16x16x32_bf16 v[88:91], v[160:163], v[192:195], v[88:91]
	v_mfma_f32_16x16x32_bf16 v[92:95], v[168:171], v[192:195], v[92:95]
	v_mfma_f32_16x16x32_bf16 v[64:67], v[160:163], v[200:203], v[64:67]
	v_mfma_f32_16x16x32_bf16 v[68:71], v[168:171], v[200:203], v[68:71]
	s_barrier
	s_add_i32 s59, s59, s10
	v_lshl_add_u64 v[204:205], s[8:9], 0, v[224:225]
	s_mov_b32 m0, s59
	ds_read_b128 v[172:175], v139 offset:16384
	ds_read_b128 v[176:179], v139 offset:17408
	ds_read_b128 v[180:183], v139 offset:18432
	ds_read_b128 v[184:187], v139 offset:19456
	ds_read_b128 v[188:191], v139 offset:20480
	ds_read_b128 v[192:195], v139 offset:21504
	ds_read_b128 v[196:199], v139 offset:22528
	ds_read_b128 v[200:203], v139 offset:23552
	global_load_lds_dwordx4 v[204:205], off
	s_add_i32 m0, s59, 0x2000
	s_add_u32 s60, s8, 0x10000
	v_lshl_add_u64 v[206:207], s[8:9], 0, v[128:129]
	s_addc_u32 s61, s9, 0
	s_add_i32 s59, s62, s10
	global_load_lds_dwordx4 v[206:207], off
	v_lshl_add_u64 v[208:209], s[60:61], 0, v[224:225]
	s_mov_b32 m0, s59
	v_lshl_add_u64 v[210:211], s[28:29], 0, v[130:131]
	global_load_lds_dwordx4 v[208:209], off
	v_lshl_add_u64 v[208:209], s[60:61], 0, v[128:129]
	s_add_i32 m0, s59, 0x2000
	s_nop 0
	global_load_lds_dwordx4 v[208:209], off
	v_lshl_add_u64 v[208:209], s[28:29], 0, v[132:133]
	s_mov_b32 m0, s31
	s_nop 0
	global_load_lds_dwordx4 v[208:209], off
	s_mov_b32 m0, s33
	s_nop 0
	global_load_lds_dwordx4 v[210:211], off
	s_waitcnt vmcnt(8)
	s_waitcnt lgkmcnt(0)
	s_barrier
	v_mfma_f32_16x16x32_bf16 v[56:59], v[140:143], v[172:175], v[56:59]
	v_mfma_f32_16x16x32_bf16 v[60:63], v[148:151], v[172:175], v[60:63]
	v_mfma_f32_16x16x32_bf16 v[32:35], v[140:143], v[180:183], v[32:35]
	v_mfma_f32_16x16x32_bf16 v[36:39], v[148:151], v[180:183], v[36:39]
	v_mfma_f32_16x16x32_bf16 v[16:19], v[140:143], v[188:191], v[16:19]
	v_mfma_f32_16x16x32_bf16 v[20:23], v[148:151], v[188:191], v[20:23]
	v_mfma_f32_16x16x32_bf16 v[0:3], v[140:143], v[196:199], v[0:3]
	v_mfma_f32_16x16x32_bf16 v[4:7], v[148:151], v[196:199], v[4:7]
	v_mfma_f32_16x16x32_bf16 v[56:59], v[144:147], v[176:179], v[56:59]
	v_mfma_f32_16x16x32_bf16 v[60:63], v[152:155], v[176:179], v[60:63]
	v_mfma_f32_16x16x32_bf16 v[32:35], v[144:147], v[184:187], v[32:35]
	v_mfma_f32_16x16x32_bf16 v[36:39], v[152:155], v[184:187], v[36:39]
	v_mfma_f32_16x16x32_bf16 v[16:19], v[144:147], v[192:195], v[16:19]
	v_mfma_f32_16x16x32_bf16 v[20:23], v[152:155], v[192:195], v[20:23]
	v_mfma_f32_16x16x32_bf16 v[0:3], v[144:147], v[200:203], v[0:3]
	v_mfma_f32_16x16x32_bf16 v[4:7], v[152:155], v[200:203], v[4:7]
	v_mfma_f32_16x16x32_bf16 v[72:75], v[156:159], v[172:175], v[72:75]
	v_mfma_f32_16x16x32_bf16 v[76:79], v[164:167], v[172:175], v[76:79]
	v_mfma_f32_16x16x32_bf16 v[40:43], v[156:159], v[180:183], v[40:43]
	v_mfma_f32_16x16x32_bf16 v[44:47], v[164:167], v[180:183], v[44:47]
	v_mfma_f32_16x16x32_bf16 v[24:27], v[156:159], v[188:191], v[24:27]
	v_mfma_f32_16x16x32_bf16 v[28:31], v[164:167], v[188:191], v[28:31]
	v_mfma_f32_16x16x32_bf16 v[8:11], v[156:159], v[196:199], v[8:11]
	v_mfma_f32_16x16x32_bf16 v[12:15], v[164:167], v[196:199], v[12:15]
	v_mfma_f32_16x16x32_bf16 v[72:75], v[160:163], v[176:179], v[72:75]
	v_mfma_f32_16x16x32_bf16 v[76:79], v[168:171], v[176:179], v[76:79]
	v_mfma_f32_16x16x32_bf16 v[40:43], v[160:163], v[184:187], v[40:43]
	v_mfma_f32_16x16x32_bf16 v[44:47], v[168:171], v[184:187], v[44:47]
	v_mfma_f32_16x16x32_bf16 v[24:27], v[160:163], v[192:195], v[24:27]
	v_mfma_f32_16x16x32_bf16 v[28:31], v[168:171], v[192:195], v[28:31]
	v_mfma_f32_16x16x32_bf16 v[8:11], v[160:163], v[200:203], v[8:11]
	v_mfma_f32_16x16x32_bf16 v[12:15], v[168:171], v[200:203], v[12:15]
	s_barrier
	s_add_i32 s59, 0, 0x18000
	s_add_i32 s60, 0, 0x1c000
	v_add_u32_e32 v152, s59, v138
	v_add_u32_e32 v168, s60, v138
	ds_read_b128 v[140:143], v152
	ds_read_b128 v[144:147], v152 offset:1024
	ds_read_b128 v[148:151], v152 offset:2048
	ds_read_b128 v[152:155], v152 offset:3072
	ds_read_b128 v[156:159], v168
	ds_read_b128 v[160:163], v168 offset:1024
	ds_read_b128 v[164:167], v168 offset:2048
	ds_read_b128 v[168:171], v168 offset:3072
	s_add_u32 s28, s28, 0x10000
	s_addc_u32 s29, s29, 0
	s_mov_b32 m0, s44
	v_lshl_add_u64 v[212:213], s[28:29], 0, v[132:133]
	ds_read_b128 v[172:175], v139 offset:32768
	ds_read_b128 v[176:179], v139 offset:33792
	ds_read_b128 v[180:183], v139 offset:34816
	ds_read_b128 v[184:187], v139 offset:35840
	ds_read_b128 v[188:191], v139 offset:36864
	ds_read_b128 v[192:195], v139 offset:37888
	ds_read_b128 v[196:199], v139 offset:38912
	ds_read_b128 v[200:203], v139 offset:39936
	global_load_lds_dwordx4 v[212:213], off
	v_lshl_add_u64 v[212:213], s[28:29], 0, v[130:131]
	s_mov_b32 m0, s45
	s_nop 0
	global_load_lds_dwordx4 v[212:213], off
	s_waitcnt vmcnt(8)
	s_waitcnt lgkmcnt(0)
	s_barrier
	v_mfma_f32_16x16x32_bf16 v[112:115], v[140:143], v[172:175], v[112:115]
	v_mfma_f32_16x16x32_bf16 v[116:119], v[148:151], v[172:175], v[116:119]
	v_mfma_f32_16x16x32_bf16 v[96:99], v[140:143], v[180:183], v[96:99]
	v_mfma_f32_16x16x32_bf16 v[100:103], v[148:151], v[180:183], v[100:103]
	v_mfma_f32_16x16x32_bf16 v[80:83], v[140:143], v[188:191], v[80:83]
	v_mfma_f32_16x16x32_bf16 v[84:87], v[148:151], v[188:191], v[84:87]
	v_mfma_f32_16x16x32_bf16 v[48:51], v[140:143], v[196:199], v[48:51]
	v_mfma_f32_16x16x32_bf16 v[52:55], v[148:151], v[196:199], v[52:55]
	v_mfma_f32_16x16x32_bf16 v[112:115], v[144:147], v[176:179], v[112:115]
	v_mfma_f32_16x16x32_bf16 v[116:119], v[152:155], v[176:179], v[116:119]
	v_mfma_f32_16x16x32_bf16 v[96:99], v[144:147], v[184:187], v[96:99]
	v_mfma_f32_16x16x32_bf16 v[100:103], v[152:155], v[184:187], v[100:103]
	v_mfma_f32_16x16x32_bf16 v[80:83], v[144:147], v[192:195], v[80:83]
	v_mfma_f32_16x16x32_bf16 v[84:87], v[152:155], v[192:195], v[84:87]
	v_mfma_f32_16x16x32_bf16 v[48:51], v[144:147], v[200:203], v[48:51]
	v_mfma_f32_16x16x32_bf16 v[52:55], v[152:155], v[200:203], v[52:55]
	v_mfma_f32_16x16x32_bf16 v[120:123], v[156:159], v[172:175], v[120:123]
	v_mfma_f32_16x16x32_bf16 v[124:127], v[164:167], v[172:175], v[124:127]
	v_mfma_f32_16x16x32_bf16 v[104:107], v[156:159], v[180:183], v[104:107]
	v_mfma_f32_16x16x32_bf16 v[108:111], v[164:167], v[180:183], v[108:111]
	v_mfma_f32_16x16x32_bf16 v[88:91], v[156:159], v[188:191], v[88:91]
	v_mfma_f32_16x16x32_bf16 v[92:95], v[164:167], v[188:191], v[92:95]
	v_mfma_f32_16x16x32_bf16 v[64:67], v[156:159], v[196:199], v[64:67]
	v_mfma_f32_16x16x32_bf16 v[68:71], v[164:167], v[196:199], v[68:71]
	v_mfma_f32_16x16x32_bf16 v[120:123], v[160:163], v[176:179], v[120:123]
	v_mfma_f32_16x16x32_bf16 v[124:127], v[168:171], v[176:179], v[124:127]
	v_mfma_f32_16x16x32_bf16 v[104:107], v[160:163], v[184:187], v[104:107]
	v_mfma_f32_16x16x32_bf16 v[108:111], v[168:171], v[184:187], v[108:111]
	v_mfma_f32_16x16x32_bf16 v[88:91], v[160:163], v[192:195], v[88:91]
	v_mfma_f32_16x16x32_bf16 v[92:95], v[168:171], v[192:195], v[92:95]
	v_mfma_f32_16x16x32_bf16 v[64:67], v[160:163], v[200:203], v[64:67]
	v_mfma_f32_16x16x32_bf16 v[68:71], v[168:171], v[200:203], v[68:71]
	s_barrier
	s_add_i32 s28, s59, s10
	v_lshl_add_u64 v[204:205], v[204:205], 0, s[24:25]
	s_mov_b32 m0, s28
	ds_read_b128 v[172:175], v139 offset:49152
	ds_read_b128 v[176:179], v139 offset:50176
	ds_read_b128 v[180:183], v139 offset:51200
	ds_read_b128 v[184:187], v139 offset:52224
	ds_read_b128 v[188:191], v139 offset:53248
	ds_read_b128 v[192:195], v139 offset:54272
	ds_read_b128 v[196:199], v139 offset:55296
	ds_read_b128 v[200:203], v139 offset:56320
	global_load_lds_dwordx4 v[204:205], off
	s_add_i32 m0, s28, 0x2000
	s_add_u32 s8, s8, 0x10080
	v_lshl_add_u64 v[204:205], v[206:207], 0, s[24:25]
	s_addc_u32 s9, s9, 0
	s_add_i32 s28, s60, s10
	global_load_lds_dwordx4 v[204:205], off
	v_lshl_add_u64 v[204:205], s[8:9], 0, v[224:225]
	s_mov_b32 m0, s28
	s_nop 0
	global_load_lds_dwordx4 v[204:205], off
	v_lshl_add_u64 v[204:205], s[8:9], 0, v[128:129]
	s_add_i32 m0, s28, 0x2000
	s_nop 0
	global_load_lds_dwordx4 v[204:205], off
	v_lshl_add_u64 v[204:205], v[208:209], 0, s[24:25]
	s_mov_b32 m0, s48
	s_nop 0
	global_load_lds_dwordx4 v[204:205], off
	v_lshl_add_u64 v[204:205], v[210:211], 0, s[24:25]
	s_mov_b32 m0, s49
	s_nop 0
	global_load_lds_dwordx4 v[204:205], off
	s_waitcnt vmcnt(8)
	s_waitcnt lgkmcnt(0)
	s_barrier
	v_mfma_f32_16x16x32_bf16 v[56:59], v[140:143], v[172:175], v[56:59]
	v_mfma_f32_16x16x32_bf16 v[60:63], v[148:151], v[172:175], v[60:63]
	v_mfma_f32_16x16x32_bf16 v[32:35], v[140:143], v[180:183], v[32:35]
	v_mfma_f32_16x16x32_bf16 v[36:39], v[148:151], v[180:183], v[36:39]
	v_mfma_f32_16x16x32_bf16 v[16:19], v[140:143], v[188:191], v[16:19]
	v_mfma_f32_16x16x32_bf16 v[20:23], v[148:151], v[188:191], v[20:23]
	v_mfma_f32_16x16x32_bf16 v[0:3], v[140:143], v[196:199], v[0:3]
	v_mfma_f32_16x16x32_bf16 v[4:7], v[148:151], v[196:199], v[4:7]
	v_mfma_f32_16x16x32_bf16 v[56:59], v[144:147], v[176:179], v[56:59]
	v_mfma_f32_16x16x32_bf16 v[60:63], v[152:155], v[176:179], v[60:63]
	v_mfma_f32_16x16x32_bf16 v[32:35], v[144:147], v[184:187], v[32:35]
	v_mfma_f32_16x16x32_bf16 v[36:39], v[152:155], v[184:187], v[36:39]
	v_mfma_f32_16x16x32_bf16 v[16:19], v[144:147], v[192:195], v[16:19]
	v_mfma_f32_16x16x32_bf16 v[20:23], v[152:155], v[192:195], v[20:23]
	v_mfma_f32_16x16x32_bf16 v[0:3], v[144:147], v[200:203], v[0:3]
	v_mfma_f32_16x16x32_bf16 v[4:7], v[152:155], v[200:203], v[4:7]
	v_mfma_f32_16x16x32_bf16 v[72:75], v[156:159], v[172:175], v[72:75]
	v_mfma_f32_16x16x32_bf16 v[76:79], v[164:167], v[172:175], v[76:79]
	v_mfma_f32_16x16x32_bf16 v[40:43], v[156:159], v[180:183], v[40:43]
	v_mfma_f32_16x16x32_bf16 v[44:47], v[164:167], v[180:183], v[44:47]
	v_mfma_f32_16x16x32_bf16 v[24:27], v[156:159], v[188:191], v[24:27]
	v_mfma_f32_16x16x32_bf16 v[28:31], v[164:167], v[188:191], v[28:31]
	v_mfma_f32_16x16x32_bf16 v[8:11], v[156:159], v[196:199], v[8:11]
	v_mfma_f32_16x16x32_bf16 v[12:15], v[164:167], v[196:199], v[12:15]
	v_mfma_f32_16x16x32_bf16 v[72:75], v[160:163], v[176:179], v[72:75]
	v_mfma_f32_16x16x32_bf16 v[76:79], v[168:171], v[176:179], v[76:79]
	v_mfma_f32_16x16x32_bf16 v[40:43], v[160:163], v[184:187], v[40:43]
	v_mfma_f32_16x16x32_bf16 v[44:47], v[168:171], v[184:187], v[44:47]
	v_mfma_f32_16x16x32_bf16 v[24:27], v[160:163], v[192:195], v[24:27]
	v_mfma_f32_16x16x32_bf16 v[28:31], v[168:171], v[192:195], v[28:31]
	v_mfma_f32_16x16x32_bf16 v[8:11], v[160:163], v[200:203], v[8:11]
	v_mfma_f32_16x16x32_bf16 v[12:15], v[168:171], v[200:203], v[12:15]
	s_barrier
	s_add_u32 s12, s12, 0x100
	s_addc_u32 s13, s13, 0
	s_add_u32 s56, s56, 0x100
	s_addc_u32 s57, s57, 0
	s_cmp_ge_i32 s58, s47
	s_mov_b32 s8, s58
	s_cbranch_scc0 .LBB0_2092
	s_mov_b64 s[56:57], 0x400000
	s_mov_b64 s[58:59], 0x3fffff
	s_mov_b64 s[60:61], 0x20000

.LBB0_2239:
	s_add_i32 s30, s28, 2
	s_add_u32 s8, s12, 0x100
	s_addc_u32 s9, s13, 0
	s_add_i32 s31, 0, 0x10000
	s_cmp_eq_u32 s63, s28
	s_cselect_b32 s49, s43, s9
	s_cselect_b32 s48, s42, s8
	s_cselect_b32 s29, s47, s7
	s_cselect_b32 s28, s46, s3
	s_add_i32 s33, 0, 0x14000
	v_add_u32_e32 v100, s31, v230
	v_add_u32_e32 v124, s33, v230
	ds_read_b128 v[84:87], v100
	ds_read_b128 v[88:91], v100 offset:1024
	ds_read_b128 v[96:99], v100 offset:2048
	ds_read_b128 v[100:103], v100 offset:3072
	ds_read_b128 v[112:115], v124
	ds_read_b128 v[116:119], v124 offset:1024
	ds_read_b128 v[120:123], v124 offset:2048
	ds_read_b128 v[124:127], v124 offset:3072
	v_lshl_add_u64 v[202:203], s[12:13], 0, v[198:199]
	s_add_i32 m0, s56, 0xc000
	ds_read_b128 v[160:163], v231
	ds_read_b128 v[164:167], v231 offset:1024
	ds_read_b128 v[168:171], v231 offset:2048
	ds_read_b128 v[172:175], v231 offset:3072
	ds_read_b128 v[176:179], v231 offset:4096
	ds_read_b128 v[180:183], v231 offset:5120
	ds_read_b128 v[184:187], v231 offset:6144
	ds_read_b128 v[188:191], v231 offset:7168
	global_load_lds_dwordx4 v[202:203], off
	v_lshl_add_u64 v[202:203], s[12:13], 0, v[200:201]
	s_add_i32 m0, s56, 0xe000
	s_nop 0
	global_load_lds_dwordx4 v[202:203], off
	s_waitcnt vmcnt(8)
	s_waitcnt lgkmcnt(0)
	s_barrier
	v_mfma_f32_16x16x32_bf16 v[152:155], v[84:87], v[160:163], v[152:155]
	v_mfma_f32_16x16x32_bf16 v[156:159], v[96:99], v[160:163], v[156:159]
	v_mfma_f32_16x16x32_bf16 v[140:143], v[84:87], v[168:171], v[140:143]
	v_mfma_f32_16x16x32_bf16 v[136:139], v[96:99], v[168:171], v[136:139]
	v_mfma_f32_16x16x32_bf16 v[108:111], v[84:87], v[176:179], v[108:111]
	v_mfma_f32_16x16x32_bf16 v[104:107], v[96:99], v[176:179], v[104:107]
	v_mfma_f32_16x16x32_bf16 v[76:79], v[84:87], v[184:187], v[76:79]
	v_mfma_f32_16x16x32_bf16 v[72:75], v[96:99], v[184:187], v[72:75]
	v_mfma_f32_16x16x32_bf16 v[152:155], v[88:91], v[164:167], v[152:155]
	v_mfma_f32_16x16x32_bf16 v[156:159], v[100:103], v[164:167], v[156:159]
	v_mfma_f32_16x16x32_bf16 v[140:143], v[88:91], v[172:175], v[140:143]
	v_mfma_f32_16x16x32_bf16 v[136:139], v[100:103], v[172:175], v[136:139]
	v_mfma_f32_16x16x32_bf16 v[108:111], v[88:91], v[180:183], v[108:111]
	v_mfma_f32_16x16x32_bf16 v[104:107], v[100:103], v[180:183], v[104:107]
	v_mfma_f32_16x16x32_bf16 v[76:79], v[88:91], v[188:191], v[76:79]
	v_mfma_f32_16x16x32_bf16 v[72:75], v[100:103], v[188:191], v[72:75]
	v_mfma_f32_16x16x32_bf16 v[148:151], v[112:115], v[160:163], v[148:151]
	v_mfma_f32_16x16x32_bf16 v[144:147], v[120:123], v[160:163], v[144:147]
	v_mfma_f32_16x16x32_bf16 v[132:135], v[112:115], v[168:171], v[132:135]
	v_mfma_f32_16x16x32_bf16 v[128:131], v[120:123], v[168:171], v[128:131]
	v_mfma_f32_16x16x32_bf16 v[92:95], v[112:115], v[176:179], v[92:95]
	v_mfma_f32_16x16x32_bf16 v[80:83], v[120:123], v[176:179], v[80:83]
	v_mfma_f32_16x16x32_bf16 v[68:71], v[112:115], v[184:187], v[68:71]
	v_mfma_f32_16x16x32_bf16 v[64:67], v[120:123], v[184:187], v[64:67]
	v_mfma_f32_16x16x32_bf16 v[148:151], v[116:119], v[164:167], v[148:151]
	v_mfma_f32_16x16x32_bf16 v[144:147], v[124:127], v[164:167], v[144:147]
	v_mfma_f32_16x16x32_bf16 v[132:135], v[116:119], v[172:175], v[132:135]
	v_mfma_f32_16x16x32_bf16 v[128:131], v[124:127], v[172:175], v[128:131]
	v_mfma_f32_16x16x32_bf16 v[92:95], v[116:119], v[180:183], v[92:95]
	v_mfma_f32_16x16x32_bf16 v[80:83], v[124:127], v[180:183], v[80:83]
	v_mfma_f32_16x16x32_bf16 v[68:71], v[116:119], v[188:191], v[68:71]
	v_mfma_f32_16x16x32_bf16 v[64:67], v[124:127], v[188:191], v[64:67]
	s_barrier
	s_add_i32 s12, s31, s54
	v_lshl_add_u64 v[202:203], s[28:29], 0, v[224:225]
	s_mov_b32 m0, s12
	ds_read_b128 v[160:163], v231 offset:16384
	ds_read_b128 v[164:167], v231 offset:17408
	ds_read_b128 v[168:171], v231 offset:18432
	ds_read_b128 v[172:175], v231 offset:19456
	ds_read_b128 v[176:179], v231 offset:20480
	ds_read_b128 v[180:183], v231 offset:21504
	ds_read_b128 v[184:187], v231 offset:22528
	ds_read_b128 v[188:191], v231 offset:23552
	global_load_lds_dwordx4 v[202:203], off
	s_add_i32 m0, s12, 0x2000
	s_add_u32 s12, s28, 0x158000
	v_lshl_add_u64 v[204:205], s[28:29], 0, v[192:193]
	s_addc_u32 s13, s29, 0
	s_add_i32 s31, s33, s54
	global_load_lds_dwordx4 v[204:205], off
	v_lshl_add_u64 v[206:207], s[12:13], 0, v[224:225]
	s_mov_b32 m0, s31
	v_lshl_add_u64 v[208:209], s[48:49], 0, v[194:195]
	global_load_lds_dwordx4 v[206:207], off
	v_lshl_add_u64 v[206:207], s[12:13], 0, v[192:193]
	s_add_i32 m0, s31, 0x2000
	s_nop 0
	global_load_lds_dwordx4 v[206:207], off
	v_lshl_add_u64 v[206:207], s[48:49], 0, v[196:197]
	s_mov_b32 m0, s56
	s_nop 0
	global_load_lds_dwordx4 v[206:207], off
	s_mov_b32 m0, s57
	s_nop 0
	global_load_lds_dwordx4 v[208:209], off
	s_waitcnt vmcnt(8)
	s_waitcnt lgkmcnt(0)
	s_barrier
	v_mfma_f32_16x16x32_bf16 v[60:63], v[84:87], v[160:163], v[60:63]
	v_mfma_f32_16x16x32_bf16 v[56:59], v[96:99], v[160:163], v[56:59]
	v_mfma_f32_16x16x32_bf16 v[44:47], v[84:87], v[168:171], v[44:47]
	v_mfma_f32_16x16x32_bf16 v[40:43], v[96:99], v[168:171], v[40:43]
	v_mfma_f32_16x16x32_bf16 v[28:31], v[84:87], v[176:179], v[28:31]
	v_mfma_f32_16x16x32_bf16 v[24:27], v[96:99], v[176:179], v[24:27]
	v_mfma_f32_16x16x32_bf16 v[12:15], v[84:87], v[184:187], v[12:15]
	v_mfma_f32_16x16x32_bf16 v[8:11], v[96:99], v[184:187], v[8:11]
	v_mfma_f32_16x16x32_bf16 v[60:63], v[88:91], v[164:167], v[60:63]
	v_mfma_f32_16x16x32_bf16 v[56:59], v[100:103], v[164:167], v[56:59]
	v_mfma_f32_16x16x32_bf16 v[44:47], v[88:91], v[172:175], v[44:47]
	v_mfma_f32_16x16x32_bf16 v[40:43], v[100:103], v[172:175], v[40:43]
	v_mfma_f32_16x16x32_bf16 v[28:31], v[88:91], v[180:183], v[28:31]
	v_mfma_f32_16x16x32_bf16 v[24:27], v[100:103], v[180:183], v[24:27]
	v_mfma_f32_16x16x32_bf16 v[12:15], v[88:91], v[188:191], v[12:15]
	v_mfma_f32_16x16x32_bf16 v[8:11], v[100:103], v[188:191], v[8:11]
	v_mfma_f32_16x16x32_bf16 v[52:55], v[112:115], v[160:163], v[52:55]
	v_mfma_f32_16x16x32_bf16 v[48:51], v[120:123], v[160:163], v[48:51]
	v_mfma_f32_16x16x32_bf16 v[36:39], v[112:115], v[168:171], v[36:39]
	v_mfma_f32_16x16x32_bf16 v[32:35], v[120:123], v[168:171], v[32:35]
	v_mfma_f32_16x16x32_bf16 v[20:23], v[112:115], v[176:179], v[20:23]
	v_mfma_f32_16x16x32_bf16 v[16:19], v[120:123], v[176:179], v[16:19]
	v_mfma_f32_16x16x32_bf16 v[4:7], v[112:115], v[184:187], v[4:7]
	v_mfma_f32_16x16x32_bf16 v[0:3], v[120:123], v[184:187], v[0:3]
	v_mfma_f32_16x16x32_bf16 v[52:55], v[116:119], v[164:167], v[52:55]
	v_mfma_f32_16x16x32_bf16 v[48:51], v[124:127], v[164:167], v[48:51]
	v_mfma_f32_16x16x32_bf16 v[36:39], v[116:119], v[172:175], v[36:39]
	v_mfma_f32_16x16x32_bf16 v[32:35], v[124:127], v[172:175], v[32:35]
	v_mfma_f32_16x16x32_bf16 v[20:23], v[116:119], v[180:183], v[20:23]
	v_mfma_f32_16x16x32_bf16 v[16:19], v[124:127], v[180:183], v[16:19]
	v_mfma_f32_16x16x32_bf16 v[4:7], v[116:119], v[188:191], v[4:7]
	v_mfma_f32_16x16x32_bf16 v[0:3], v[124:127], v[188:191], v[0:3]
	s_barrier
	s_add_i32 s31, 0, 0x18000
	s_add_i32 s33, 0, 0x1c000
	v_add_u32_e32 v100, s31, v230
	v_add_u32_e32 v124, s33, v230
	ds_read_b128 v[84:87], v100
	ds_read_b128 v[88:91], v100 offset:1024
	ds_read_b128 v[96:99], v100 offset:2048
	ds_read_b128 v[100:103], v100 offset:3072
	ds_read_b128 v[112:115], v124
	ds_read_b128 v[116:119], v124 offset:1024
	ds_read_b128 v[120:123], v124 offset:2048
	ds_read_b128 v[124:127], v124 offset:3072
	s_add_u32 s12, s48, 0x158000
	s_addc_u32 s13, s49, 0
	s_mov_b32 m0, s58
	v_lshl_add_u64 v[210:211], s[12:13], 0, v[196:197]
	ds_read_b128 v[160:163], v231 offset:32768
	ds_read_b128 v[164:167], v231 offset:33792
	ds_read_b128 v[168:171], v231 offset:34816
	ds_read_b128 v[172:175], v231 offset:35840
	ds_read_b128 v[176:179], v231 offset:36864
	ds_read_b128 v[180:183], v231 offset:37888
	ds_read_b128 v[184:187], v231 offset:38912
	ds_read_b128 v[188:191], v231 offset:39936
	global_load_lds_dwordx4 v[210:211], off
	v_lshl_add_u64 v[210:211], s[12:13], 0, v[194:195]
	s_mov_b32 m0, s59
	s_nop 0
	global_load_lds_dwordx4 v[210:211], off
	s_waitcnt vmcnt(8)
	s_waitcnt lgkmcnt(0)
	s_barrier
	v_mfma_f32_16x16x32_bf16 v[152:155], v[84:87], v[160:163], v[152:155]
	v_mfma_f32_16x16x32_bf16 v[156:159], v[96:99], v[160:163], v[156:159]
	v_mfma_f32_16x16x32_bf16 v[140:143], v[84:87], v[168:171], v[140:143]
	v_mfma_f32_16x16x32_bf16 v[136:139], v[96:99], v[168:171], v[136:139]
	v_mfma_f32_16x16x32_bf16 v[108:111], v[84:87], v[176:179], v[108:111]
	v_mfma_f32_16x16x32_bf16 v[104:107], v[96:99], v[176:179], v[104:107]
	v_mfma_f32_16x16x32_bf16 v[76:79], v[84:87], v[184:187], v[76:79]
	v_mfma_f32_16x16x32_bf16 v[72:75], v[96:99], v[184:187], v[72:75]
	v_mfma_f32_16x16x32_bf16 v[152:155], v[88:91], v[164:167], v[152:155]
	v_mfma_f32_16x16x32_bf16 v[156:159], v[100:103], v[164:167], v[156:159]
	v_mfma_f32_16x16x32_bf16 v[140:143], v[88:91], v[172:175], v[140:143]
	v_mfma_f32_16x16x32_bf16 v[136:139], v[100:103], v[172:175], v[136:139]
	v_mfma_f32_16x16x32_bf16 v[108:111], v[88:91], v[180:183], v[108:111]
	v_mfma_f32_16x16x32_bf16 v[104:107], v[100:103], v[180:183], v[104:107]
	v_mfma_f32_16x16x32_bf16 v[76:79], v[88:91], v[188:191], v[76:79]
	v_mfma_f32_16x16x32_bf16 v[72:75], v[100:103], v[188:191], v[72:75]
	v_mfma_f32_16x16x32_bf16 v[148:151], v[112:115], v[160:163], v[148:151]
	v_mfma_f32_16x16x32_bf16 v[144:147], v[120:123], v[160:163], v[144:147]
	v_mfma_f32_16x16x32_bf16 v[132:135], v[112:115], v[168:171], v[132:135]
	v_mfma_f32_16x16x32_bf16 v[128:131], v[120:123], v[168:171], v[128:131]
	v_mfma_f32_16x16x32_bf16 v[92:95], v[112:115], v[176:179], v[92:95]
	v_mfma_f32_16x16x32_bf16 v[80:83], v[120:123], v[176:179], v[80:83]
	v_mfma_f32_16x16x32_bf16 v[68:71], v[112:115], v[184:187], v[68:71]
	v_mfma_f32_16x16x32_bf16 v[64:67], v[120:123], v[184:187], v[64:67]
	v_mfma_f32_16x16x32_bf16 v[148:151], v[116:119], v[164:167], v[148:151]
	v_mfma_f32_16x16x32_bf16 v[144:147], v[124:127], v[164:167], v[144:147]
	v_mfma_f32_16x16x32_bf16 v[132:135], v[116:119], v[172:175], v[132:135]
	v_mfma_f32_16x16x32_bf16 v[128:131], v[124:127], v[172:175], v[128:131]
	v_mfma_f32_16x16x32_bf16 v[92:95], v[116:119], v[180:183], v[92:95]
	v_mfma_f32_16x16x32_bf16 v[80:83], v[124:127], v[180:183], v[80:83]
	v_mfma_f32_16x16x32_bf16 v[68:71], v[116:119], v[188:191], v[68:71]
	v_mfma_f32_16x16x32_bf16 v[64:67], v[124:127], v[188:191], v[64:67]
	s_barrier
	s_add_i32 s12, s31, s54
	v_lshl_add_u64 v[202:203], v[202:203], 0, s[24:25]
	s_mov_b32 m0, s12
	ds_read_b128 v[160:163], v231 offset:49152
	ds_read_b128 v[164:167], v231 offset:50176
	ds_read_b128 v[168:171], v231 offset:51200
	ds_read_b128 v[172:175], v231 offset:52224
	ds_read_b128 v[176:179], v231 offset:53248
	ds_read_b128 v[180:183], v231 offset:54272
	ds_read_b128 v[184:187], v231 offset:55296
	ds_read_b128 v[188:191], v231 offset:56320
	global_load_lds_dwordx4 v[202:203], off
	s_add_i32 m0, s12, 0x2000
	s_add_u32 s12, s28, 0x158080
	v_lshl_add_u64 v[202:203], v[204:205], 0, s[24:25]
	s_addc_u32 s13, s29, 0
	s_add_i32 s28, s33, s54
	global_load_lds_dwordx4 v[202:203], off
	v_lshl_add_u64 v[202:203], s[12:13], 0, v[224:225]
	s_mov_b32 m0, s28
	s_nop 0
	global_load_lds_dwordx4 v[202:203], off
	v_lshl_add_u64 v[202:203], s[12:13], 0, v[192:193]
	s_add_i32 m0, s28, 0x2000
	s_nop 0
	global_load_lds_dwordx4 v[202:203], off
	v_lshl_add_u64 v[202:203], v[206:207], 0, s[24:25]
	s_mov_b32 m0, s61
	s_nop 0
	global_load_lds_dwordx4 v[202:203], off
	v_lshl_add_u64 v[202:203], v[208:209], 0, s[24:25]
	s_mov_b32 m0, s62
	s_nop 0
	global_load_lds_dwordx4 v[202:203], off
	s_waitcnt vmcnt(8)
	s_waitcnt lgkmcnt(0)
	s_barrier
	v_mfma_f32_16x16x32_bf16 v[60:63], v[84:87], v[160:163], v[60:63]
	v_mfma_f32_16x16x32_bf16 v[56:59], v[96:99], v[160:163], v[56:59]
	v_mfma_f32_16x16x32_bf16 v[44:47], v[84:87], v[168:171], v[44:47]
	v_mfma_f32_16x16x32_bf16 v[40:43], v[96:99], v[168:171], v[40:43]
	v_mfma_f32_16x16x32_bf16 v[28:31], v[84:87], v[176:179], v[28:31]
	v_mfma_f32_16x16x32_bf16 v[24:27], v[96:99], v[176:179], v[24:27]
	v_mfma_f32_16x16x32_bf16 v[12:15], v[84:87], v[184:187], v[12:15]
	v_mfma_f32_16x16x32_bf16 v[8:11], v[96:99], v[184:187], v[8:11]
	v_mfma_f32_16x16x32_bf16 v[60:63], v[88:91], v[164:167], v[60:63]
	v_mfma_f32_16x16x32_bf16 v[56:59], v[100:103], v[164:167], v[56:59]
	v_mfma_f32_16x16x32_bf16 v[44:47], v[88:91], v[172:175], v[44:47]
	v_mfma_f32_16x16x32_bf16 v[40:43], v[100:103], v[172:175], v[40:43]
	v_mfma_f32_16x16x32_bf16 v[28:31], v[88:91], v[180:183], v[28:31]
	v_mfma_f32_16x16x32_bf16 v[24:27], v[100:103], v[180:183], v[24:27]
	v_mfma_f32_16x16x32_bf16 v[12:15], v[88:91], v[188:191], v[12:15]
	v_mfma_f32_16x16x32_bf16 v[8:11], v[100:103], v[188:191], v[8:11]
	v_mfma_f32_16x16x32_bf16 v[52:55], v[112:115], v[160:163], v[52:55]
	v_mfma_f32_16x16x32_bf16 v[48:51], v[120:123], v[160:163], v[48:51]
	v_mfma_f32_16x16x32_bf16 v[36:39], v[112:115], v[168:171], v[36:39]
	v_mfma_f32_16x16x32_bf16 v[32:35], v[120:123], v[168:171], v[32:35]
	v_mfma_f32_16x16x32_bf16 v[20:23], v[112:115], v[176:179], v[20:23]
	v_mfma_f32_16x16x32_bf16 v[16:19], v[120:123], v[176:179], v[16:19]
	v_mfma_f32_16x16x32_bf16 v[4:7], v[112:115], v[184:187], v[4:7]
	v_mfma_f32_16x16x32_bf16 v[0:3], v[120:123], v[184:187], v[0:3]
	v_mfma_f32_16x16x32_bf16 v[52:55], v[116:119], v[164:167], v[52:55]
	v_mfma_f32_16x16x32_bf16 v[48:51], v[124:127], v[164:167], v[48:51]
	v_mfma_f32_16x16x32_bf16 v[36:39], v[116:119], v[172:175], v[36:39]
	v_mfma_f32_16x16x32_bf16 v[32:35], v[124:127], v[172:175], v[32:35]
	v_mfma_f32_16x16x32_bf16 v[20:23], v[116:119], v[180:183], v[20:23]
	v_mfma_f32_16x16x32_bf16 v[16:19], v[124:127], v[180:183], v[16:19]
	v_mfma_f32_16x16x32_bf16 v[4:7], v[116:119], v[188:191], v[4:7]
	v_mfma_f32_16x16x32_bf16 v[0:3], v[124:127], v[188:191], v[0:3]
	s_barrier
	s_add_u32 s3, s3, 0x100
	s_addc_u32 s7, s7, 0
	s_cmp_ge_i32 s30, s60
	s_mov_b64 s[12:13], s[8:9]
	s_mov_b32 s28, s30
	s_cbranch_scc0 .LBB0_2239
	v_readlane_b32 s48, v253, 35
	v_readlane_b32 s49, v253, 36
	s_and_b64 vcc, exec, s[44:45]
	s_cbranch_vccnz .LBB0_2244
	s_branch .LBB0_2245

.LBB0_2404:
	s_add_i32 s40, s8, 2
	s_add_u32 s9, s12, 0xfff80080
	s_addc_u32 s16, s13, -1
	s_add_i32 s41, 0, 0x10000
	s_cmp_eq_u32 s93, s8
	s_cselect_b32 s17, s7, s16
	s_cselect_b32 s16, s22, s9
	s_cselect_b32 s9, s23, s33
	s_cselect_b32 s8, s30, s31
	s_add_i32 s71, 0, 0x14000
	v_add_u32_e32 v52, s41, v202
	v_add_u32_e32 v156, s71, v202
	ds_read_b128 v[40:43], v52
	ds_read_b128 v[44:47], v52 offset:1024
	ds_read_b128 v[48:51], v52 offset:2048
	ds_read_b128 v[52:55], v52 offset:3072
	ds_read_b128 v[80:83], v156
	ds_read_b128 v[84:87], v156 offset:1024
	ds_read_b128 v[152:155], v156 offset:2048
	ds_read_b128 v[156:159], v156 offset:3072
	v_lshl_add_u64 v[204:205], s[12:13], 0, v[182:183]
	s_add_i32 m0, s84, 0xc000
	ds_read_b128 v[160:163], v203
	ds_read_b128 v[164:167], v203 offset:1024
	ds_read_b128 v[168:171], v203 offset:2048
	ds_read_b128 v[172:175], v203 offset:3072
	ds_read_b128 v[186:189], v203 offset:4096
	ds_read_b128 v[190:193], v203 offset:5120
	ds_read_b128 v[194:197], v203 offset:6144
	ds_read_b128 v[198:201], v203 offset:7168
	global_load_lds_dwordx4 v[204:205], off
	v_lshl_add_u64 v[204:205], s[12:13], 0, v[184:185]
	s_add_i32 m0, s84, 0xe000
	s_nop 0
	global_load_lds_dwordx4 v[204:205], off
	s_waitcnt vmcnt(8)
	s_waitcnt lgkmcnt(0)
	s_barrier
	v_mfma_f32_16x16x32_bf16 v[76:79], v[40:43], v[160:163], v[76:79]
	v_mfma_f32_16x16x32_bf16 v[72:75], v[48:51], v[160:163], v[72:75]
	v_mfma_f32_16x16x32_bf16 v[140:143], v[40:43], v[168:171], v[140:143]
	v_mfma_f32_16x16x32_bf16 v[136:139], v[48:51], v[168:171], v[136:139]
	v_mfma_f32_16x16x32_bf16 v[124:127], v[40:43], v[186:189], v[124:127]
	v_mfma_f32_16x16x32_bf16 v[120:123], v[48:51], v[186:189], v[120:123]
	v_mfma_f32_16x16x32_bf16 v[108:111], v[40:43], v[194:197], v[108:111]
	v_mfma_f32_16x16x32_bf16 v[104:107], v[48:51], v[194:197], v[104:107]
	v_mfma_f32_16x16x32_bf16 v[76:79], v[44:47], v[164:167], v[76:79]
	v_mfma_f32_16x16x32_bf16 v[72:75], v[52:55], v[164:167], v[72:75]
	v_mfma_f32_16x16x32_bf16 v[140:143], v[44:47], v[172:175], v[140:143]
	v_mfma_f32_16x16x32_bf16 v[136:139], v[52:55], v[172:175], v[136:139]
	v_mfma_f32_16x16x32_bf16 v[124:127], v[44:47], v[190:193], v[124:127]
	v_mfma_f32_16x16x32_bf16 v[120:123], v[52:55], v[190:193], v[120:123]
	v_mfma_f32_16x16x32_bf16 v[108:111], v[44:47], v[198:201], v[108:111]
	v_mfma_f32_16x16x32_bf16 v[104:107], v[52:55], v[198:201], v[104:107]
	v_mfma_f32_16x16x32_bf16 v[148:151], v[80:83], v[160:163], v[148:151]
	v_mfma_f32_16x16x32_bf16 v[144:147], v[152:155], v[160:163], v[144:147]
	v_mfma_f32_16x16x32_bf16 v[132:135], v[80:83], v[168:171], v[132:135]
	v_mfma_f32_16x16x32_bf16 v[128:131], v[152:155], v[168:171], v[128:131]
	v_mfma_f32_16x16x32_bf16 v[116:119], v[80:83], v[186:189], v[116:119]
	v_mfma_f32_16x16x32_bf16 v[112:115], v[152:155], v[186:189], v[112:115]
	v_mfma_f32_16x16x32_bf16 v[100:103], v[80:83], v[194:197], v[100:103]
	v_mfma_f32_16x16x32_bf16 v[96:99], v[152:155], v[194:197], v[96:99]
	v_mfma_f32_16x16x32_bf16 v[148:151], v[84:87], v[164:167], v[148:151]
	v_mfma_f32_16x16x32_bf16 v[144:147], v[156:159], v[164:167], v[144:147]
	v_mfma_f32_16x16x32_bf16 v[132:135], v[84:87], v[172:175], v[132:135]
	v_mfma_f32_16x16x32_bf16 v[128:131], v[156:159], v[172:175], v[128:131]
	v_mfma_f32_16x16x32_bf16 v[116:119], v[84:87], v[190:193], v[116:119]
	v_mfma_f32_16x16x32_bf16 v[112:115], v[156:159], v[190:193], v[112:115]
	v_mfma_f32_16x16x32_bf16 v[100:103], v[84:87], v[198:201], v[100:103]
	v_mfma_f32_16x16x32_bf16 v[96:99], v[156:159], v[198:201], v[96:99]
	s_barrier
	s_add_i32 s41, s41, s28
	v_lshl_add_u64 v[204:205], s[8:9], 0, v[224:225]
	s_mov_b32 m0, s41
	ds_read_b128 v[160:163], v203 offset:16384
	ds_read_b128 v[164:167], v203 offset:17408
	ds_read_b128 v[168:171], v203 offset:18432
	ds_read_b128 v[172:175], v203 offset:19456
	ds_read_b128 v[186:189], v203 offset:20480
	ds_read_b128 v[190:193], v203 offset:21504
	ds_read_b128 v[194:197], v203 offset:22528
	ds_read_b128 v[198:201], v203 offset:23552
	global_load_lds_dwordx4 v[204:205], off
	s_add_i32 m0, s41, 0x2000
	s_add_u32 s42, s8, 0x80000
	v_lshl_add_u64 v[206:207], s[8:9], 0, v[176:177]
	s_addc_u32 s43, s9, 0
	s_add_i32 s41, s71, s28
	global_load_lds_dwordx4 v[206:207], off
	v_lshl_add_u64 v[208:209], s[42:43], 0, v[224:225]
	s_mov_b32 m0, s41
	v_lshl_add_u64 v[210:211], s[16:17], 0, v[178:179]
	global_load_lds_dwordx4 v[208:209], off
	v_lshl_add_u64 v[208:209], s[42:43], 0, v[176:177]
	s_add_i32 m0, s41, 0x2000
	s_nop 0
	global_load_lds_dwordx4 v[208:209], off
	v_lshl_add_u64 v[208:209], s[16:17], 0, v[180:181]
	s_mov_b32 m0, s84
	s_nop 0
	global_load_lds_dwordx4 v[208:209], off
	s_mov_b32 m0, s85
	s_nop 0
	global_load_lds_dwordx4 v[210:211], off
	s_waitcnt vmcnt(8)
	s_waitcnt lgkmcnt(0)
	s_barrier
	v_mfma_f32_16x16x32_bf16 v[92:95], v[40:43], v[160:163], v[92:95]
	v_mfma_f32_16x16x32_bf16 v[88:91], v[48:51], v[160:163], v[88:91]
	v_mfma_f32_16x16x32_bf16 v[60:63], v[40:43], v[168:171], v[60:63]
	v_mfma_f32_16x16x32_bf16 v[56:59], v[48:51], v[168:171], v[56:59]
	v_mfma_f32_16x16x32_bf16 v[28:31], v[40:43], v[186:189], v[28:31]
	v_mfma_f32_16x16x32_bf16 v[24:27], v[48:51], v[186:189], v[24:27]
	v_mfma_f32_16x16x32_bf16 v[12:15], v[40:43], v[194:197], v[12:15]
	v_mfma_f32_16x16x32_bf16 v[8:11], v[48:51], v[194:197], v[8:11]
	v_mfma_f32_16x16x32_bf16 v[92:95], v[44:47], v[164:167], v[92:95]
	v_mfma_f32_16x16x32_bf16 v[88:91], v[52:55], v[164:167], v[88:91]
	v_mfma_f32_16x16x32_bf16 v[60:63], v[44:47], v[172:175], v[60:63]
	v_mfma_f32_16x16x32_bf16 v[56:59], v[52:55], v[172:175], v[56:59]
	v_mfma_f32_16x16x32_bf16 v[28:31], v[44:47], v[190:193], v[28:31]
	v_mfma_f32_16x16x32_bf16 v[24:27], v[52:55], v[190:193], v[24:27]
	v_mfma_f32_16x16x32_bf16 v[12:15], v[44:47], v[198:201], v[12:15]
	v_mfma_f32_16x16x32_bf16 v[8:11], v[52:55], v[198:201], v[8:11]
	v_mfma_f32_16x16x32_bf16 v[36:39], v[80:83], v[168:171], v[36:39]
	v_mfma_f32_16x16x32_bf16 v[32:35], v[152:155], v[168:171], v[32:35]
	v_mfma_f32_16x16x32_bf16 v[20:23], v[80:83], v[186:189], v[20:23]
	v_mfma_f32_16x16x32_bf16 v[16:19], v[152:155], v[186:189], v[16:19]
	v_mfma_f32_16x16x32_bf16 v[4:7], v[80:83], v[194:197], v[4:7]
	v_mfma_f32_16x16x32_bf16 v[0:3], v[152:155], v[194:197], v[0:3]
	v_mfma_f32_16x16x32_bf16 v[40:43], v[80:83], v[160:163], v[68:71]
	v_mfma_f32_16x16x32_bf16 v[44:47], v[152:155], v[160:163], v[64:67]
	v_mfma_f32_16x16x32_bf16 v[36:39], v[84:87], v[172:175], v[36:39]
	v_mfma_f32_16x16x32_bf16 v[32:35], v[156:159], v[172:175], v[32:35]
	v_mfma_f32_16x16x32_bf16 v[20:23], v[84:87], v[190:193], v[20:23]
	v_mfma_f32_16x16x32_bf16 v[16:19], v[156:159], v[190:193], v[16:19]
	v_mfma_f32_16x16x32_bf16 v[4:7], v[84:87], v[198:201], v[4:7]
	v_mfma_f32_16x16x32_bf16 v[0:3], v[156:159], v[198:201], v[0:3]
	v_mfma_f32_16x16x32_bf16 v[40:43], v[84:87], v[164:167], v[40:43]
	v_mfma_f32_16x16x32_bf16 v[44:47], v[156:159], v[164:167], v[44:47]
	s_barrier
	s_add_i32 s41, 0, 0x18000
	s_add_i32 s42, 0, 0x1c000
	v_add_u32_e32 v68, s41, v202
	v_add_u32_e32 v156, s42, v202
	ds_read_b128 v[48:51], v68
	ds_read_b128 v[52:55], v68 offset:1024
	ds_read_b128 v[64:67], v68 offset:2048
	ds_read_b128 v[68:71], v68 offset:3072
	ds_read_b128 v[80:83], v156
	ds_read_b128 v[84:87], v156 offset:1024
	ds_read_b128 v[152:155], v156 offset:2048
	ds_read_b128 v[156:159], v156 offset:3072
	s_add_u32 s16, s16, 0x80000
	s_addc_u32 s17, s17, 0
	s_mov_b32 m0, s86
	v_lshl_add_u64 v[212:213], s[16:17], 0, v[180:181]
	ds_read_b128 v[160:163], v203 offset:32768
	ds_read_b128 v[164:167], v203 offset:33792
	ds_read_b128 v[168:171], v203 offset:34816
	ds_read_b128 v[172:175], v203 offset:35840
	ds_read_b128 v[186:189], v203 offset:36864
	ds_read_b128 v[190:193], v203 offset:37888
	ds_read_b128 v[194:197], v203 offset:38912
	ds_read_b128 v[198:201], v203 offset:39936
	global_load_lds_dwordx4 v[212:213], off
	v_lshl_add_u64 v[212:213], s[16:17], 0, v[178:179]
	s_mov_b32 m0, s87
	s_nop 0
	global_load_lds_dwordx4 v[212:213], off
	s_waitcnt vmcnt(8)
	s_waitcnt lgkmcnt(0)
	s_barrier
	v_mfma_f32_16x16x32_bf16 v[76:79], v[48:51], v[160:163], v[76:79]
	v_mfma_f32_16x16x32_bf16 v[72:75], v[64:67], v[160:163], v[72:75]
	v_mfma_f32_16x16x32_bf16 v[140:143], v[48:51], v[168:171], v[140:143]
	v_mfma_f32_16x16x32_bf16 v[136:139], v[64:67], v[168:171], v[136:139]
	v_mfma_f32_16x16x32_bf16 v[124:127], v[48:51], v[186:189], v[124:127]
	v_mfma_f32_16x16x32_bf16 v[120:123], v[64:67], v[186:189], v[120:123]
	v_mfma_f32_16x16x32_bf16 v[108:111], v[48:51], v[194:197], v[108:111]
	v_mfma_f32_16x16x32_bf16 v[104:107], v[64:67], v[194:197], v[104:107]
	v_mfma_f32_16x16x32_bf16 v[76:79], v[52:55], v[164:167], v[76:79]
	v_mfma_f32_16x16x32_bf16 v[72:75], v[68:71], v[164:167], v[72:75]
	v_mfma_f32_16x16x32_bf16 v[140:143], v[52:55], v[172:175], v[140:143]
	v_mfma_f32_16x16x32_bf16 v[136:139], v[68:71], v[172:175], v[136:139]
	v_mfma_f32_16x16x32_bf16 v[124:127], v[52:55], v[190:193], v[124:127]
	v_mfma_f32_16x16x32_bf16 v[120:123], v[68:71], v[190:193], v[120:123]
	v_mfma_f32_16x16x32_bf16 v[108:111], v[52:55], v[198:201], v[108:111]
	v_mfma_f32_16x16x32_bf16 v[104:107], v[68:71], v[198:201], v[104:107]
	v_mfma_f32_16x16x32_bf16 v[148:151], v[80:83], v[160:163], v[148:151]
	v_mfma_f32_16x16x32_bf16 v[144:147], v[152:155], v[160:163], v[144:147]
	v_mfma_f32_16x16x32_bf16 v[132:135], v[80:83], v[168:171], v[132:135]
	v_mfma_f32_16x16x32_bf16 v[128:131], v[152:155], v[168:171], v[128:131]
	v_mfma_f32_16x16x32_bf16 v[116:119], v[80:83], v[186:189], v[116:119]
	v_mfma_f32_16x16x32_bf16 v[112:115], v[152:155], v[186:189], v[112:115]
	v_mfma_f32_16x16x32_bf16 v[100:103], v[80:83], v[194:197], v[100:103]
	v_mfma_f32_16x16x32_bf16 v[96:99], v[152:155], v[194:197], v[96:99]
	v_mfma_f32_16x16x32_bf16 v[148:151], v[84:87], v[164:167], v[148:151]
	v_mfma_f32_16x16x32_bf16 v[144:147], v[156:159], v[164:167], v[144:147]
	v_mfma_f32_16x16x32_bf16 v[132:135], v[84:87], v[172:175], v[132:135]
	v_mfma_f32_16x16x32_bf16 v[128:131], v[156:159], v[172:175], v[128:131]
	v_mfma_f32_16x16x32_bf16 v[116:119], v[84:87], v[190:193], v[116:119]
	v_mfma_f32_16x16x32_bf16 v[112:115], v[156:159], v[190:193], v[112:115]
	v_mfma_f32_16x16x32_bf16 v[100:103], v[84:87], v[198:201], v[100:103]
	v_mfma_f32_16x16x32_bf16 v[96:99], v[156:159], v[198:201], v[96:99]
	s_barrier
	s_add_i32 s16, s41, s28
	v_lshl_add_u64 v[204:205], v[204:205], 0, s[24:25]
	s_mov_b32 m0, s16
	ds_read_b128 v[160:163], v203 offset:49152
	ds_read_b128 v[164:167], v203 offset:50176
	ds_read_b128 v[168:171], v203 offset:51200
	ds_read_b128 v[172:175], v203 offset:52224
	ds_read_b128 v[186:189], v203 offset:53248
	ds_read_b128 v[190:193], v203 offset:54272
	ds_read_b128 v[194:197], v203 offset:55296
	ds_read_b128 v[198:201], v203 offset:56320
	global_load_lds_dwordx4 v[204:205], off
	s_add_i32 m0, s16, 0x2000
	s_add_u32 s8, s8, 0x80080
	v_lshl_add_u64 v[204:205], v[206:207], 0, s[24:25]
	s_addc_u32 s9, s9, 0
	s_add_i32 s16, s42, s28
	global_load_lds_dwordx4 v[204:205], off
	v_lshl_add_u64 v[204:205], s[8:9], 0, v[224:225]
	s_mov_b32 m0, s16
	s_nop 0
	global_load_lds_dwordx4 v[204:205], off
	v_lshl_add_u64 v[204:205], s[8:9], 0, v[176:177]
	s_add_i32 m0, s16, 0x2000
	s_nop 0
	global_load_lds_dwordx4 v[204:205], off
	v_lshl_add_u64 v[204:205], v[208:209], 0, s[24:25]
	s_mov_b32 m0, s18
	s_nop 0
	global_load_lds_dwordx4 v[204:205], off
	v_lshl_add_u64 v[204:205], v[210:211], 0, s[24:25]
	s_mov_b32 m0, s19
	s_nop 0
	global_load_lds_dwordx4 v[204:205], off
	s_waitcnt vmcnt(8)
	s_waitcnt lgkmcnt(0)
	s_barrier
	v_mfma_f32_16x16x32_bf16 v[92:95], v[48:51], v[160:163], v[92:95]
	v_mfma_f32_16x16x32_bf16 v[88:91], v[64:67], v[160:163], v[88:91]
	v_mfma_f32_16x16x32_bf16 v[60:63], v[48:51], v[168:171], v[60:63]
	v_mfma_f32_16x16x32_bf16 v[56:59], v[64:67], v[168:171], v[56:59]
	v_mfma_f32_16x16x32_bf16 v[28:31], v[48:51], v[186:189], v[28:31]
	v_mfma_f32_16x16x32_bf16 v[24:27], v[64:67], v[186:189], v[24:27]
	v_mfma_f32_16x16x32_bf16 v[12:15], v[48:51], v[194:197], v[12:15]
	v_mfma_f32_16x16x32_bf16 v[8:11], v[64:67], v[194:197], v[8:11]
	v_mfma_f32_16x16x32_bf16 v[92:95], v[52:55], v[164:167], v[92:95]
	v_mfma_f32_16x16x32_bf16 v[88:91], v[68:71], v[164:167], v[88:91]
	v_mfma_f32_16x16x32_bf16 v[60:63], v[52:55], v[172:175], v[60:63]
	v_mfma_f32_16x16x32_bf16 v[56:59], v[68:71], v[172:175], v[56:59]
	v_mfma_f32_16x16x32_bf16 v[28:31], v[52:55], v[190:193], v[28:31]
	v_mfma_f32_16x16x32_bf16 v[24:27], v[68:71], v[190:193], v[24:27]
	v_mfma_f32_16x16x32_bf16 v[12:15], v[52:55], v[198:201], v[12:15]
	v_mfma_f32_16x16x32_bf16 v[8:11], v[68:71], v[198:201], v[8:11]
	v_mfma_f32_16x16x32_bf16 v[40:43], v[80:83], v[160:163], v[40:43]
	v_mfma_f32_16x16x32_bf16 v[68:71], v[84:87], v[164:167], v[40:43]
	v_mfma_f32_16x16x32_bf16 v[40:43], v[152:155], v[160:163], v[44:47]
	v_mfma_f32_16x16x32_bf16 v[36:39], v[80:83], v[168:171], v[36:39]
	v_mfma_f32_16x16x32_bf16 v[32:35], v[152:155], v[168:171], v[32:35]
	v_mfma_f32_16x16x32_bf16 v[20:23], v[80:83], v[186:189], v[20:23]
	v_mfma_f32_16x16x32_bf16 v[16:19], v[152:155], v[186:189], v[16:19]
	v_mfma_f32_16x16x32_bf16 v[4:7], v[80:83], v[194:197], v[4:7]
	v_mfma_f32_16x16x32_bf16 v[0:3], v[152:155], v[194:197], v[0:3]
	v_mfma_f32_16x16x32_bf16 v[64:67], v[156:159], v[164:167], v[40:43]
	v_mfma_f32_16x16x32_bf16 v[36:39], v[84:87], v[172:175], v[36:39]
	v_mfma_f32_16x16x32_bf16 v[32:35], v[156:159], v[172:175], v[32:35]
	v_mfma_f32_16x16x32_bf16 v[20:23], v[84:87], v[190:193], v[20:23]
	v_mfma_f32_16x16x32_bf16 v[16:19], v[156:159], v[190:193], v[16:19]
	v_mfma_f32_16x16x32_bf16 v[4:7], v[84:87], v[198:201], v[4:7]
	v_mfma_f32_16x16x32_bf16 v[0:3], v[156:159], v[198:201], v[0:3]
	s_barrier
	s_add_u32 s12, s12, 0x100
	s_addc_u32 s13, s13, 0
	s_add_u32 s31, s31, 0x100
	s_addc_u32 s33, s33, 0
	s_cmp_ge_i32 s40, s27
	s_mov_b32 s8, s40
	s_cbranch_scc0 .LBB0_2404
